# GEMM phases: per-MFMA-block s_setprio flips deleted, one static s_setprio 1 for the trailing wave half (waves 4-7), reset to 0 at phase end
# baseline (speedup 1.0000x reference)
;     __device__ __forceinline__ long arow(int pm) const { return (long)pm * BM; }
;     __device__ __forceinline__ long arow(int pm) const { if (pm < 132) { const int b = pm / 33, i = pm - b * 33; return (long)b * 8192 + 254 * i - 1; } return 32768 + (long)(pm - 132) * 256; }
;     __device__ __forceinline__ bool next(int i, Unit& u) const { if (i > 0) return false; u.pm = pm; u.pn = pn; return true; }
;     __device__ __forceinline__ long arow(int p) const { return (long)p * BM; }
; template <class Epi, class Sched, bool ALIGN_EPI = false, bool SP2 = false>
; __device__ __forceinline__ void gemm_phase(PG8_LAS unsigned char* lds, const Gemm g, const Sched& S, const Epi& E) {
;     int tid_ = threadIdx.x; asm volatile("" : "+v"(tid_));
;     const int tid = tid_, wid = __builtin_amdgcn_readfirstlane(tid >> 6), lane = tid & 63, wr = wid >> 2, wc = wid & 3, fr = lane & 15, fq = lane >> 4;
;     const int K = g.K, nt = K / BK, LD = g.ld ? g.ld : g.K;
;     unsigned voffA[2], voffB[2];
; #pragma unroll
;     for (int i = 0; i < 2; ++i) { int R, C; stage_rc(tid * 16 + i * 8192, R, C); const int Rb = Epi::PERM ? ((R & ~31) + perm32(R & 31)) : R;
;         voffA[i] = (unsigned)(R * LD + C) * 2u; voffB[i] = (unsigned)(Rb * LD + C) * 2u; }
;     const size_t kstep = (size_t)(BK * 2);
;     const size_t hstep = (size_t)HALF * LD * 2;
;     const size_t tstep = 2 * hstep;
;     const unsigned ldsw = (unsigned)wid * 1024u;
;     const int aoff = lds_byte(wr * 64 + fr, fq * 8), boff = lds_byte(wc * 32 + fr, fq * 8);
;     ...
;     Unit cur, nxt; int ui = 0;
;     if (!S.next(0, cur)) return;
;     f32x4 acc[2][2][4][2];
; #pragma unroll
;     for (int a = 0; a < 2; ++a)
; #pragma unroll
;         for (int b = 0; b < 2; ++b)
; #pragma unroll
;             for (int m = 0; m < 4; ++m)
; #pragma unroll
;                 for (int n = 0; n < 2; ++n) acc[a][b][m][n] = (f32x4){0.f, 0.f, 0.f, 0.f};
;     bf16x8 At[4][2], B0[2][2], B1[2][2];
;     const long rowb = (long)LD * 2;
;     const char* cA = (const char*)g.A + S.arow(cur.pm) * rowb; const char* cB = (const char*)g.Bt + (size_t)cur.pn * tstep;
;     S.a_ready(cur);
;     if constexpr (SP2) {
;         PG8_STAGE(PG8_SB(0, 0), cB, voffB); PG8_STAGE(PG8_SB(0, 1), cB + hstep, voffB); PG8_STAGE(PG8_SA(0, 0), cA, voffA); PG8_STAGE(PG8_SA(0, 1), cA + hstep, voffA);
;         if (wr == 1) PG8_BAR;
.LBB0_172:
	s_or_b64 exec, exec, s[0:1]
	v_readlane_b32 s0, v254, 27
	v_readlane_b32 s1, v254, 28
	s_mov_b32 s1, s79
	v_readlane_b32 s2, v253, 8
	v_writelane_b32 v254, s0, 27
	s_waitcnt lgkmcnt(0)
	v_mov_b32_e32 v2, v225
	v_readlane_b32 s3, v253, 9
	v_writelane_b32 v254, s1, 28
	s_barrier
	s_and_b64 vcc, exec, s[2:3]
	v_readfirstlane_b32 s0, v2
	s_cbranch_vccz .LBB0_192
	v_lshlrev_b32_e32 v6, 4, v2
	v_add_u32_e32 v4, 0x2000, v6
	v_ashrrev_i32_e32 v3, 31, v4
	v_lshrrev_b32_e32 v3, 22, v3
	v_add_u32_e32 v3, v4, v3
	v_ashrrev_i32_e32 v3, 10, v3
	v_mul_i32_i24_e32 v5, 0x400, v3
	v_sub_u32_e32 v4, v4, v5
	v_lshrrev_b32_e32 v5, 4, v4
	v_bitop3_b32 v5, v5, v4, 32 bitop3:0x6c
	v_ashrrev_i32_e32 v4, 31, v5
	v_lshrrev_b32_e32 v4, 26, v4
	v_add_u32_e32 v7, v5, v4
	v_lshlrev_b32_e32 v8, 3, v3
	v_readlane_b32 s2, v254, 27
	v_ashrrev_i32_e32 v4, 6, v7
	v_and_b32_e32 v8, -16, v8
	s_mul_i32 s1, s2, 0x480000
	v_readlane_b32 s2, v253, 6
	v_add_u32_e32 v8, v4, v8
	s_add_u32 s22, s2, s1
	v_and_b32_e32 v9, 3, v4
	s_mov_b32 s2, 0x1fffe0
	v_lshrrev_b32_e32 v10, 2, v8
	v_lshlrev_b32_e32 v11, 1, v8
	v_and_b32_e32 v7, 0xc0, v7
	v_and_or_b32 v9, v8, s2, v9
	v_and_b32_e32 v10, 4, v10
	v_and_b32_e32 v11, 24, v11
	v_sub_u32_e32 v5, v5, v7
	v_mov_b32_e32 v14, 1
	v_or3_b32 v9, v9, v10, v11
	v_lshlrev_b32_e32 v10, 5, v3
	v_ashrrev_i16_sdwa v5, v14, sext(v5) dst_sel:DWORD dst_unused:UNUSED_PAD src0_sel:DWORD src1_sel:BYTE_0
	v_and_b32_e32 v10, 32, v10
	v_bfe_i32 v5, v5, 0, 16
	v_add_lshl_u32 v7, v10, v5, 1
	v_lshl_add_u32 v36, v9, 11, v7
	v_lshl_add_u32 v138, v8, 11, v7
	v_bfe_i32 v7, v2, 27, 1
	v_lshrrev_b32_e32 v7, 22, v7
	v_add_u32_e32 v7, v6, v7
	v_and_b32_e32 v7, 0xfffffc00, v7
	v_sub_u32_e32 v6, v6, v7
	v_lshrrev_b32_e32 v7, 4, v6
	v_bitop3_b32 v8, v7, v6, 32 bitop3:0x6c
	v_ashrrev_i32_e32 v7, 31, v2
	v_lshrrev_b32_e32 v7, 26, v7
	v_ashrrev_i32_e32 v6, 31, v8
	v_add_u32_e32 v7, v2, v7
	v_lshrrev_b32_e32 v6, 26, v6
	v_ashrrev_i32_e32 v7, 6, v7
	v_add_u32_e32 v9, v8, v6
	v_lshlrev_b32_e32 v10, 3, v7
	v_ashrrev_i32_e32 v6, 6, v9
	v_and_b32_e32 v10, -16, v10
	v_add_u32_e32 v10, v6, v10
	v_readlane_b32 s1, v253, 7
	v_and_b32_e32 v11, 3, v6
	v_lshrrev_b32_e32 v12, 2, v10
	v_lshlrev_b32_e32 v13, 1, v10
	v_and_b32_e32 v9, 0xc0, v9
	v_readlane_b32 s3, v254, 28
	s_addc_u32 s23, s1, 0
	s_ashr_i32 s4, s0, 6
	v_and_or_b32 v11, v10, s2, v11
	v_and_b32_e32 v12, 4, v12
	v_and_b32_e32 v13, 24, v13
	v_sub_u32_e32 v8, v8, v9
	s_ashr_i32 s1, s0, 8
	s_lshl_b32 s24, s4, 10
	v_or3_b32 v11, v11, v12, v13
	v_lshlrev_b32_e32 v12, 5, v7
	v_ashrrev_i16_sdwa v8, v14, sext(v8) dst_sel:DWORD dst_unused:UNUSED_PAD src0_sel:DWORD src1_sel:BYTE_0
	v_readlane_b32 s2, v254, 10
	v_and_b32_e32 v12, 32, v12
	v_bfe_i32 v8, v8, 0, 16
	v_readlane_b32 s3, v254, 11
	s_add_u32 s18, s22, s2
	v_add_lshl_u32 v9, v12, v8, 1
	s_addc_u32 s19, s23, s3
	s_add_i32 s25, s24, 0
	v_lshl_add_u32 v34, v11, 11, v9
	s_add_i32 m0, s25, 0x10000
	v_lshl_add_u32 v140, v10, 11, v9
	global_load_lds_dwordx4 v34, s[18:19]
	s_add_i32 m0, s25, 0x12000
	s_add_u32 s2, s18, 0x40000
	global_load_lds_dwordx4 v36, s[18:19]
	s_addc_u32 s3, s19, 0
	s_add_i32 m0, s25, 0x14000
	s_add_i32 s26, s25, 0x2000
	global_load_lds_dwordx4 v34, s[2:3]
	s_add_i32 m0, s25, 0x16000
	s_add_i32 s27, s25, 0x4000
	global_load_lds_dwordx4 v36, s[2:3]
	v_readlane_b32 s2, v254, 16
	s_mov_b32 m0, s25
	v_readlane_b32 s3, v254, 17
	s_add_i32 s28, s25, 0x6000
	s_cmp_eq_u32 s1, 1
	v_mov_b32_e32 v214, 1
	s_nop 1
	global_load_lds_dwordx4 v140, s[2:3]
	s_mov_b32 m0, s26
	s_nop 0
	global_load_lds_dwordx4 v138, s[2:3]
	v_readlane_b32 s2, v254, 18
	s_mov_b32 m0, s27
	v_readlane_b32 s3, v254, 19
	s_nop 4
	global_load_lds_dwordx4 v140, s[2:3]
	s_mov_b32 m0, s28
	s_nop 0
	global_load_lds_dwordx4 v138, s[2:3]
	s_cselect_b64 s[2:3], -1, 0
	s_cmp_lg_u32 s1, 1
	s_cbranch_scc1 .LBB0_175
	s_barrier
	s_setprio 1

; #define PG8_STAGE(bufoff, gbase, voff) do { _Pragma("unroll") for (int _i = 0; _i < 2; ++_i) \
;         __builtin_amdgcn_global_load_lds((const unsigned*)((const char*)(gbase) + (voff)[_i]), (PG8_LAS unsigned*)(lds + (bufoff) + ldsw + _i * 8192), 16, 0, 0); } while (0)
; #define PG8_LDA(dst, b, h) do { _Pragma("unroll") for (int m = 0; m < 4; ++m) _Pragma("unroll") for (int k = 0; k < 2; ++k) dst[m][k] = *(const PG8_LAS bf16x8*)(lds + PG8_SA(b, h) + aoff + m * 2048 + k * 1024); } while (0)
; #define PG8_LDB(dst, b, h) do { _Pragma("unroll") for (int n = 0; n < 2; ++n) _Pragma("unroll") for (int k = 0; k < 2; ++k) dst[n][k] = *(const PG8_LAS bf16x8*)(lds + PG8_SB(b, h) + boff + n * 2048 + k * 1024); } while (0)
; #define PG8_MMA(ai, bj, At, Bt) do { __builtin_amdgcn_s_setprio(1); _Pragma("unroll") for (int m = 0; m < 4; ++m) _Pragma("unroll") for (int n = 0; n < 2; ++n) _Pragma("unroll") for (int k = 0; k < 2; ++k) \
;         acc[ai][bj][m][n] = __builtin_amdgcn_mfma_f32_16x16x32_bf16(Bt[n][k], At[m][k], acc[ai][bj][m][n], 0, 0, 0); __builtin_amdgcn_s_setprio(0); } while (0)
; #define PG8_WAIT_V(n) asm volatile("s_waitcnt vmcnt(" #n ")" ::: "memory")
; #define PG8_WAIT_L(n) asm volatile("s_waitcnt lgkmcnt(" #n ")" ::: "memory")
; template <class Epi, class Sched, bool ALIGN_EPI = false, bool SP2 = false>
; __device__ __forceinline__ void gemm_phase(PG8_LAS unsigned char* lds, const Gemm g, const Sched& S, const Epi& E) {
;     ...
;             const bool last = (t == nt - 2);
;             const char* a1 = cA + (size_t)(t + 1) * kstep;
;             const char* a2 = last ? nA : cA + (size_t)(t + 2) * kstep; const char* b2 = last ? nB : cB + (size_t)(t + 2) * kstep;
;             const char* a3 = a2 + kstep; const char* b3 = b2 + kstep;
;             if (last && has_next) S.a_ready(nxt);
;             if constexpr (SP2) {
;             PG8_LDB(B0, 0, 0); PG8_LDB(B1, 0, 1); PG8_SCHED; PG8_LDA(At, 0, 0); PG8_STAGE(PG8_SA(1, 1), a1 + hstep, voffA);
;             PG8_WAIT_V(8); PG8_WAIT_L(0); PG8_BAR; PG8_MMA(0, 0, At, B0); PG8_MMA(0, 1, At, B1); PG8_BAR; PG8_SCHED;
;             PG8_LDA(At, 0, 1); PG8_STAGE(PG8_SB(0, 0), b2, voffB); PG8_STAGE(PG8_SB(0, 1), b2 + hstep, voffB); PG8_STAGE(PG8_SA(0, 0), a2, voffA);
;             PG8_WAIT_V(8); PG8_WAIT_L(0); PG8_BAR; PG8_MMA(1, 0, At, B0); PG8_MMA(1, 1, At, B1); PG8_BAR; PG8_SCHED;
.LBB0_185:
	s_add_u32 s18, s16, 0xfffc0080
	s_addc_u32 s19, s17, -1
	s_add_i32 s41, 0, 0x10000
	s_cmp_eq_u32 s40, 12
	s_cselect_b32 s21, s9, s19
	s_cselect_b32 s20, s36, s18
	v_add_u32_e32 v38, s41, v151
	s_cselect_b32 s19, s7, s39
	s_cselect_b32 s18, s37, s38
	s_add_i32 s44, 0, 0x14000
	ds_read_b128 v[146:149], v38
	ds_read_b128 v[154:157], v38 offset:1024
	ds_read_b128 v[158:161], v38 offset:2048
	ds_read_b128 v[162:165], v38 offset:3072
	v_add_u32_e32 v38, s44, v151
	ds_read_b128 v[166:169], v38
	ds_read_b128 v[170:173], v38 offset:1024
	ds_read_b128 v[174:177], v38 offset:2048
	ds_read_b128 v[178:181], v38 offset:3072
	v_lshl_add_u64 v[202:203], s[16:17], 0, v[142:143]
	s_add_i32 m0, s25, 0xc000
	ds_read_b128 v[186:189], v153
	ds_read_b128 v[190:193], v153 offset:1024
	ds_read_b128 v[194:197], v153 offset:2048
	ds_read_b128 v[198:201], v153 offset:3072
	ds_read_b128 v[226:229], v153 offset:4096
	ds_read_b128 v[230:233], v153 offset:5120
	ds_read_b128 v[234:237], v153 offset:6144
	ds_read_b128 v[238:241], v153 offset:7168
	global_load_lds_dwordx4 v[202:203], off
	v_lshl_add_u64 v[202:203], s[16:17], 0, v[144:145]
	s_add_i32 m0, s25, 0xe000
	s_nop 0
	global_load_lds_dwordx4 v[202:203], off
	s_waitcnt vmcnt(8)
	s_waitcnt lgkmcnt(0)
	s_barrier
	s_waitcnt lgkmcnt(0)
	v_mfma_f32_16x16x32_bf16 v[134:137], v[146:149], v[186:189], v[134:137]
	v_mfma_f32_16x16x32_bf16 v[130:133], v[158:161], v[186:189], v[130:133]
	v_mfma_f32_16x16x32_bf16 v[126:129], v[146:149], v[194:197], v[126:129]
	v_mfma_f32_16x16x32_bf16 v[118:121], v[158:161], v[194:197], v[118:121]
	v_mfma_f32_16x16x32_bf16 v[110:113], v[146:149], v[226:229], v[110:113]
	v_mfma_f32_16x16x32_bf16 v[102:105], v[158:161], v[226:229], v[102:105]
	v_mfma_f32_16x16x32_bf16 v[94:97], v[146:149], v[234:237], v[94:97]
	v_mfma_f32_16x16x32_bf16 v[86:89], v[158:161], v[234:237], v[86:89]
	v_mfma_f32_16x16x32_bf16 v[134:137], v[154:157], v[190:193], v[134:137]
	v_mfma_f32_16x16x32_bf16 v[130:133], v[162:165], v[190:193], v[130:133]
	v_mfma_f32_16x16x32_bf16 v[126:129], v[154:157], v[198:201], v[126:129]
	v_mfma_f32_16x16x32_bf16 v[118:121], v[162:165], v[198:201], v[118:121]
	v_mfma_f32_16x16x32_bf16 v[110:113], v[154:157], v[230:233], v[110:113]
	v_mfma_f32_16x16x32_bf16 v[102:105], v[162:165], v[230:233], v[102:105]
	v_mfma_f32_16x16x32_bf16 v[94:97], v[154:157], v[238:241], v[94:97]
	v_mfma_f32_16x16x32_bf16 v[86:89], v[162:165], v[238:241], v[86:89]
	v_mfma_f32_16x16x32_bf16 v[122:125], v[166:169], v[186:189], v[122:125]
	v_mfma_f32_16x16x32_bf16 v[114:117], v[174:177], v[186:189], v[114:117]
	v_mfma_f32_16x16x32_bf16 v[106:109], v[166:169], v[194:197], v[106:109]
	v_mfma_f32_16x16x32_bf16 v[98:101], v[174:177], v[194:197], v[98:101]
	v_mfma_f32_16x16x32_bf16 v[90:93], v[166:169], v[226:229], v[90:93]
	v_mfma_f32_16x16x32_bf16 v[82:85], v[174:177], v[226:229], v[82:85]
	v_mfma_f32_16x16x32_bf16 v[78:81], v[166:169], v[234:237], v[78:81]
	v_mfma_f32_16x16x32_bf16 v[74:77], v[174:177], v[234:237], v[74:77]
	v_mfma_f32_16x16x32_bf16 v[122:125], v[170:173], v[190:193], v[122:125]
	v_mfma_f32_16x16x32_bf16 v[114:117], v[178:181], v[190:193], v[114:117]
	v_mfma_f32_16x16x32_bf16 v[106:109], v[170:173], v[198:201], v[106:109]
	v_mfma_f32_16x16x32_bf16 v[98:101], v[178:181], v[198:201], v[98:101]
	v_mfma_f32_16x16x32_bf16 v[90:93], v[170:173], v[230:233], v[90:93]
	v_mfma_f32_16x16x32_bf16 v[82:85], v[178:181], v[230:233], v[82:85]
	v_mfma_f32_16x16x32_bf16 v[78:81], v[170:173], v[238:241], v[78:81]
	v_mfma_f32_16x16x32_bf16 v[74:77], v[178:181], v[238:241], v[74:77]
	s_barrier
	s_add_i32 s41, s41, s24
	v_lshl_add_u64 v[202:203], s[18:19], 0, v[34:35]
	s_mov_b32 m0, s41
	ds_read_b128 v[186:189], v153 offset:16384
	ds_read_b128 v[190:193], v153 offset:17408
	ds_read_b128 v[194:197], v153 offset:18432
	ds_read_b128 v[198:201], v153 offset:19456
	ds_read_b128 v[226:229], v153 offset:20480
	ds_read_b128 v[230:233], v153 offset:21504
	ds_read_b128 v[234:237], v153 offset:22528
	ds_read_b128 v[238:241], v153 offset:23552
	global_load_lds_dwordx4 v[202:203], off
	s_add_i32 m0, s41, 0x2000
	s_add_u32 s42, s18, 0x40000
	v_lshl_add_u64 v[208:209], s[18:19], 0, v[36:37]
	s_addc_u32 s43, s19, 0
	s_add_i32 s41, s44, s24
	global_load_lds_dwordx4 v[208:209], off
	v_lshl_add_u64 v[210:211], s[42:43], 0, v[34:35]
	s_mov_b32 m0, s41
	v_lshl_add_u64 v[218:219], s[20:21], 0, v[138:139]
	global_load_lds_dwordx4 v[210:211], off
	v_lshl_add_u64 v[210:211], s[42:43], 0, v[36:37]
	s_add_i32 m0, s41, 0x2000
	s_nop 0
	global_load_lds_dwordx4 v[210:211], off
	v_lshl_add_u64 v[210:211], s[20:21], 0, v[140:141]
	s_mov_b32 m0, s25
	s_nop 0
	global_load_lds_dwordx4 v[210:211], off
	s_mov_b32 m0, s26
	s_nop 0
	global_load_lds_dwordx4 v[218:219], off
	s_waitcnt vmcnt(8)
	s_waitcnt lgkmcnt(0)
	s_barrier
; #define PG8_STAGE(bufoff, gbase, voff) do { _Pragma("unroll") for (int _i = 0; _i < 2; ++_i) \
;         __builtin_amdgcn_global_load_lds((const unsigned*)((const char*)(gbase) + (voff)[_i]), (PG8_LAS unsigned*)(lds + (bufoff) + ldsw + _i * 8192), 16, 0, 0); } while (0)
; #define PG8_LDA(dst, b, h) do { _Pragma("unroll") for (int m = 0; m < 4; ++m) _Pragma("unroll") for (int k = 0; k < 2; ++k) dst[m][k] = *(const PG8_LAS bf16x8*)(lds + PG8_SA(b, h) + aoff + m * 2048 + k * 1024); } while (0)
; #define PG8_LDB(dst, b, h) do { _Pragma("unroll") for (int n = 0; n < 2; ++n) _Pragma("unroll") for (int k = 0; k < 2; ++k) dst[n][k] = *(const PG8_LAS bf16x8*)(lds + PG8_SB(b, h) + boff + n * 2048 + k * 1024); } while (0)
; #define PG8_MMA(ai, bj, At, Bt) do { __builtin_amdgcn_s_setprio(1); _Pragma("unroll") for (int m = 0; m < 4; ++m) _Pragma("unroll") for (int n = 0; n < 2; ++n) _Pragma("unroll") for (int k = 0; k < 2; ++k) \
;         acc[ai][bj][m][n] = __builtin_amdgcn_mfma_f32_16x16x32_bf16(Bt[n][k], At[m][k], acc[ai][bj][m][n], 0, 0, 0); __builtin_amdgcn_s_setprio(0); } while (0)
; #define PG8_WAIT_V(n) asm volatile("s_waitcnt vmcnt(" #n ")" ::: "memory")
; #define PG8_WAIT_L(n) asm volatile("s_waitcnt lgkmcnt(" #n ")" ::: "memory")
; #define PG8_BAR __builtin_amdgcn_s_barrier()
; #define PG8_SCHED __builtin_amdgcn_sched_barrier(0)
; template <class Epi, class Sched, bool ALIGN_EPI = false, bool SP2 = false>
; __device__ __forceinline__ void gemm_phase(PG8_LAS unsigned char* lds, const Gemm g, const Sched& S, const Epi& E) {
;     ...
;             PG8_WAIT_V(8); PG8_WAIT_L(0); PG8_BAR; PG8_MMA(1, 0, At, B0); PG8_MMA(1, 1, At, B1); PG8_BAR; PG8_SCHED;
;             PG8_LDB(B0, 1, 0); PG8_LDB(B1, 1, 1); PG8_SCHED; PG8_LDA(At, 1, 0); PG8_STAGE(PG8_SA(0, 1), a2 + hstep, voffA);
;             PG8_WAIT_V(8); PG8_WAIT_L(0); PG8_BAR; PG8_MMA(0, 0, At, B0); PG8_MMA(0, 1, At, B1); PG8_BAR; PG8_SCHED;
	s_waitcnt lgkmcnt(0)
	v_mfma_f32_16x16x32_bf16 v[70:73], v[146:149], v[186:189], v[70:73]
	v_mfma_f32_16x16x32_bf16 v[66:69], v[158:161], v[186:189], v[66:69]
	v_mfma_f32_16x16x32_bf16 v[62:65], v[146:149], v[194:197], v[62:65]
	v_mfma_f32_16x16x32_bf16 v[54:57], v[158:161], v[194:197], v[54:57]
	v_mfma_f32_16x16x32_bf16 v[46:49], v[146:149], v[226:229], v[46:49]
	v_mfma_f32_16x16x32_bf16 v[30:33], v[158:161], v[226:229], v[30:33]
	v_mfma_f32_16x16x32_bf16 v[22:25], v[146:149], v[234:237], v[22:25]
	v_mfma_f32_16x16x32_bf16 v[14:17], v[158:161], v[234:237], v[14:17]
	v_mfma_f32_16x16x32_bf16 v[70:73], v[154:157], v[190:193], v[70:73]
	v_mfma_f32_16x16x32_bf16 v[66:69], v[162:165], v[190:193], v[66:69]
	v_mfma_f32_16x16x32_bf16 v[62:65], v[154:157], v[198:201], v[62:65]
	v_mfma_f32_16x16x32_bf16 v[54:57], v[162:165], v[198:201], v[54:57]
	v_mfma_f32_16x16x32_bf16 v[46:49], v[154:157], v[230:233], v[46:49]
	v_mfma_f32_16x16x32_bf16 v[30:33], v[162:165], v[230:233], v[30:33]
	v_mfma_f32_16x16x32_bf16 v[22:25], v[154:157], v[238:241], v[22:25]
	v_mfma_f32_16x16x32_bf16 v[14:17], v[162:165], v[238:241], v[14:17]
	v_mfma_f32_16x16x32_bf16 v[58:61], v[166:169], v[186:189], v[58:61]
	v_mfma_f32_16x16x32_bf16 v[50:53], v[174:177], v[186:189], v[50:53]
	v_mfma_f32_16x16x32_bf16 v[42:45], v[166:169], v[194:197], v[42:45]
	v_mfma_f32_16x16x32_bf16 v[26:29], v[174:177], v[194:197], v[26:29]
	v_mfma_f32_16x16x32_bf16 v[18:21], v[166:169], v[226:229], v[18:21]
	v_mfma_f32_16x16x32_bf16 v[10:13], v[174:177], v[226:229], v[10:13]
	v_mfma_f32_16x16x32_bf16 v[6:9], v[166:169], v[234:237], v[6:9]
	v_mfma_f32_16x16x32_bf16 v[2:5], v[174:177], v[234:237], v[2:5]
	v_mfma_f32_16x16x32_bf16 v[58:61], v[170:173], v[190:193], v[58:61]
	v_mfma_f32_16x16x32_bf16 v[50:53], v[178:181], v[190:193], v[50:53]
	v_mfma_f32_16x16x32_bf16 v[42:45], v[170:173], v[198:201], v[42:45]
	v_mfma_f32_16x16x32_bf16 v[26:29], v[178:181], v[198:201], v[26:29]
	v_mfma_f32_16x16x32_bf16 v[18:21], v[170:173], v[230:233], v[18:21]
	v_mfma_f32_16x16x32_bf16 v[10:13], v[178:181], v[230:233], v[10:13]
	v_mfma_f32_16x16x32_bf16 v[6:9], v[170:173], v[238:241], v[6:9]
	v_mfma_f32_16x16x32_bf16 v[2:5], v[178:181], v[238:241], v[2:5]
	s_barrier
	s_add_i32 s41, 0, 0x18000
	v_add_u32_e32 v38, s41, v151
	s_add_i32 s42, 0, 0x1c000
	ds_read_b128 v[146:149], v38
	ds_read_b128 v[154:157], v38 offset:1024
	ds_read_b128 v[158:161], v38 offset:2048
	ds_read_b128 v[162:165], v38 offset:3072
	v_add_u32_e32 v38, s42, v151
	ds_read_b128 v[166:169], v38
	ds_read_b128 v[170:173], v38 offset:1024
	ds_read_b128 v[174:177], v38 offset:2048
	ds_read_b128 v[178:181], v38 offset:3072
	s_add_u32 s20, s20, 0x40000
	s_addc_u32 s21, s21, 0
	s_mov_b32 m0, s27
	v_lshl_add_u64 v[220:221], s[20:21], 0, v[140:141]
	ds_read_b128 v[186:189], v153 offset:32768
	ds_read_b128 v[190:193], v153 offset:33792
	ds_read_b128 v[194:197], v153 offset:34816
	ds_read_b128 v[198:201], v153 offset:35840
	ds_read_b128 v[226:229], v153 offset:36864
	ds_read_b128 v[230:233], v153 offset:37888
	ds_read_b128 v[234:237], v153 offset:38912
	ds_read_b128 v[238:241], v153 offset:39936
	global_load_lds_dwordx4 v[220:221], off
	v_lshl_add_u64 v[220:221], s[20:21], 0, v[138:139]
	s_mov_b32 m0, s28
	s_nop 0
	global_load_lds_dwordx4 v[220:221], off
	s_waitcnt vmcnt(8)
	s_waitcnt lgkmcnt(0)
	s_barrier
	s_waitcnt lgkmcnt(0)
	v_mfma_f32_16x16x32_bf16 v[134:137], v[146:149], v[186:189], v[134:137]
	v_mfma_f32_16x16x32_bf16 v[130:133], v[158:161], v[186:189], v[130:133]
	v_mfma_f32_16x16x32_bf16 v[126:129], v[146:149], v[194:197], v[126:129]
	v_mfma_f32_16x16x32_bf16 v[118:121], v[158:161], v[194:197], v[118:121]
	v_mfma_f32_16x16x32_bf16 v[110:113], v[146:149], v[226:229], v[110:113]
	v_mfma_f32_16x16x32_bf16 v[102:105], v[158:161], v[226:229], v[102:105]
	v_mfma_f32_16x16x32_bf16 v[94:97], v[146:149], v[234:237], v[94:97]
	v_mfma_f32_16x16x32_bf16 v[86:89], v[158:161], v[234:237], v[86:89]
	v_mfma_f32_16x16x32_bf16 v[134:137], v[154:157], v[190:193], v[134:137]
	v_mfma_f32_16x16x32_bf16 v[130:133], v[162:165], v[190:193], v[130:133]
	v_mfma_f32_16x16x32_bf16 v[126:129], v[154:157], v[198:201], v[126:129]
	v_mfma_f32_16x16x32_bf16 v[118:121], v[162:165], v[198:201], v[118:121]
	v_mfma_f32_16x16x32_bf16 v[110:113], v[154:157], v[230:233], v[110:113]
	v_mfma_f32_16x16x32_bf16 v[102:105], v[162:165], v[230:233], v[102:105]
	v_mfma_f32_16x16x32_bf16 v[94:97], v[154:157], v[238:241], v[94:97]
	v_mfma_f32_16x16x32_bf16 v[86:89], v[162:165], v[238:241], v[86:89]
	v_mfma_f32_16x16x32_bf16 v[122:125], v[166:169], v[186:189], v[122:125]
	v_mfma_f32_16x16x32_bf16 v[114:117], v[174:177], v[186:189], v[114:117]
	v_mfma_f32_16x16x32_bf16 v[106:109], v[166:169], v[194:197], v[106:109]
	v_mfma_f32_16x16x32_bf16 v[98:101], v[174:177], v[194:197], v[98:101]
	v_mfma_f32_16x16x32_bf16 v[90:93], v[166:169], v[226:229], v[90:93]
	v_mfma_f32_16x16x32_bf16 v[82:85], v[174:177], v[226:229], v[82:85]
	v_mfma_f32_16x16x32_bf16 v[78:81], v[166:169], v[234:237], v[78:81]
	v_mfma_f32_16x16x32_bf16 v[74:77], v[174:177], v[234:237], v[74:77]
	v_mfma_f32_16x16x32_bf16 v[122:125], v[170:173], v[190:193], v[122:125]
	v_mfma_f32_16x16x32_bf16 v[114:117], v[178:181], v[190:193], v[114:117]
	v_mfma_f32_16x16x32_bf16 v[106:109], v[170:173], v[198:201], v[106:109]
	v_mfma_f32_16x16x32_bf16 v[98:101], v[178:181], v[198:201], v[98:101]
	v_mfma_f32_16x16x32_bf16 v[90:93], v[170:173], v[230:233], v[90:93]
	v_mfma_f32_16x16x32_bf16 v[82:85], v[178:181], v[230:233], v[82:85]
	v_mfma_f32_16x16x32_bf16 v[78:81], v[170:173], v[238:241], v[78:81]
	v_mfma_f32_16x16x32_bf16 v[74:77], v[178:181], v[238:241], v[74:77]
	s_barrier
; #define PG8_STAGE(bufoff, gbase, voff) do { _Pragma("unroll") for (int _i = 0; _i < 2; ++_i) \
;         __builtin_amdgcn_global_load_lds((const unsigned*)((const char*)(gbase) + (voff)[_i]), (PG8_LAS unsigned*)(lds + (bufoff) + ldsw + _i * 8192), 16, 0, 0); } while (0)
; #define PG8_LDA(dst, b, h) do { _Pragma("unroll") for (int m = 0; m < 4; ++m) _Pragma("unroll") for (int k = 0; k < 2; ++k) dst[m][k] = *(const PG8_LAS bf16x8*)(lds + PG8_SA(b, h) + aoff + m * 2048 + k * 1024); } while (0)
; #define PG8_MMA(ai, bj, At, Bt) do { __builtin_amdgcn_s_setprio(1); _Pragma("unroll") for (int m = 0; m < 4; ++m) _Pragma("unroll") for (int n = 0; n < 2; ++n) _Pragma("unroll") for (int k = 0; k < 2; ++k) \
;         acc[ai][bj][m][n] = __builtin_amdgcn_mfma_f32_16x16x32_bf16(Bt[n][k], At[m][k], acc[ai][bj][m][n], 0, 0, 0); __builtin_amdgcn_s_setprio(0); } while (0)
; #define PG8_WAIT_V(n) asm volatile("s_waitcnt vmcnt(" #n ")" ::: "memory")
; #define PG8_WAIT_L(n) asm volatile("s_waitcnt lgkmcnt(" #n ")" ::: "memory")
; #define PG8_BAR __builtin_amdgcn_s_barrier()
; #define PG8_SCHED __builtin_amdgcn_sched_barrier(0)
; template <class Epi, class Sched, bool ALIGN_EPI = false, bool SP2 = false>
; __device__ __forceinline__ void gemm_phase(PG8_LAS unsigned char* lds, const Gemm g, const Sched& S, const Epi& E) {
;     ...
;             PG8_LDA(At, 1, 1); PG8_STAGE(PG8_SB(1, 0), b3, voffB); PG8_STAGE(PG8_SB(1, 1), b3 + hstep, voffB); PG8_STAGE(PG8_SA(1, 0), a3, voffA);
;             PG8_WAIT_V(8); PG8_WAIT_L(0); PG8_BAR; PG8_MMA(1, 0, At, B0); PG8_MMA(1, 1, At, B1); PG8_BAR; PG8_SCHED;
	s_add_i32 s20, s41, s24
	v_lshl_add_u64 v[202:203], v[202:203], 0, s[70:71]
	s_mov_b32 m0, s20
	ds_read_b128 v[186:189], v153 offset:49152
	ds_read_b128 v[190:193], v153 offset:50176
	ds_read_b128 v[194:197], v153 offset:51200
	ds_read_b128 v[198:201], v153 offset:52224
	ds_read_b128 v[226:229], v153 offset:53248
	ds_read_b128 v[230:233], v153 offset:54272
	ds_read_b128 v[234:237], v153 offset:55296
	ds_read_b128 v[238:241], v153 offset:56320
	global_load_lds_dwordx4 v[202:203], off
	s_add_i32 m0, s20, 0x2000
	s_add_u32 s18, s18, 0x40080
	v_lshl_add_u64 v[202:203], v[208:209], 0, s[70:71]
	s_addc_u32 s19, s19, 0
	s_add_i32 s20, s42, s24
	global_load_lds_dwordx4 v[202:203], off
	v_lshl_add_u64 v[202:203], s[18:19], 0, v[34:35]
	s_mov_b32 m0, s20
	s_nop 0
	global_load_lds_dwordx4 v[202:203], off
	v_lshl_add_u64 v[202:203], s[18:19], 0, v[36:37]
	s_add_i32 m0, s20, 0x2000
	s_nop 0
	global_load_lds_dwordx4 v[202:203], off
	v_lshl_add_u64 v[202:203], v[210:211], 0, s[70:71]
	s_mov_b32 m0, s29
	s_nop 0
	global_load_lds_dwordx4 v[202:203], off
	v_lshl_add_u64 v[202:203], v[218:219], 0, s[70:71]
	s_mov_b32 m0, s30
	s_nop 0
	global_load_lds_dwordx4 v[202:203], off
	s_waitcnt vmcnt(8)
	s_waitcnt lgkmcnt(0)
	s_barrier
	s_waitcnt lgkmcnt(0)
	v_mfma_f32_16x16x32_bf16 v[70:73], v[146:149], v[186:189], v[70:73]
	v_mfma_f32_16x16x32_bf16 v[66:69], v[158:161], v[186:189], v[66:69]
	v_mfma_f32_16x16x32_bf16 v[62:65], v[146:149], v[194:197], v[62:65]
	v_mfma_f32_16x16x32_bf16 v[54:57], v[158:161], v[194:197], v[54:57]
	v_mfma_f32_16x16x32_bf16 v[46:49], v[146:149], v[226:229], v[46:49]
	v_mfma_f32_16x16x32_bf16 v[30:33], v[158:161], v[226:229], v[30:33]
	v_mfma_f32_16x16x32_bf16 v[22:25], v[146:149], v[234:237], v[22:25]
	v_mfma_f32_16x16x32_bf16 v[14:17], v[158:161], v[234:237], v[14:17]
	v_mfma_f32_16x16x32_bf16 v[70:73], v[154:157], v[190:193], v[70:73]
	v_mfma_f32_16x16x32_bf16 v[66:69], v[162:165], v[190:193], v[66:69]
	v_mfma_f32_16x16x32_bf16 v[62:65], v[154:157], v[198:201], v[62:65]
	v_mfma_f32_16x16x32_bf16 v[54:57], v[162:165], v[198:201], v[54:57]
	v_mfma_f32_16x16x32_bf16 v[46:49], v[154:157], v[230:233], v[46:49]
	v_mfma_f32_16x16x32_bf16 v[30:33], v[162:165], v[230:233], v[30:33]
	v_mfma_f32_16x16x32_bf16 v[22:25], v[154:157], v[238:241], v[22:25]
	v_mfma_f32_16x16x32_bf16 v[14:17], v[162:165], v[238:241], v[14:17]
	v_mfma_f32_16x16x32_bf16 v[58:61], v[166:169], v[186:189], v[58:61]
	v_mfma_f32_16x16x32_bf16 v[50:53], v[174:177], v[186:189], v[50:53]
	v_mfma_f32_16x16x32_bf16 v[42:45], v[166:169], v[194:197], v[42:45]
	v_mfma_f32_16x16x32_bf16 v[26:29], v[174:177], v[194:197], v[26:29]
	v_mfma_f32_16x16x32_bf16 v[18:21], v[166:169], v[226:229], v[18:21]
	v_mfma_f32_16x16x32_bf16 v[10:13], v[174:177], v[226:229], v[10:13]
	v_mfma_f32_16x16x32_bf16 v[6:9], v[166:169], v[234:237], v[6:9]
	v_mfma_f32_16x16x32_bf16 v[2:5], v[174:177], v[234:237], v[2:5]
	v_mfma_f32_16x16x32_bf16 v[58:61], v[170:173], v[190:193], v[58:61]
	v_mfma_f32_16x16x32_bf16 v[50:53], v[178:181], v[190:193], v[50:53]
	v_mfma_f32_16x16x32_bf16 v[42:45], v[170:173], v[198:201], v[42:45]
	v_mfma_f32_16x16x32_bf16 v[26:29], v[178:181], v[198:201], v[26:29]
	v_mfma_f32_16x16x32_bf16 v[18:21], v[170:173], v[230:233], v[18:21]
	v_mfma_f32_16x16x32_bf16 v[10:13], v[178:181], v[230:233], v[10:13]
	v_mfma_f32_16x16x32_bf16 v[6:9], v[170:173], v[238:241], v[6:9]
	v_mfma_f32_16x16x32_bf16 v[2:5], v[178:181], v[238:241], v[2:5]
	s_barrier
	s_add_i32 s40, s40, 2
	s_add_u32 s16, s16, 0x100
	s_addc_u32 s17, s17, 0
	s_add_u32 s38, s38, 0x100
	s_addc_u32 s39, s39, 0
	s_cmp_gt_u32 s40, 13
	s_cbranch_scc0 .LBB0_185
	s_and_b64 vcc, exec, s[4:5]
	s_cbranch_vccz .LBB0_188
	s_barrier

; #define PG8_WAIT_V(n) asm volatile("s_waitcnt vmcnt(" #n ")" ::: "memory")
; #define PG8_BAR __builtin_amdgcn_s_barrier()
; template <class Epi, class Sched, bool ALIGN_EPI = false, bool SP2 = false>
; __device__ __forceinline__ void gemm_phase(PG8_LAS unsigned char* lds, const Gemm g, const Sched& S, const Epi& E) {
;     ...
;     PG8_WAIT_V(0);
;     if constexpr (!ALIGN_EPI) { if (wr == 0) PG8_BAR; }
;     PG8_BAR;
; __device__ __forceinline__ void xcd_barrier(const XcdBarrier& b) {
;     asm volatile("s_waitcnt vmcnt(0)" ::: "memory");
;     __syncthreads();
;     if (threadIdx.x == 0) {
;         unsigned* bar = b.bar;
;         __builtin_amdgcn_s_waitcnt(0);
;         unsigned nloc = b.st[0], nx = b.st[1];
;         if (nloc == 0u) { xcd_barrier_complete(bar, b.x, nloc, nx); b.st[0] = nloc; b.st[1] = nx; }
.LBB0_192:
	ds_read_b64 v[2:3], v204
	s_setprio 0
	s_getreg_b32 s4, hwreg(HW_REG_XCC_ID, 0, 4)
	s_waitcnt vmcnt(0)
	s_waitcnt vmcnt(0) lgkmcnt(0)
	s_barrier
	v_readfirstlane_b32 s3, v3
	v_readfirstlane_b32 s2, v2
	s_and_saveexec_b64 s[0:1], s[76:77]
	s_xor_b64 s[0:1], exec, s[0:1]
	s_cbranch_execz .LBB0_246
	v_readlane_b32 s5, v254, 24
	s_waitcnt vmcnt(0) expcnt(0) lgkmcnt(0)
	s_and_b32 s48, s4, 15
	v_mov_b32_e32 v2, s5
	ds_read_b32 v4, v2
	v_readlane_b32 s5, v254, 25
	s_waitcnt lgkmcnt(0)
	v_cmp_ne_u32_e32 vcc, 0, v4
	v_mov_b32_e32 v2, s5
	ds_read_b32 v2, v2
	s_cbranch_vccnz .LBB0_209
	v_readlane_b32 s4, v253, 0
	v_readlane_b32 s5, v253, 1
	s_load_dwordx2 s[8:9], s[4:5], 0x4
	s_add_u32 s4, s2, 0x1200
	s_addc_u32 s5, s3, 0
	s_add_u32 s6, s2, 0x1400
	s_addc_u32 s7, s3, 0
	s_waitcnt lgkmcnt(0)
	s_mul_i32 s49, s8, s84
	s_add_u32 s8, s2, 0x1500
	s_mul_i32 s49, s49, s9
	s_addc_u32 s9, s3, 0
	s_add_u32 s10, s2, 0x1600
	s_addc_u32 s11, s3, 0
	s_add_u32 s12, s2, 0x1700
	s_addc_u32 s13, s3, 0
	s_add_u32 s16, s2, 0x1800
	s_addc_u32 s17, s3, 0
	s_add_u32 s18, s2, 0x1900
	s_addc_u32 s19, s3, 0
	s_add_u32 s20, s2, 0x1a00
	s_addc_u32 s21, s3, 0
	s_add_u32 s22, s2, 0x1b00
	s_addc_u32 s23, s3, 0
	s_add_u32 s24, s2, 0x1c00
	s_addc_u32 s25, s3, 0
	s_add_u32 s26, s2, 0x1d00
	s_addc_u32 s27, s3, 0
	s_add_u32 s28, s2, 0x1e00
	s_addc_u32 s29, s3, 0
	s_add_u32 s30, s2, 0x1f00
	s_addc_u32 s31, s3, 0
	s_add_u32 s34, s2, 0x2000
	s_addc_u32 s35, s3, 0
	s_add_u32 s36, s2, 0x2100
	s_addc_u32 s37, s3, 0
	s_add_u32 s38, s2, 0x2200
	s_addc_u32 s39, s3, 0
	s_add_u32 s40, s2, 0x2300
	s_addc_u32 s41, s3, 0
	s_mov_b32 s50, 1
	s_branch .LBB0_197

;     __device__ __forceinline__ long arow(int pm) const { return (long)pm * BM; }
;     __device__ __forceinline__ long arow(int pm) const { if (pm < 132) { const int b = pm / 33, i = pm - b * 33; return (long)b * 8192 + 254 * i - 1; } return 32768 + (long)(pm - 132) * 256; }
;     __device__ __forceinline__ long arow(int p) const { return (long)p * BM; }
; #define PG8_STAGE(bufoff, gbase, voff) do { _Pragma("unroll") for (int _i = 0; _i < 2; ++_i) \
;         __builtin_amdgcn_global_load_lds((const unsigned*)((const char*)(gbase) + (voff)[_i]), (PG8_LAS unsigned*)(lds + (bufoff) + ldsw + _i * 8192), 16, 0, 0); } while (0)
; #define PG8_BAR __builtin_amdgcn_s_barrier()
; template <class Epi, class Sched, bool ALIGN_EPI = false, bool SP2 = false>
; __device__ __forceinline__ void gemm_phase(PG8_LAS unsigned char* lds, const Gemm g, const Sched& S, const Epi& E) {
;     ...
;     for (int i = 0; i < 2; ++i) { int R, C; stage_rc(tid * 16 + i * 8192, R, C); const int Rb = Epi::PERM ? ((R & ~31) + perm32(R & 31)) : R;
;         voffA[i] = (unsigned)(R * LD + C) * 2u; voffB[i] = (unsigned)(Rb * LD + C) * 2u; }
;     ...
;     const char* cA = (const char*)g.A + S.arow(cur.pm) * rowb; const char* cB = (const char*)g.Bt + (size_t)cur.pn * tstep;
;     S.a_ready(cur);
;     if constexpr (SP2) {
;         PG8_STAGE(PG8_SB(0, 0), cB, voffB); PG8_STAGE(PG8_SB(0, 1), cB + hstep, voffB); PG8_STAGE(PG8_SA(0, 0), cA, voffA); PG8_STAGE(PG8_SA(0, 1), cA + hstep, voffA);
;         if (wr == 1) PG8_BAR;
.LBB0_529:
	s_or_b64 exec, exec, s[0:1]
	s_waitcnt lgkmcnt(0)
	s_barrier
	ds_read_b64 v[2:3], v217
	v_readlane_b32 s0, v255, 7
	v_mov_b32_e32 v10, v225
	v_readlane_b32 s1, v255, 8
	s_waitcnt lgkmcnt(0)
	v_readfirstlane_b32 s24, v3
	v_readfirstlane_b32 s25, v2
	s_and_b64 vcc, exec, s[0:1]
	v_readfirstlane_b32 s2, v10
	s_cbranch_vccnz .LBB0_553
	v_lshlrev_b32_e32 v2, 4, v10
	v_add_u32_e32 v3, 0x2000, v2
	v_ashrrev_i32_e32 v4, 31, v3
	v_lshrrev_b32_e32 v4, 22, v4
	v_add_u32_e32 v4, v3, v4
	v_ashrrev_i32_e32 v6, 10, v4
	v_mul_i32_i24_e32 v4, 0x400, v6
	v_sub_u32_e32 v3, v3, v4
	v_lshrrev_b32_e32 v4, 4, v3
	v_bitop3_b32 v3, v4, v3, 32 bitop3:0x6c
	v_ashrrev_i32_e32 v4, 31, v3
	v_lshrrev_b32_e32 v4, 26, v4
	v_add_u32_e32 v4, v3, v4
	v_ashrrev_i32_e32 v7, 6, v4
	v_and_b32_e32 v4, 0xc0, v4
	v_sub_u32_e32 v3, v3, v4
	v_mov_b32_e32 v14, 1
	v_ashrrev_i16_sdwa v3, v14, sext(v3) dst_sel:DWORD dst_unused:UNUSED_PAD src0_sel:DWORD src1_sel:BYTE_0
	v_bfe_i32 v9, v3, 0, 16
	v_bfe_i32 v3, v10, 27, 1
	v_lshrrev_b32_e32 v3, 22, v3
	v_add_u32_e32 v3, v2, v3
	v_and_b32_e32 v3, 0xfffffc00, v3
	v_sub_u32_e32 v2, v2, v3
	v_lshrrev_b32_e32 v3, 4, v2
	v_readlane_b32 s0, v254, 27
	v_bitop3_b32 v2, v3, v2, 32 bitop3:0x6c
	v_ashrrev_i32_e32 v4, 31, v10
	v_readlane_b32 s1, v254, 28
	v_lshlrev_b32_e32 v5, 3, v6
	v_ashrrev_i32_e32 v3, 31, v2
	v_lshrrev_b32_e32 v4, 26, v4
	s_lshl_b64 s[0:1], s[0:1], 21
	v_readlane_b32 s3, v253, 27
	v_and_b32_e32 v5, 0x1ffff0, v5
	v_lshlrev_b32_e32 v8, 5, v6
	v_lshrrev_b32_e32 v3, 26, v3
	v_add_u32_e32 v4, v10, v4
	s_add_u32 s26, s3, s0
	v_readlane_b32 s0, v253, 28
	v_add_u32_e32 v5, v7, v5
	v_and_b32_e32 v8, 32, v8
	v_add_u32_e32 v3, v2, v3
	v_ashrrev_i32_e32 v12, 6, v4
	s_addc_u32 s27, s0, s1
	s_ashr_i32 s4, s2, 6
	v_lshl_or_b32 v5, v5, 10, v8
	v_ashrrev_i32_e32 v11, 6, v3
	v_lshlrev_b32_e32 v4, 3, v12
	v_and_b32_e32 v3, 0xc0, v3
	s_ashr_i32 s3, s2, 8
	s_lshl_b32 s28, s4, 10
	v_add_lshl_u32 v36, v5, v9, 1
	v_and_b32_e32 v4, 0x1ffff0, v4
	v_lshlrev_b32_e32 v5, 5, v12
	v_sub_u32_e32 v2, v2, v3
	v_readlane_b32 s0, v253, 58
	v_add_u32_e32 v4, v11, v4
	v_and_b32_e32 v13, 32, v5
	v_ashrrev_i16_sdwa v2, v14, sext(v2) dst_sel:DWORD dst_unused:UNUSED_PAD src0_sel:DWORD src1_sel:BYTE_0
	v_readlane_b32 s1, v253, 59
	s_add_u32 s18, s26, s0
	v_lshl_or_b32 v4, v4, 10, v13
	v_bfe_i32 v14, v2, 0, 16
	s_addc_u32 s19, s27, s1
	s_add_i32 s29, s28, 0
	v_add_lshl_u32 v34, v4, v14, 1
	s_add_i32 m0, s29, 0x10000
	v_mov_b32_e32 v37, v35
	global_load_lds_dwordx4 v34, s[18:19]
	s_add_i32 m0, s29, 0x12000
	s_add_u32 s0, s18, 0x40000
	global_load_lds_dwordx4 v36, s[18:19]
	s_addc_u32 s1, s19, 0
	s_add_i32 m0, s29, 0x14000
	s_add_i32 s30, s29, 0x2000
	global_load_lds_dwordx4 v34, s[0:1]
	s_add_i32 m0, s29, 0x16000
	s_add_i32 s31, s29, 0x4000
	global_load_lds_dwordx4 v36, s[0:1]
	v_readlane_b32 s0, v253, 60
	s_mov_b32 m0, s29
	v_readlane_b32 s1, v253, 61
	s_add_i32 s34, s29, 0x6000
	s_cmp_eq_u32 s3, 1
	v_mov_b32_e32 v214, 1
	v_lshl_add_u64 v[2:3], s[18:19], 0, v[34:35]
	v_lshl_add_u64 v[4:5], s[18:19], 0, v[36:37]
	global_load_lds_dwordx4 v34, s[0:1]
	s_mov_b32 m0, s30
	s_nop 0
	global_load_lds_dwordx4 v36, s[0:1]
	v_readlane_b32 s0, v253, 62
	s_mov_b32 m0, s31
	v_readlane_b32 s1, v253, 63
	s_nop 4
	global_load_lds_dwordx4 v34, s[0:1]
	s_mov_b32 m0, s34
	s_nop 0
	global_load_lds_dwordx4 v36, s[0:1]
	s_cselect_b64 s[0:1], -1, 0
	s_cmp_lg_u32 s3, 1
	s_cbranch_scc1 .LBB0_532
	s_barrier
	s_setprio 1

; #define PG8_STAGE(bufoff, gbase, voff) do { _Pragma("unroll") for (int _i = 0; _i < 2; ++_i) \
;         __builtin_amdgcn_global_load_lds((const unsigned*)((const char*)(gbase) + (voff)[_i]), (PG8_LAS unsigned*)(lds + (bufoff) + ldsw + _i * 8192), 16, 0, 0); } while (0)
; #define PG8_LDA(dst, b, h) do { _Pragma("unroll") for (int m = 0; m < 4; ++m) _Pragma("unroll") for (int k = 0; k < 2; ++k) dst[m][k] = *(const PG8_LAS bf16x8*)(lds + PG8_SA(b, h) + aoff + m * 2048 + k * 1024); } while (0)
; #define PG8_LDB(dst, b, h) do { _Pragma("unroll") for (int n = 0; n < 2; ++n) _Pragma("unroll") for (int k = 0; k < 2; ++k) dst[n][k] = *(const PG8_LAS bf16x8*)(lds + PG8_SB(b, h) + boff + n * 2048 + k * 1024); } while (0)
; #define PG8_MMA(ai, bj, At, Bt) do { __builtin_amdgcn_s_setprio(1); _Pragma("unroll") for (int m = 0; m < 4; ++m) _Pragma("unroll") for (int n = 0; n < 2; ++n) _Pragma("unroll") for (int k = 0; k < 2; ++k) \
;         acc[ai][bj][m][n] = __builtin_amdgcn_mfma_f32_16x16x32_bf16(Bt[n][k], At[m][k], acc[ai][bj][m][n], 0, 0, 0); __builtin_amdgcn_s_setprio(0); } while (0)
; #define PG8_WAIT_V(n) asm volatile("s_waitcnt vmcnt(" #n ")" ::: "memory")
; #define PG8_WAIT_L(n) asm volatile("s_waitcnt lgkmcnt(" #n ")" ::: "memory")
; template <class Epi, class Sched, bool ALIGN_EPI = false, bool SP2 = false>
; __device__ __forceinline__ void gemm_phase(PG8_LAS unsigned char* lds, const Gemm g, const Sched& S, const Epi& E) {
;     ...
;             const bool last = (t == nt - 2);
;             const char* a1 = cA + (size_t)(t + 1) * kstep;
;             const char* a2 = last ? nA : cA + (size_t)(t + 2) * kstep; const char* b2 = last ? nB : cB + (size_t)(t + 2) * kstep;
;             const char* a3 = a2 + kstep; const char* b3 = b2 + kstep;
;             if (last && has_next) S.a_ready(nxt);
;             if constexpr (SP2) {
;             PG8_LDB(B0, 0, 0); PG8_LDB(B1, 0, 1); PG8_SCHED; PG8_LDA(At, 0, 0); PG8_STAGE(PG8_SA(1, 1), a1 + hstep, voffA);
;             PG8_WAIT_V(8); PG8_WAIT_L(0); PG8_BAR; PG8_MMA(0, 0, At, B0); PG8_MMA(0, 1, At, B1); PG8_BAR; PG8_SCHED;
;             PG8_LDA(At, 0, 1); PG8_STAGE(PG8_SB(0, 0), b2, voffB); PG8_STAGE(PG8_SB(0, 1), b2 + hstep, voffB); PG8_STAGE(PG8_SA(0, 0), a2, voffA);
;             PG8_WAIT_V(8); PG8_WAIT_L(0); PG8_BAR; PG8_MMA(1, 0, At, B0); PG8_MMA(1, 1, At, B1); PG8_BAR; PG8_SCHED;
.LBB0_542:
	s_add_u32 s18, s16, 0x100
	s_addc_u32 s19, s17, 0
	s_add_i32 s45, 0, 0x10000
	s_cmp_eq_u32 s44, 12
	s_cselect_b32 s23, s9, s19
	s_cselect_b32 s22, s15, s18
	v_add_u32_e32 v38, s45, v168
	s_cselect_b32 s21, s7, s43
	s_cselect_b32 s20, s41, s42
	s_add_i32 s46, 0, 0x14000
	ds_read_b128 v[138:141], v38
	ds_read_b128 v[162:165], v38 offset:1024
	ds_read_b128 v[172:175], v38 offset:2048
	ds_read_b128 v[176:179], v38 offset:3072
	v_add_u32_e32 v38, s46, v168
	ds_read_b128 v[186:189], v38
	ds_read_b128 v[190:193], v38 offset:1024
	ds_read_b128 v[194:197], v38 offset:2048
	ds_read_b128 v[198:201], v38 offset:3072
	v_lshl_add_u64 v[166:167], s[16:17], 0, v[158:159]
	s_add_i32 m0, s29, 0xc000
	ds_read_b128 v[226:229], v170
	ds_read_b128 v[230:233], v170 offset:1024
	ds_read_b128 v[234:237], v170 offset:2048
	ds_read_b128 v[238:241], v170 offset:3072
	ds_read_b128 v[242:245], v170 offset:4096
	ds_read_b128 v[246:249], v170 offset:5120
	ds_read_b128 v[218:221], v170 offset:6144
	ds_read_b128 v[208:211], v170 offset:7168
	global_load_lds_dwordx4 v[166:167], off
	v_lshl_add_u64 v[166:167], s[16:17], 0, v[160:161]
	s_add_i32 m0, s29, 0xe000
	s_nop 0
	global_load_lds_dwordx4 v[166:167], off
	s_waitcnt vmcnt(8)
	s_waitcnt lgkmcnt(0)
	s_barrier
	s_waitcnt lgkmcnt(0)
	v_mfma_f32_16x16x32_bf16 v[134:137], v[138:141], v[226:229], v[134:137]
	v_mfma_f32_16x16x32_bf16 v[106:109], v[172:175], v[226:229], v[106:109]
	v_mfma_f32_16x16x32_bf16 v[130:133], v[138:141], v[234:237], v[130:133]
	v_mfma_f32_16x16x32_bf16 v[102:105], v[172:175], v[234:237], v[102:105]
	v_mfma_f32_16x16x32_bf16 v[126:129], v[138:141], v[242:245], v[126:129]
	v_mfma_f32_16x16x32_bf16 v[98:101], v[172:175], v[242:245], v[98:101]
	v_mfma_f32_16x16x32_bf16 v[122:125], v[138:141], v[218:221], v[122:125]
	v_mfma_f32_16x16x32_bf16 v[90:93], v[172:175], v[218:221], v[90:93]
	v_mfma_f32_16x16x32_bf16 v[134:137], v[162:165], v[230:233], v[134:137]
	v_mfma_f32_16x16x32_bf16 v[106:109], v[176:179], v[230:233], v[106:109]
	v_mfma_f32_16x16x32_bf16 v[130:133], v[162:165], v[238:241], v[130:133]
	v_mfma_f32_16x16x32_bf16 v[102:105], v[176:179], v[238:241], v[102:105]
	v_mfma_f32_16x16x32_bf16 v[126:129], v[162:165], v[246:249], v[126:129]
	v_mfma_f32_16x16x32_bf16 v[98:101], v[176:179], v[246:249], v[98:101]
	v_mfma_f32_16x16x32_bf16 v[122:125], v[162:165], v[208:211], v[122:125]
	v_mfma_f32_16x16x32_bf16 v[90:93], v[176:179], v[208:211], v[90:93]
	v_mfma_f32_16x16x32_bf16 v[82:85], v[186:189], v[226:229], v[82:85]
	v_mfma_f32_16x16x32_bf16 v[54:57], v[194:197], v[226:229], v[54:57]
	v_mfma_f32_16x16x32_bf16 v[74:77], v[186:189], v[234:237], v[74:77]
	v_mfma_f32_16x16x32_bf16 v[46:49], v[194:197], v[234:237], v[46:49]
	v_mfma_f32_16x16x32_bf16 v[66:69], v[186:189], v[242:245], v[66:69]
	v_mfma_f32_16x16x32_bf16 v[30:33], v[194:197], v[242:245], v[30:33]
	v_mfma_f32_16x16x32_bf16 v[58:61], v[186:189], v[218:221], v[58:61]
	v_mfma_f32_16x16x32_bf16 v[22:25], v[194:197], v[218:221], v[22:25]
	v_mfma_f32_16x16x32_bf16 v[82:85], v[190:193], v[230:233], v[82:85]
	v_mfma_f32_16x16x32_bf16 v[54:57], v[198:201], v[230:233], v[54:57]
	v_mfma_f32_16x16x32_bf16 v[74:77], v[190:193], v[238:241], v[74:77]
	v_mfma_f32_16x16x32_bf16 v[46:49], v[198:201], v[238:241], v[46:49]
	v_mfma_f32_16x16x32_bf16 v[66:69], v[190:193], v[246:249], v[66:69]
	v_mfma_f32_16x16x32_bf16 v[30:33], v[198:201], v[246:249], v[30:33]
	v_mfma_f32_16x16x32_bf16 v[58:61], v[190:193], v[208:211], v[58:61]
	v_mfma_f32_16x16x32_bf16 v[22:25], v[198:201], v[208:211], v[22:25]
	s_barrier
	s_add_i32 s16, s45, s28
	v_lshl_add_u64 v[166:167], s[20:21], 0, v[34:35]
	s_mov_b32 m0, s16
	ds_read_b128 v[208:211], v170 offset:16384
	ds_read_b128 v[218:221], v170 offset:17408
	ds_read_b128 v[226:229], v170 offset:18432
	ds_read_b128 v[230:233], v170 offset:19456
	ds_read_b128 v[234:237], v170 offset:20480
	ds_read_b128 v[238:241], v170 offset:21504
	ds_read_b128 v[242:245], v170 offset:22528
	ds_read_b128 v[246:249], v170 offset:23552
	global_load_lds_dwordx4 v[166:167], off
	s_add_i32 m0, s16, 0x2000
	s_add_u32 s16, s20, 0x40000
	v_lshl_add_u64 v[180:181], s[20:21], 0, v[36:37]
	s_addc_u32 s17, s21, 0
	s_add_i32 s45, s46, s28
	global_load_lds_dwordx4 v[180:181], off
	v_lshl_add_u64 v[202:203], s[16:17], 0, v[34:35]
	s_mov_b32 m0, s45
	v_lshl_add_u64 v[250:251], s[22:23], 0, v[36:37]
	global_load_lds_dwordx4 v[202:203], off
	v_lshl_add_u64 v[202:203], s[16:17], 0, v[36:37]
	s_add_i32 m0, s45, 0x2000
	s_nop 0
	global_load_lds_dwordx4 v[202:203], off
	v_lshl_add_u64 v[202:203], s[22:23], 0, v[34:35]
	s_mov_b32 m0, s29
	s_nop 0
	global_load_lds_dwordx4 v[202:203], off
	s_mov_b32 m0, s30
	s_nop 0
	global_load_lds_dwordx4 v[250:251], off
	s_waitcnt vmcnt(8)
	s_waitcnt lgkmcnt(0)
	s_barrier
; #define PG8_STAGE(bufoff, gbase, voff) do { _Pragma("unroll") for (int _i = 0; _i < 2; ++_i) \
;         __builtin_amdgcn_global_load_lds((const unsigned*)((const char*)(gbase) + (voff)[_i]), (PG8_LAS unsigned*)(lds + (bufoff) + ldsw + _i * 8192), 16, 0, 0); } while (0)
; #define PG8_LDA(dst, b, h) do { _Pragma("unroll") for (int m = 0; m < 4; ++m) _Pragma("unroll") for (int k = 0; k < 2; ++k) dst[m][k] = *(const PG8_LAS bf16x8*)(lds + PG8_SA(b, h) + aoff + m * 2048 + k * 1024); } while (0)
; #define PG8_LDB(dst, b, h) do { _Pragma("unroll") for (int n = 0; n < 2; ++n) _Pragma("unroll") for (int k = 0; k < 2; ++k) dst[n][k] = *(const PG8_LAS bf16x8*)(lds + PG8_SB(b, h) + boff + n * 2048 + k * 1024); } while (0)
; #define PG8_MMA(ai, bj, At, Bt) do { __builtin_amdgcn_s_setprio(1); _Pragma("unroll") for (int m = 0; m < 4; ++m) _Pragma("unroll") for (int n = 0; n < 2; ++n) _Pragma("unroll") for (int k = 0; k < 2; ++k) \
;         acc[ai][bj][m][n] = __builtin_amdgcn_mfma_f32_16x16x32_bf16(Bt[n][k], At[m][k], acc[ai][bj][m][n], 0, 0, 0); __builtin_amdgcn_s_setprio(0); } while (0)
; #define PG8_WAIT_V(n) asm volatile("s_waitcnt vmcnt(" #n ")" ::: "memory")
; #define PG8_WAIT_L(n) asm volatile("s_waitcnt lgkmcnt(" #n ")" ::: "memory")
; #define PG8_BAR __builtin_amdgcn_s_barrier()
; #define PG8_SCHED __builtin_amdgcn_sched_barrier(0)
; template <class Epi, class Sched, bool ALIGN_EPI = false, bool SP2 = false>
; __device__ __forceinline__ void gemm_phase(PG8_LAS unsigned char* lds, const Gemm g, const Sched& S, const Epi& E) {
;     ...
;             PG8_WAIT_V(8); PG8_WAIT_L(0); PG8_BAR; PG8_MMA(1, 0, At, B0); PG8_MMA(1, 1, At, B1); PG8_BAR; PG8_SCHED;
;             PG8_LDB(B0, 1, 0); PG8_LDB(B1, 1, 1); PG8_SCHED; PG8_LDA(At, 1, 0); PG8_STAGE(PG8_SA(0, 1), a2 + hstep, voffA);
;             PG8_WAIT_V(8); PG8_WAIT_L(0); PG8_BAR; PG8_MMA(0, 0, At, B0); PG8_MMA(0, 1, At, B1); PG8_BAR; PG8_SCHED;
	s_waitcnt lgkmcnt(0)
	v_mfma_f32_16x16x32_bf16 v[118:121], v[138:141], v[208:211], v[118:121]
	v_mfma_f32_16x16x32_bf16 v[86:89], v[172:175], v[208:211], v[86:89]
	v_mfma_f32_16x16x32_bf16 v[114:117], v[138:141], v[226:229], v[114:117]
	v_mfma_f32_16x16x32_bf16 v[78:81], v[172:175], v[226:229], v[78:81]
	v_mfma_f32_16x16x32_bf16 v[110:113], v[138:141], v[234:237], v[110:113]
	v_mfma_f32_16x16x32_bf16 v[70:73], v[172:175], v[234:237], v[70:73]
	v_mfma_f32_16x16x32_bf16 v[94:97], v[138:141], v[242:245], v[94:97]
	v_mfma_f32_16x16x32_bf16 v[62:65], v[172:175], v[242:245], v[62:65]
	v_mfma_f32_16x16x32_bf16 v[118:121], v[162:165], v[218:221], v[118:121]
	v_mfma_f32_16x16x32_bf16 v[86:89], v[176:179], v[218:221], v[86:89]
	v_mfma_f32_16x16x32_bf16 v[114:117], v[162:165], v[230:233], v[114:117]
	v_mfma_f32_16x16x32_bf16 v[78:81], v[176:179], v[230:233], v[78:81]
	v_mfma_f32_16x16x32_bf16 v[110:113], v[162:165], v[238:241], v[110:113]
	v_mfma_f32_16x16x32_bf16 v[70:73], v[176:179], v[238:241], v[70:73]
	v_mfma_f32_16x16x32_bf16 v[94:97], v[162:165], v[246:249], v[94:97]
	v_mfma_f32_16x16x32_bf16 v[62:65], v[176:179], v[246:249], v[62:65]
	v_mfma_f32_16x16x32_bf16 v[50:53], v[186:189], v[208:211], v[50:53]
	v_mfma_f32_16x16x32_bf16 v[14:17], v[194:197], v[208:211], v[14:17]
	v_mfma_f32_16x16x32_bf16 v[42:45], v[186:189], v[226:229], v[42:45]
	v_mfma_f32_16x16x32_bf16 v[10:13], v[194:197], v[226:229], v[10:13]
	v_mfma_f32_16x16x32_bf16 v[26:29], v[186:189], v[234:237], v[26:29]
	v_mfma_f32_16x16x32_bf16 v[6:9], v[194:197], v[234:237], v[6:9]
	v_mfma_f32_16x16x32_bf16 v[18:21], v[186:189], v[242:245], v[18:21]
	v_mfma_f32_16x16x32_bf16 v[2:5], v[194:197], v[242:245], v[2:5]
	v_mfma_f32_16x16x32_bf16 v[50:53], v[190:193], v[218:221], v[50:53]
	v_mfma_f32_16x16x32_bf16 v[14:17], v[198:201], v[218:221], v[14:17]
	v_mfma_f32_16x16x32_bf16 v[42:45], v[190:193], v[230:233], v[42:45]
	v_mfma_f32_16x16x32_bf16 v[10:13], v[198:201], v[230:233], v[10:13]
	v_mfma_f32_16x16x32_bf16 v[26:29], v[190:193], v[238:241], v[26:29]
	v_mfma_f32_16x16x32_bf16 v[6:9], v[198:201], v[238:241], v[6:9]
	v_mfma_f32_16x16x32_bf16 v[18:21], v[190:193], v[246:249], v[18:21]
	v_mfma_f32_16x16x32_bf16 v[2:5], v[198:201], v[246:249], v[2:5]
	s_barrier
	s_add_i32 s45, 0, 0x18000
	v_add_u32_e32 v38, s45, v168
	s_add_i32 s46, 0, 0x1c000
	ds_read_b128 v[138:141], v38
	ds_read_b128 v[162:165], v38 offset:1024
	ds_read_b128 v[172:175], v38 offset:2048
	ds_read_b128 v[176:179], v38 offset:3072
	v_add_u32_e32 v38, s46, v168
	ds_read_b128 v[186:189], v38
	ds_read_b128 v[190:193], v38 offset:1024
	ds_read_b128 v[194:197], v38 offset:2048
	ds_read_b128 v[198:201], v38 offset:3072
	s_add_u32 s16, s22, 0x40000
	s_addc_u32 s17, s23, 0
	s_mov_b32 m0, s31
	v_lshl_add_u64 v[212:213], s[16:17], 0, v[34:35]
	ds_read_b128 v[208:211], v170 offset:32768
	ds_read_b128 v[218:221], v170 offset:33792
	ds_read_b128 v[226:229], v170 offset:34816
	ds_read_b128 v[230:233], v170 offset:35840
	ds_read_b128 v[234:237], v170 offset:36864
	ds_read_b128 v[238:241], v170 offset:37888
	ds_read_b128 v[242:245], v170 offset:38912
	ds_read_b128 v[246:249], v170 offset:39936
	global_load_lds_dwordx4 v[212:213], off
	v_lshl_add_u64 v[212:213], s[16:17], 0, v[36:37]
	s_mov_b32 m0, s34
	s_nop 0
	global_load_lds_dwordx4 v[212:213], off
	s_waitcnt vmcnt(8)
	s_waitcnt lgkmcnt(0)
	s_barrier
	s_waitcnt lgkmcnt(0)
	v_mfma_f32_16x16x32_bf16 v[134:137], v[138:141], v[208:211], v[134:137]
	v_mfma_f32_16x16x32_bf16 v[106:109], v[172:175], v[208:211], v[106:109]
	v_mfma_f32_16x16x32_bf16 v[130:133], v[138:141], v[226:229], v[130:133]
	v_mfma_f32_16x16x32_bf16 v[102:105], v[172:175], v[226:229], v[102:105]
	v_mfma_f32_16x16x32_bf16 v[126:129], v[138:141], v[234:237], v[126:129]
	v_mfma_f32_16x16x32_bf16 v[98:101], v[172:175], v[234:237], v[98:101]
	v_mfma_f32_16x16x32_bf16 v[122:125], v[138:141], v[242:245], v[122:125]
	v_mfma_f32_16x16x32_bf16 v[90:93], v[172:175], v[242:245], v[90:93]
	v_mfma_f32_16x16x32_bf16 v[134:137], v[162:165], v[218:221], v[134:137]
	v_mfma_f32_16x16x32_bf16 v[106:109], v[176:179], v[218:221], v[106:109]
	v_mfma_f32_16x16x32_bf16 v[130:133], v[162:165], v[230:233], v[130:133]
	v_mfma_f32_16x16x32_bf16 v[102:105], v[176:179], v[230:233], v[102:105]
	v_mfma_f32_16x16x32_bf16 v[126:129], v[162:165], v[238:241], v[126:129]
	v_mfma_f32_16x16x32_bf16 v[98:101], v[176:179], v[238:241], v[98:101]
	v_mfma_f32_16x16x32_bf16 v[122:125], v[162:165], v[246:249], v[122:125]
	v_mfma_f32_16x16x32_bf16 v[90:93], v[176:179], v[246:249], v[90:93]
	v_mfma_f32_16x16x32_bf16 v[82:85], v[186:189], v[208:211], v[82:85]
	v_mfma_f32_16x16x32_bf16 v[54:57], v[194:197], v[208:211], v[54:57]
	v_mfma_f32_16x16x32_bf16 v[74:77], v[186:189], v[226:229], v[74:77]
	v_mfma_f32_16x16x32_bf16 v[46:49], v[194:197], v[226:229], v[46:49]
	v_mfma_f32_16x16x32_bf16 v[66:69], v[186:189], v[234:237], v[66:69]
	v_mfma_f32_16x16x32_bf16 v[30:33], v[194:197], v[234:237], v[30:33]
	v_mfma_f32_16x16x32_bf16 v[58:61], v[186:189], v[242:245], v[58:61]
	v_mfma_f32_16x16x32_bf16 v[22:25], v[194:197], v[242:245], v[22:25]
	v_mfma_f32_16x16x32_bf16 v[82:85], v[190:193], v[218:221], v[82:85]
	v_mfma_f32_16x16x32_bf16 v[54:57], v[198:201], v[218:221], v[54:57]
	v_mfma_f32_16x16x32_bf16 v[74:77], v[190:193], v[230:233], v[74:77]
	v_mfma_f32_16x16x32_bf16 v[46:49], v[198:201], v[230:233], v[46:49]
	v_mfma_f32_16x16x32_bf16 v[66:69], v[190:193], v[238:241], v[66:69]
	v_mfma_f32_16x16x32_bf16 v[30:33], v[198:201], v[238:241], v[30:33]
	v_mfma_f32_16x16x32_bf16 v[58:61], v[190:193], v[246:249], v[58:61]
	v_mfma_f32_16x16x32_bf16 v[22:25], v[198:201], v[246:249], v[22:25]
	s_barrier
; #define PG8_STAGE(bufoff, gbase, voff) do { _Pragma("unroll") for (int _i = 0; _i < 2; ++_i) \
;         __builtin_amdgcn_global_load_lds((const unsigned*)((const char*)(gbase) + (voff)[_i]), (PG8_LAS unsigned*)(lds + (bufoff) + ldsw + _i * 8192), 16, 0, 0); } while (0)
; #define PG8_LDA(dst, b, h) do { _Pragma("unroll") for (int m = 0; m < 4; ++m) _Pragma("unroll") for (int k = 0; k < 2; ++k) dst[m][k] = *(const PG8_LAS bf16x8*)(lds + PG8_SA(b, h) + aoff + m * 2048 + k * 1024); } while (0)
; #define PG8_MMA(ai, bj, At, Bt) do { __builtin_amdgcn_s_setprio(1); _Pragma("unroll") for (int m = 0; m < 4; ++m) _Pragma("unroll") for (int n = 0; n < 2; ++n) _Pragma("unroll") for (int k = 0; k < 2; ++k) \
;         acc[ai][bj][m][n] = __builtin_amdgcn_mfma_f32_16x16x32_bf16(Bt[n][k], At[m][k], acc[ai][bj][m][n], 0, 0, 0); __builtin_amdgcn_s_setprio(0); } while (0)
; #define PG8_WAIT_V(n) asm volatile("s_waitcnt vmcnt(" #n ")" ::: "memory")
; #define PG8_WAIT_L(n) asm volatile("s_waitcnt lgkmcnt(" #n ")" ::: "memory")
; #define PG8_BAR __builtin_amdgcn_s_barrier()
; #define PG8_SCHED __builtin_amdgcn_sched_barrier(0)
; template <class Epi, class Sched, bool ALIGN_EPI = false, bool SP2 = false>
; __device__ __forceinline__ void gemm_phase(PG8_LAS unsigned char* lds, const Gemm g, const Sched& S, const Epi& E) {
;     ...
;             PG8_LDA(At, 1, 1); PG8_STAGE(PG8_SB(1, 0), b3, voffB); PG8_STAGE(PG8_SB(1, 1), b3 + hstep, voffB); PG8_STAGE(PG8_SA(1, 0), a3, voffA);
;             PG8_WAIT_V(8); PG8_WAIT_L(0); PG8_BAR; PG8_MMA(1, 0, At, B0); PG8_MMA(1, 1, At, B1); PG8_BAR; PG8_SCHED;
	s_add_i32 s16, s45, s28
	v_lshl_add_u64 v[166:167], v[166:167], 0, s[70:71]
	s_mov_b32 m0, s16
	ds_read_b128 v[208:211], v170 offset:49152
	ds_read_b128 v[218:221], v170 offset:50176
	ds_read_b128 v[226:229], v170 offset:51200
	ds_read_b128 v[230:233], v170 offset:52224
	ds_read_b128 v[234:237], v170 offset:53248
	ds_read_b128 v[238:241], v170 offset:54272
	ds_read_b128 v[242:245], v170 offset:55296
	ds_read_b128 v[246:249], v170 offset:56320
	global_load_lds_dwordx4 v[166:167], off
	s_add_i32 m0, s16, 0x2000
	s_add_u32 s16, s20, 0x40080
	v_lshl_add_u64 v[166:167], v[180:181], 0, s[70:71]
	s_addc_u32 s17, s21, 0
	s_add_i32 s20, s46, s28
	global_load_lds_dwordx4 v[166:167], off
	v_lshl_add_u64 v[166:167], s[16:17], 0, v[34:35]
	s_mov_b32 m0, s20
	s_nop 0
	global_load_lds_dwordx4 v[166:167], off
	v_lshl_add_u64 v[166:167], s[16:17], 0, v[36:37]
	s_add_i32 m0, s20, 0x2000
	s_nop 0
	global_load_lds_dwordx4 v[166:167], off
	v_lshl_add_u64 v[166:167], v[202:203], 0, s[70:71]
	s_mov_b32 m0, s37
	s_nop 0
	global_load_lds_dwordx4 v[166:167], off
	v_lshl_add_u64 v[166:167], v[250:251], 0, s[70:71]
	s_mov_b32 m0, s38
	s_nop 0
	global_load_lds_dwordx4 v[166:167], off
	s_waitcnt vmcnt(8)
	s_waitcnt lgkmcnt(0)
	s_barrier
	s_waitcnt lgkmcnt(0)
	v_mfma_f32_16x16x32_bf16 v[118:121], v[138:141], v[208:211], v[118:121]
	v_mfma_f32_16x16x32_bf16 v[86:89], v[172:175], v[208:211], v[86:89]
	v_mfma_f32_16x16x32_bf16 v[114:117], v[138:141], v[226:229], v[114:117]
	v_mfma_f32_16x16x32_bf16 v[78:81], v[172:175], v[226:229], v[78:81]
	v_mfma_f32_16x16x32_bf16 v[110:113], v[138:141], v[234:237], v[110:113]
	v_mfma_f32_16x16x32_bf16 v[70:73], v[172:175], v[234:237], v[70:73]
	v_mfma_f32_16x16x32_bf16 v[94:97], v[138:141], v[242:245], v[94:97]
	v_mfma_f32_16x16x32_bf16 v[62:65], v[172:175], v[242:245], v[62:65]
	v_mfma_f32_16x16x32_bf16 v[118:121], v[162:165], v[218:221], v[118:121]
	v_mfma_f32_16x16x32_bf16 v[86:89], v[176:179], v[218:221], v[86:89]
	v_mfma_f32_16x16x32_bf16 v[114:117], v[162:165], v[230:233], v[114:117]
	v_mfma_f32_16x16x32_bf16 v[78:81], v[176:179], v[230:233], v[78:81]
	v_mfma_f32_16x16x32_bf16 v[110:113], v[162:165], v[238:241], v[110:113]
	v_mfma_f32_16x16x32_bf16 v[70:73], v[176:179], v[238:241], v[70:73]
	v_mfma_f32_16x16x32_bf16 v[94:97], v[162:165], v[246:249], v[94:97]
	v_mfma_f32_16x16x32_bf16 v[62:65], v[176:179], v[246:249], v[62:65]
	v_mfma_f32_16x16x32_bf16 v[50:53], v[186:189], v[208:211], v[50:53]
	v_mfma_f32_16x16x32_bf16 v[14:17], v[194:197], v[208:211], v[14:17]
	v_mfma_f32_16x16x32_bf16 v[42:45], v[186:189], v[226:229], v[42:45]
	v_mfma_f32_16x16x32_bf16 v[10:13], v[194:197], v[226:229], v[10:13]
	v_mfma_f32_16x16x32_bf16 v[26:29], v[186:189], v[234:237], v[26:29]
	v_mfma_f32_16x16x32_bf16 v[6:9], v[194:197], v[234:237], v[6:9]
	v_mfma_f32_16x16x32_bf16 v[18:21], v[186:189], v[242:245], v[18:21]
	v_mfma_f32_16x16x32_bf16 v[2:5], v[194:197], v[242:245], v[2:5]
	v_mfma_f32_16x16x32_bf16 v[50:53], v[190:193], v[218:221], v[50:53]
	v_mfma_f32_16x16x32_bf16 v[14:17], v[198:201], v[218:221], v[14:17]
	v_mfma_f32_16x16x32_bf16 v[42:45], v[190:193], v[230:233], v[42:45]
	v_mfma_f32_16x16x32_bf16 v[10:13], v[198:201], v[230:233], v[10:13]
	v_mfma_f32_16x16x32_bf16 v[26:29], v[190:193], v[238:241], v[26:29]
	v_mfma_f32_16x16x32_bf16 v[6:9], v[198:201], v[238:241], v[6:9]
	v_mfma_f32_16x16x32_bf16 v[18:21], v[190:193], v[246:249], v[18:21]
	v_mfma_f32_16x16x32_bf16 v[2:5], v[198:201], v[246:249], v[2:5]
	s_barrier
	s_add_i32 s44, s44, 2
	s_add_u32 s42, s42, 0x100
	s_addc_u32 s43, s43, 0
	s_cmp_gt_u32 s44, 13
	s_mov_b64 s[16:17], s[18:19]
	s_cbranch_scc0 .LBB0_542
	s_and_b64 vcc, exec, s[2:3]
	s_cbranch_vccz .LBB0_545
	s_barrier

; #define PG8_STAGE(bufoff, gbase, voff) do { _Pragma("unroll") for (int _i = 0; _i < 2; ++_i) \
;         __builtin_amdgcn_global_load_lds((const unsigned*)((const char*)(gbase) + (voff)[_i]), (PG8_LAS unsigned*)(lds + (bufoff) + ldsw + _i * 8192), 16, 0, 0); } while (0)
; #define PG8_LDA(dst, b, h) do { _Pragma("unroll") for (int m = 0; m < 4; ++m) _Pragma("unroll") for (int k = 0; k < 2; ++k) dst[m][k] = *(const PG8_LAS bf16x8*)(lds + PG8_SA(b, h) + aoff + m * 2048 + k * 1024); } while (0)
; #define PG8_LDB(dst, b, h) do { _Pragma("unroll") for (int n = 0; n < 2; ++n) _Pragma("unroll") for (int k = 0; k < 2; ++k) dst[n][k] = *(const PG8_LAS bf16x8*)(lds + PG8_SB(b, h) + boff + n * 2048 + k * 1024); } while (0)
; #define PG8_MMA(ai, bj, At, Bt) do { __builtin_amdgcn_s_setprio(1); _Pragma("unroll") for (int m = 0; m < 4; ++m) _Pragma("unroll") for (int n = 0; n < 2; ++n) _Pragma("unroll") for (int k = 0; k < 2; ++k) \
;         acc[ai][bj][m][n] = __builtin_amdgcn_mfma_f32_16x16x32_bf16(Bt[n][k], At[m][k], acc[ai][bj][m][n], 0, 0, 0); __builtin_amdgcn_s_setprio(0); } while (0)
; #define PG8_WAIT_V(n) asm volatile("s_waitcnt vmcnt(" #n ")" ::: "memory")
; #define PG8_WAIT_L(n) asm volatile("s_waitcnt lgkmcnt(" #n ")" ::: "memory")
; template <class Epi, class Sched, bool ALIGN_EPI = false, bool SP2 = false>
; __device__ __forceinline__ void gemm_phase(PG8_LAS unsigned char* lds, const Gemm g, const Sched& S, const Epi& E) {
;     ...
;             const bool last = (t == nt - 2);
;             const char* a1 = cA + (size_t)(t + 1) * kstep;
;             const char* a2 = last ? nA : cA + (size_t)(t + 2) * kstep; const char* b2 = last ? nB : cB + (size_t)(t + 2) * kstep;
;             const char* a3 = a2 + kstep; const char* b3 = b2 + kstep;
;             if (last && has_next) S.a_ready(nxt);
;             if constexpr (SP2) {
;             PG8_LDB(B0, 0, 0); PG8_LDB(B1, 0, 1); PG8_SCHED; PG8_LDA(At, 0, 0); PG8_STAGE(PG8_SA(1, 1), a1 + hstep, voffA);
;             PG8_WAIT_V(8); PG8_WAIT_L(0); PG8_BAR; PG8_MMA(0, 0, At, B0); PG8_MMA(0, 1, At, B1); PG8_BAR; PG8_SCHED;
;             PG8_LDA(At, 0, 1); PG8_STAGE(PG8_SB(0, 0), b2, voffB); PG8_STAGE(PG8_SB(0, 1), b2 + hstep, voffB); PG8_STAGE(PG8_SA(0, 0), a2, voffA);
;             PG8_WAIT_V(8); PG8_WAIT_L(0); PG8_BAR; PG8_MMA(1, 0, At, B0); PG8_MMA(1, 1, At, B1); PG8_BAR; PG8_SCHED;
.LBB0_557:
	s_add_i32 s5, s4, 0x100
	s_and_b64 s[2:3], s[2:3], exec
	s_cselect_b32 s3, 0, s5
	s_cselect_b32 s2, 0, 0
	s_add_u32 s6, s62, s3
	s_addc_u32 s7, s63, s2
	s_add_i32 s31, 0, 0x10000
	s_add_u32 s8, s60, s3
	s_addc_u32 s9, s61, s2
	s_add_i32 s3, 0, 0x14000
	s_add_u32 s12, s64, s4
	s_addc_u32 s13, s65, 0
	s_add_i32 s30, s31, s15
	s_add_i32 m0, s16, 0xc000
	s_add_i32 s35, s16, 0xe000
	s_add_i32 s27, s30, 0x2000
	v_add_u32_e32 v38, s31, v139
	s_add_u32 s10, s8, 0x40000
	ds_read_b128 v[144:147], v38
	ds_read_b128 v[148:151], v38 offset:1024
	ds_read_b128 v[152:155], v38 offset:2048
	ds_read_b128 v[156:159], v38 offset:3072
	v_add_u32_e32 v38, s3, v139
	s_addc_u32 s11, s9, 0
	s_add_i32 s29, s3, s15
	ds_read_b128 v[160:163], v38
	ds_read_b128 v[164:167], v38 offset:1024
	ds_read_b128 v[168:171], v38 offset:2048
	ds_read_b128 v[172:175], v38 offset:3072
	s_add_i32 s28, s29, 0x2000
	s_add_i32 s26, 0, 0x18000
	s_add_i32 s25, 0, 0x1c000
	s_add_u32 s4, s6, 0x40000
	s_addc_u32 s5, s7, 0
	s_add_i32 s24, s26, s15
	s_add_i32 s23, s24, 0x2000
	s_add_u32 s2, s8, 0x40080
	s_addc_u32 s3, s9, 0
	s_add_i32 s34, s25, s15
	s_add_i32 s31, s34, 0x2000
	v_lshl_add_u64 v[180:181], s[12:13], 0, v[34:35]
	v_lshl_add_u64 v[180:181], v[180:181], 0, s[70:71]
	ds_read_b128 v[176:179], v140
	ds_read_b128 v[186:189], v140 offset:1024
	ds_read_b128 v[190:193], v140 offset:2048
	ds_read_b128 v[194:197], v140 offset:3072
	ds_read_b128 v[198:201], v140 offset:4096
	ds_read_b128 v[208:211], v140 offset:5120
	ds_read_b128 v[218:221], v140 offset:6144
	ds_read_b128 v[226:229], v140 offset:7168
	global_load_lds_dwordx4 v[180:181], off
	v_lshl_add_u64 v[180:181], s[12:13], 0, v[36:37]
	v_lshl_add_u64 v[180:181], v[180:181], 0, s[70:71]
	s_mov_b32 m0, s35
	s_nop 0
	global_load_lds_dwordx4 v[180:181], off
	s_waitcnt vmcnt(8)
	s_waitcnt lgkmcnt(0)
	s_barrier
	s_waitcnt lgkmcnt(0)
	v_mfma_f32_16x16x32_bf16 v[134:137], v[144:147], v[176:179], v[134:137]
	v_mfma_f32_16x16x32_bf16 v[102:105], v[152:155], v[176:179], v[102:105]
	v_mfma_f32_16x16x32_bf16 v[130:133], v[144:147], v[190:193], v[130:133]
	v_mfma_f32_16x16x32_bf16 v[98:101], v[152:155], v[190:193], v[98:101]
	v_mfma_f32_16x16x32_bf16 v[126:129], v[144:147], v[198:201], v[126:129]
	v_mfma_f32_16x16x32_bf16 v[94:97], v[152:155], v[198:201], v[94:97]
	v_mfma_f32_16x16x32_bf16 v[122:125], v[144:147], v[218:221], v[122:125]
	v_mfma_f32_16x16x32_bf16 v[90:93], v[152:155], v[218:221], v[90:93]
	v_mfma_f32_16x16x32_bf16 v[134:137], v[148:151], v[186:189], v[134:137]
	v_mfma_f32_16x16x32_bf16 v[102:105], v[156:159], v[186:189], v[102:105]
	v_mfma_f32_16x16x32_bf16 v[130:133], v[148:151], v[194:197], v[130:133]
	v_mfma_f32_16x16x32_bf16 v[98:101], v[156:159], v[194:197], v[98:101]
	v_mfma_f32_16x16x32_bf16 v[126:129], v[148:151], v[208:211], v[126:129]
	v_mfma_f32_16x16x32_bf16 v[94:97], v[156:159], v[208:211], v[94:97]
	v_mfma_f32_16x16x32_bf16 v[122:125], v[148:151], v[226:229], v[122:125]
	v_mfma_f32_16x16x32_bf16 v[90:93], v[156:159], v[226:229], v[90:93]
	v_mfma_f32_16x16x32_bf16 v[70:73], v[160:163], v[176:179], v[70:73]
	v_mfma_f32_16x16x32_bf16 v[30:33], v[168:171], v[176:179], v[30:33]
	v_mfma_f32_16x16x32_bf16 v[66:69], v[160:163], v[190:193], v[66:69]
	v_mfma_f32_16x16x32_bf16 v[26:29], v[168:171], v[190:193], v[26:29]
	v_mfma_f32_16x16x32_bf16 v[62:65], v[160:163], v[198:201], v[62:65]
	v_mfma_f32_16x16x32_bf16 v[22:25], v[168:171], v[198:201], v[22:25]
	v_mfma_f32_16x16x32_bf16 v[58:61], v[160:163], v[218:221], v[58:61]
	v_mfma_f32_16x16x32_bf16 v[18:21], v[168:171], v[218:221], v[18:21]
	v_mfma_f32_16x16x32_bf16 v[70:73], v[164:167], v[186:189], v[70:73]
	v_mfma_f32_16x16x32_bf16 v[30:33], v[172:175], v[186:189], v[30:33]
	v_mfma_f32_16x16x32_bf16 v[66:69], v[164:167], v[194:197], v[66:69]
	v_mfma_f32_16x16x32_bf16 v[26:29], v[172:175], v[194:197], v[26:29]
	v_mfma_f32_16x16x32_bf16 v[62:65], v[164:167], v[208:211], v[62:65]
	v_mfma_f32_16x16x32_bf16 v[22:25], v[172:175], v[208:211], v[22:25]
	v_mfma_f32_16x16x32_bf16 v[58:61], v[164:167], v[226:229], v[58:61]
	v_mfma_f32_16x16x32_bf16 v[18:21], v[172:175], v[226:229], v[18:21]
	s_barrier
	s_mov_b32 m0, s30
	v_lshl_add_u64 v[180:181], s[8:9], 0, v[34:35]
	ds_read_b128 v[176:179], v140 offset:16384
	ds_read_b128 v[186:189], v140 offset:17408
	ds_read_b128 v[190:193], v140 offset:18432
	ds_read_b128 v[194:197], v140 offset:19456
	ds_read_b128 v[198:201], v140 offset:20480
	ds_read_b128 v[208:211], v140 offset:21504
	ds_read_b128 v[218:221], v140 offset:22528
	ds_read_b128 v[226:229], v140 offset:23552
	global_load_lds_dwordx4 v[180:181], off
	v_lshl_add_u64 v[202:203], s[8:9], 0, v[36:37]
	s_mov_b32 m0, s27
	v_lshl_add_u64 v[212:213], s[10:11], 0, v[34:35]
	global_load_lds_dwordx4 v[202:203], off
	s_mov_b32 m0, s29
	v_lshl_add_u64 v[230:231], s[6:7], 0, v[36:37]
	global_load_lds_dwordx4 v[212:213], off
	v_lshl_add_u64 v[212:213], s[10:11], 0, v[36:37]
	s_mov_b32 m0, s28
	s_nop 0
	global_load_lds_dwordx4 v[212:213], off
	v_lshl_add_u64 v[212:213], s[6:7], 0, v[34:35]
	s_mov_b32 m0, s16
	s_nop 0
	global_load_lds_dwordx4 v[212:213], off
	s_mov_b32 m0, s17
	s_nop 0
	global_load_lds_dwordx4 v[230:231], off
	s_waitcnt vmcnt(8)
	s_waitcnt lgkmcnt(0)
	s_barrier
; #define PG8_STAGE(bufoff, gbase, voff) do { _Pragma("unroll") for (int _i = 0; _i < 2; ++_i) \
;         __builtin_amdgcn_global_load_lds((const unsigned*)((const char*)(gbase) + (voff)[_i]), (PG8_LAS unsigned*)(lds + (bufoff) + ldsw + _i * 8192), 16, 0, 0); } while (0)
; #define PG8_LDA(dst, b, h) do { _Pragma("unroll") for (int m = 0; m < 4; ++m) _Pragma("unroll") for (int k = 0; k < 2; ++k) dst[m][k] = *(const PG8_LAS bf16x8*)(lds + PG8_SA(b, h) + aoff + m * 2048 + k * 1024); } while (0)
; #define PG8_LDB(dst, b, h) do { _Pragma("unroll") for (int n = 0; n < 2; ++n) _Pragma("unroll") for (int k = 0; k < 2; ++k) dst[n][k] = *(const PG8_LAS bf16x8*)(lds + PG8_SB(b, h) + boff + n * 2048 + k * 1024); } while (0)
; #define PG8_MMA(ai, bj, At, Bt) do { __builtin_amdgcn_s_setprio(1); _Pragma("unroll") for (int m = 0; m < 4; ++m) _Pragma("unroll") for (int n = 0; n < 2; ++n) _Pragma("unroll") for (int k = 0; k < 2; ++k) \
;         acc[ai][bj][m][n] = __builtin_amdgcn_mfma_f32_16x16x32_bf16(Bt[n][k], At[m][k], acc[ai][bj][m][n], 0, 0, 0); __builtin_amdgcn_s_setprio(0); } while (0)
; #define PG8_WAIT_V(n) asm volatile("s_waitcnt vmcnt(" #n ")" ::: "memory")
; #define PG8_WAIT_L(n) asm volatile("s_waitcnt lgkmcnt(" #n ")" ::: "memory")
; #define PG8_BAR __builtin_amdgcn_s_barrier()
; #define PG8_SCHED __builtin_amdgcn_sched_barrier(0)
; template <class Epi, class Sched, bool ALIGN_EPI = false, bool SP2 = false>
; __device__ __forceinline__ void gemm_phase(PG8_LAS unsigned char* lds, const Gemm g, const Sched& S, const Epi& E) {
;     ...
;             PG8_WAIT_V(8); PG8_WAIT_L(0); PG8_BAR; PG8_MMA(1, 0, At, B0); PG8_MMA(1, 1, At, B1); PG8_BAR; PG8_SCHED;
;             PG8_LDB(B0, 1, 0); PG8_LDB(B1, 1, 1); PG8_SCHED; PG8_LDA(At, 1, 0); PG8_STAGE(PG8_SA(0, 1), a2 + hstep, voffA);
;             PG8_WAIT_V(8); PG8_WAIT_L(0); PG8_BAR; PG8_MMA(0, 0, At, B0); PG8_MMA(0, 1, At, B1); PG8_BAR; PG8_SCHED;
	s_waitcnt lgkmcnt(0)
	v_mfma_f32_16x16x32_bf16 v[118:121], v[144:147], v[176:179], v[118:121]
	v_mfma_f32_16x16x32_bf16 v[86:89], v[152:155], v[176:179], v[86:89]
	v_mfma_f32_16x16x32_bf16 v[114:117], v[144:147], v[190:193], v[114:117]
	v_mfma_f32_16x16x32_bf16 v[82:85], v[152:155], v[190:193], v[82:85]
	v_mfma_f32_16x16x32_bf16 v[110:113], v[144:147], v[198:201], v[110:113]
	v_mfma_f32_16x16x32_bf16 v[78:81], v[152:155], v[198:201], v[78:81]
	v_mfma_f32_16x16x32_bf16 v[106:109], v[144:147], v[218:221], v[106:109]
	v_mfma_f32_16x16x32_bf16 v[74:77], v[152:155], v[218:221], v[74:77]
	v_mfma_f32_16x16x32_bf16 v[118:121], v[148:151], v[186:189], v[118:121]
	v_mfma_f32_16x16x32_bf16 v[86:89], v[156:159], v[186:189], v[86:89]
	v_mfma_f32_16x16x32_bf16 v[114:117], v[148:151], v[194:197], v[114:117]
	v_mfma_f32_16x16x32_bf16 v[82:85], v[156:159], v[194:197], v[82:85]
	v_mfma_f32_16x16x32_bf16 v[110:113], v[148:151], v[208:211], v[110:113]
	v_mfma_f32_16x16x32_bf16 v[78:81], v[156:159], v[208:211], v[78:81]
	v_mfma_f32_16x16x32_bf16 v[106:109], v[148:151], v[226:229], v[106:109]
	v_mfma_f32_16x16x32_bf16 v[74:77], v[156:159], v[226:229], v[74:77]
	v_mfma_f32_16x16x32_bf16 v[54:57], v[160:163], v[176:179], v[54:57]
	v_mfma_f32_16x16x32_bf16 v[14:17], v[168:171], v[176:179], v[14:17]
	v_mfma_f32_16x16x32_bf16 v[50:53], v[160:163], v[190:193], v[50:53]
	v_mfma_f32_16x16x32_bf16 v[10:13], v[168:171], v[190:193], v[10:13]
	v_mfma_f32_16x16x32_bf16 v[46:49], v[160:163], v[198:201], v[46:49]
	v_mfma_f32_16x16x32_bf16 v[6:9], v[168:171], v[198:201], v[6:9]
	v_mfma_f32_16x16x32_bf16 v[42:45], v[160:163], v[218:221], v[42:45]
	v_mfma_f32_16x16x32_bf16 v[2:5], v[168:171], v[218:221], v[2:5]
	v_mfma_f32_16x16x32_bf16 v[54:57], v[164:167], v[186:189], v[54:57]
	v_mfma_f32_16x16x32_bf16 v[14:17], v[172:175], v[186:189], v[14:17]
	v_mfma_f32_16x16x32_bf16 v[50:53], v[164:167], v[194:197], v[50:53]
	v_mfma_f32_16x16x32_bf16 v[10:13], v[172:175], v[194:197], v[10:13]
	v_mfma_f32_16x16x32_bf16 v[46:49], v[164:167], v[208:211], v[46:49]
	v_mfma_f32_16x16x32_bf16 v[6:9], v[172:175], v[208:211], v[6:9]
	v_mfma_f32_16x16x32_bf16 v[42:45], v[164:167], v[226:229], v[42:45]
	v_mfma_f32_16x16x32_bf16 v[2:5], v[172:175], v[226:229], v[2:5]
	s_barrier
	v_add_u32_e32 v38, s26, v139
	ds_read_b128 v[144:147], v38
	ds_read_b128 v[148:151], v38 offset:1024
	ds_read_b128 v[152:155], v38 offset:2048
	ds_read_b128 v[156:159], v38 offset:3072
	v_add_u32_e32 v38, s25, v139
	ds_read_b128 v[160:163], v38
	ds_read_b128 v[164:167], v38 offset:1024
	ds_read_b128 v[168:171], v38 offset:2048
	ds_read_b128 v[172:175], v38 offset:3072
	s_mov_b32 m0, s18
	v_lshl_add_u64 v[232:233], s[4:5], 0, v[34:35]
	ds_read_b128 v[176:179], v140 offset:32768
	ds_read_b128 v[186:189], v140 offset:33792
	ds_read_b128 v[190:193], v140 offset:34816
	ds_read_b128 v[194:197], v140 offset:35840
	ds_read_b128 v[198:201], v140 offset:36864
	ds_read_b128 v[208:211], v140 offset:37888
	ds_read_b128 v[218:221], v140 offset:38912
	ds_read_b128 v[226:229], v140 offset:39936
	global_load_lds_dwordx4 v[232:233], off
	v_lshl_add_u64 v[232:233], s[4:5], 0, v[36:37]
	s_mov_b32 m0, s19
	s_nop 0
	global_load_lds_dwordx4 v[232:233], off
	s_waitcnt vmcnt(8)
	s_waitcnt lgkmcnt(0)
	s_barrier
	s_waitcnt lgkmcnt(0)
	v_mfma_f32_16x16x32_bf16 v[134:137], v[144:147], v[176:179], v[134:137]
	v_mfma_f32_16x16x32_bf16 v[102:105], v[152:155], v[176:179], v[102:105]
	v_mfma_f32_16x16x32_bf16 v[130:133], v[144:147], v[190:193], v[130:133]
	v_mfma_f32_16x16x32_bf16 v[98:101], v[152:155], v[190:193], v[98:101]
	v_mfma_f32_16x16x32_bf16 v[126:129], v[144:147], v[198:201], v[126:129]
	v_mfma_f32_16x16x32_bf16 v[94:97], v[152:155], v[198:201], v[94:97]
	v_mfma_f32_16x16x32_bf16 v[122:125], v[144:147], v[218:221], v[122:125]
	v_mfma_f32_16x16x32_bf16 v[90:93], v[152:155], v[218:221], v[90:93]
	v_mfma_f32_16x16x32_bf16 v[134:137], v[148:151], v[186:189], v[134:137]
	v_mfma_f32_16x16x32_bf16 v[102:105], v[156:159], v[186:189], v[102:105]
	v_mfma_f32_16x16x32_bf16 v[130:133], v[148:151], v[194:197], v[130:133]
	v_mfma_f32_16x16x32_bf16 v[98:101], v[156:159], v[194:197], v[98:101]
	v_mfma_f32_16x16x32_bf16 v[126:129], v[148:151], v[208:211], v[126:129]
	v_mfma_f32_16x16x32_bf16 v[94:97], v[156:159], v[208:211], v[94:97]
	v_mfma_f32_16x16x32_bf16 v[122:125], v[148:151], v[226:229], v[122:125]
	v_mfma_f32_16x16x32_bf16 v[90:93], v[156:159], v[226:229], v[90:93]
	v_mfma_f32_16x16x32_bf16 v[70:73], v[160:163], v[176:179], v[70:73]
	v_mfma_f32_16x16x32_bf16 v[30:33], v[168:171], v[176:179], v[30:33]
	v_mfma_f32_16x16x32_bf16 v[66:69], v[160:163], v[190:193], v[66:69]
	v_mfma_f32_16x16x32_bf16 v[26:29], v[168:171], v[190:193], v[26:29]
	v_mfma_f32_16x16x32_bf16 v[62:65], v[160:163], v[198:201], v[62:65]
	v_mfma_f32_16x16x32_bf16 v[22:25], v[168:171], v[198:201], v[22:25]
	v_mfma_f32_16x16x32_bf16 v[58:61], v[160:163], v[218:221], v[58:61]
	v_mfma_f32_16x16x32_bf16 v[18:21], v[168:171], v[218:221], v[18:21]
	v_mfma_f32_16x16x32_bf16 v[70:73], v[164:167], v[186:189], v[70:73]
	v_mfma_f32_16x16x32_bf16 v[30:33], v[172:175], v[186:189], v[30:33]
	v_mfma_f32_16x16x32_bf16 v[66:69], v[164:167], v[194:197], v[66:69]
	v_mfma_f32_16x16x32_bf16 v[26:29], v[172:175], v[194:197], v[26:29]
	v_mfma_f32_16x16x32_bf16 v[62:65], v[164:167], v[208:211], v[62:65]
	v_mfma_f32_16x16x32_bf16 v[22:25], v[172:175], v[208:211], v[22:25]
	v_mfma_f32_16x16x32_bf16 v[58:61], v[164:167], v[226:229], v[58:61]
	v_mfma_f32_16x16x32_bf16 v[18:21], v[172:175], v[226:229], v[18:21]
	s_barrier
; #define PG8_STAGE(bufoff, gbase, voff) do { _Pragma("unroll") for (int _i = 0; _i < 2; ++_i) \
;         __builtin_amdgcn_global_load_lds((const unsigned*)((const char*)(gbase) + (voff)[_i]), (PG8_LAS unsigned*)(lds + (bufoff) + ldsw + _i * 8192), 16, 0, 0); } while (0)
; #define PG8_LDA(dst, b, h) do { _Pragma("unroll") for (int m = 0; m < 4; ++m) _Pragma("unroll") for (int k = 0; k < 2; ++k) dst[m][k] = *(const PG8_LAS bf16x8*)(lds + PG8_SA(b, h) + aoff + m * 2048 + k * 1024); } while (0)
; #define PG8_MMA(ai, bj, At, Bt) do { __builtin_amdgcn_s_setprio(1); _Pragma("unroll") for (int m = 0; m < 4; ++m) _Pragma("unroll") for (int n = 0; n < 2; ++n) _Pragma("unroll") for (int k = 0; k < 2; ++k) \
;         acc[ai][bj][m][n] = __builtin_amdgcn_mfma_f32_16x16x32_bf16(Bt[n][k], At[m][k], acc[ai][bj][m][n], 0, 0, 0); __builtin_amdgcn_s_setprio(0); } while (0)
; #define PG8_WAIT_V(n) asm volatile("s_waitcnt vmcnt(" #n ")" ::: "memory")
; #define PG8_WAIT_L(n) asm volatile("s_waitcnt lgkmcnt(" #n ")" ::: "memory")
; #define PG8_BAR __builtin_amdgcn_s_barrier()
; #define PG8_SCHED __builtin_amdgcn_sched_barrier(0)
; template <class Epi, class Sched, bool ALIGN_EPI = false, bool SP2 = false>
; __device__ __forceinline__ void gemm_phase(PG8_LAS unsigned char* lds, const Gemm g, const Sched& S, const Epi& E) {
;     ...
;             PG8_LDA(At, 1, 1); PG8_STAGE(PG8_SB(1, 0), b3, voffB); PG8_STAGE(PG8_SB(1, 1), b3 + hstep, voffB); PG8_STAGE(PG8_SA(1, 0), a3, voffA);
;             PG8_WAIT_V(8); PG8_WAIT_L(0); PG8_BAR; PG8_MMA(1, 0, At, B0); PG8_MMA(1, 1, At, B1); PG8_BAR; PG8_SCHED;
	s_mov_b32 m0, s24
	v_lshl_add_u64 v[180:181], v[180:181], 0, s[70:71]
	ds_read_b128 v[176:179], v140 offset:49152
	ds_read_b128 v[186:189], v140 offset:50176
	ds_read_b128 v[190:193], v140 offset:51200
	ds_read_b128 v[194:197], v140 offset:52224
	ds_read_b128 v[198:201], v140 offset:53248
	ds_read_b128 v[208:211], v140 offset:54272
	ds_read_b128 v[218:221], v140 offset:55296
	ds_read_b128 v[226:229], v140 offset:56320
	global_load_lds_dwordx4 v[180:181], off
	v_lshl_add_u64 v[180:181], v[202:203], 0, s[70:71]
	s_mov_b32 m0, s23
	s_nop 0
	global_load_lds_dwordx4 v[180:181], off
	v_lshl_add_u64 v[180:181], s[2:3], 0, v[34:35]
	s_mov_b32 m0, s34
	s_nop 0
	global_load_lds_dwordx4 v[180:181], off
	v_lshl_add_u64 v[180:181], s[2:3], 0, v[36:37]
	s_mov_b32 m0, s31
	s_nop 0
	global_load_lds_dwordx4 v[180:181], off
	v_lshl_add_u64 v[180:181], v[212:213], 0, s[70:71]
	s_mov_b32 m0, s21
	s_nop 0
	global_load_lds_dwordx4 v[180:181], off
	v_lshl_add_u64 v[180:181], v[230:231], 0, s[70:71]
	s_mov_b32 m0, s22
	s_nop 0
	global_load_lds_dwordx4 v[180:181], off
	s_waitcnt vmcnt(8)
	s_waitcnt lgkmcnt(0)
	s_barrier
	s_waitcnt lgkmcnt(0)
	v_mfma_f32_16x16x32_bf16 v[118:121], v[144:147], v[176:179], v[118:121]
	v_mfma_f32_16x16x32_bf16 v[86:89], v[152:155], v[176:179], v[86:89]
	v_mfma_f32_16x16x32_bf16 v[114:117], v[144:147], v[190:193], v[114:117]
	v_mfma_f32_16x16x32_bf16 v[82:85], v[152:155], v[190:193], v[82:85]
	v_mfma_f32_16x16x32_bf16 v[110:113], v[144:147], v[198:201], v[110:113]
	v_mfma_f32_16x16x32_bf16 v[78:81], v[152:155], v[198:201], v[78:81]
	v_mfma_f32_16x16x32_bf16 v[106:109], v[144:147], v[218:221], v[106:109]
	v_mfma_f32_16x16x32_bf16 v[74:77], v[152:155], v[218:221], v[74:77]
	v_mfma_f32_16x16x32_bf16 v[118:121], v[148:151], v[186:189], v[118:121]
	v_mfma_f32_16x16x32_bf16 v[86:89], v[156:159], v[186:189], v[86:89]
	v_mfma_f32_16x16x32_bf16 v[114:117], v[148:151], v[194:197], v[114:117]
	v_mfma_f32_16x16x32_bf16 v[82:85], v[156:159], v[194:197], v[82:85]
	v_mfma_f32_16x16x32_bf16 v[110:113], v[148:151], v[208:211], v[110:113]
	v_mfma_f32_16x16x32_bf16 v[78:81], v[156:159], v[208:211], v[78:81]
	v_mfma_f32_16x16x32_bf16 v[106:109], v[148:151], v[226:229], v[106:109]
	v_mfma_f32_16x16x32_bf16 v[74:77], v[156:159], v[226:229], v[74:77]
	v_mfma_f32_16x16x32_bf16 v[54:57], v[160:163], v[176:179], v[54:57]
	v_mfma_f32_16x16x32_bf16 v[14:17], v[168:171], v[176:179], v[14:17]
	v_mfma_f32_16x16x32_bf16 v[50:53], v[160:163], v[190:193], v[50:53]
	v_mfma_f32_16x16x32_bf16 v[10:13], v[168:171], v[190:193], v[10:13]
	v_mfma_f32_16x16x32_bf16 v[46:49], v[160:163], v[198:201], v[46:49]
	v_mfma_f32_16x16x32_bf16 v[6:9], v[168:171], v[198:201], v[6:9]
	v_mfma_f32_16x16x32_bf16 v[42:45], v[160:163], v[218:221], v[42:45]
	v_mfma_f32_16x16x32_bf16 v[2:5], v[168:171], v[218:221], v[2:5]
	v_mfma_f32_16x16x32_bf16 v[54:57], v[164:167], v[186:189], v[54:57]
	v_mfma_f32_16x16x32_bf16 v[14:17], v[172:175], v[186:189], v[14:17]
	v_mfma_f32_16x16x32_bf16 v[50:53], v[164:167], v[194:197], v[50:53]
	v_mfma_f32_16x16x32_bf16 v[10:13], v[172:175], v[194:197], v[10:13]
	v_mfma_f32_16x16x32_bf16 v[46:49], v[164:167], v[208:211], v[46:49]
	v_mfma_f32_16x16x32_bf16 v[6:9], v[172:175], v[208:211], v[6:9]
	v_mfma_f32_16x16x32_bf16 v[42:45], v[164:167], v[226:229], v[42:45]
	v_mfma_f32_16x16x32_bf16 v[2:5], v[172:175], v[226:229], v[2:5]
	s_barrier
	s_andn2_b64 vcc, exec, s[0:1]
	s_mov_b64 s[2:3], -1
	s_mov_b64 s[0:1], 0
	s_movk_i32 s4, 0x100
	s_cbranch_vccz .LBB0_557
	s_cmpk_lt_u32 s14, 0x100
	s_cbranch_scc0 .LBB0_560
	s_barrier

; __device__ __forceinline__ void xcd_barrier(const XcdBarrier& b) {
;     asm volatile("s_waitcnt vmcnt(0)" ::: "memory");
;     __syncthreads();
;     if (threadIdx.x == 0) {
;         unsigned* bar = b.bar;
;         __builtin_amdgcn_s_waitcnt(0);
;         unsigned nloc = b.st[0], nx = b.st[1];
;         if (nloc == 0u) { xcd_barrier_complete(bar, b.x, nloc, nx); b.st[0] = nloc; b.st[1] = nx; }
.LBB0_561:
	ds_read_b64 v[2:3], v204
	s_setprio 0
	s_getreg_b32 s4, hwreg(HW_REG_XCC_ID, 0, 4)
	s_waitcnt vmcnt(0)
	s_waitcnt lgkmcnt(0)
	s_barrier
	v_readfirstlane_b32 s3, v3
	v_readfirstlane_b32 s2, v2
	s_and_saveexec_b64 s[0:1], s[76:77]
	s_cbranch_execz .LBB0_613
	v_readlane_b32 s5, v254, 24
	s_waitcnt vmcnt(0) expcnt(0) lgkmcnt(0)
	s_and_b32 s46, s4, 15
	v_mov_b32_e32 v2, s5
	ds_read_b32 v4, v2
	v_readlane_b32 s5, v254, 25
	s_waitcnt lgkmcnt(0)
	v_cmp_ne_u32_e32 vcc, 0, v4
	v_mov_b32_e32 v2, s5
	ds_read_b32 v2, v2
	s_cbranch_vccnz .LBB0_577
	v_readlane_b32 s4, v253, 0
	v_readlane_b32 s5, v253, 1
	s_load_dwordx2 s[8:9], s[4:5], 0x4
	s_add_u32 s4, s2, 0x1200
	s_addc_u32 s5, s3, 0
	s_add_u32 s6, s2, 0x1400
	s_addc_u32 s7, s3, 0
	s_waitcnt lgkmcnt(0)
	s_mul_i32 s47, s8, s84
	s_add_u32 s8, s2, 0x1500
	s_mul_i32 s47, s47, s9
	s_addc_u32 s9, s3, 0
	s_add_u32 s10, s2, 0x1600
	s_addc_u32 s11, s3, 0
	s_add_u32 s12, s2, 0x1700
	s_addc_u32 s13, s3, 0
	s_add_u32 s14, s2, 0x1800
	s_addc_u32 s15, s3, 0
	s_add_u32 s16, s2, 0x1900
	s_addc_u32 s17, s3, 0
	s_add_u32 s18, s2, 0x1a00
	s_addc_u32 s19, s3, 0
	s_add_u32 s20, s2, 0x1b00
	s_addc_u32 s21, s3, 0
	s_add_u32 s22, s2, 0x1c00
	s_addc_u32 s23, s3, 0
	s_add_u32 s24, s2, 0x1d00
	s_addc_u32 s25, s3, 0
	s_add_u32 s26, s2, 0x1e00
	s_addc_u32 s27, s3, 0
	s_add_u32 s28, s2, 0x1f00
	s_addc_u32 s29, s3, 0
	s_add_u32 s30, s2, 0x2000
	s_addc_u32 s31, s3, 0
	s_add_u32 s34, s2, 0x2100
	s_addc_u32 s35, s3, 0
	s_add_u32 s36, s2, 0x2200
	s_addc_u32 s37, s3, 0
	s_add_u32 s38, s2, 0x2300
	s_addc_u32 s39, s3, 0
	s_mov_b32 s48, 1
	s_branch .LBB0_565

;     __device__ __forceinline__ long arow(int pm) const { return (long)pm * BM; }
;     __device__ __forceinline__ long arow(int p) const { return (long)p * BM; }
; #define PG8_STAGE(bufoff, gbase, voff) do { _Pragma("unroll") for (int _i = 0; _i < 2; ++_i) \
;         __builtin_amdgcn_global_load_lds((const unsigned*)((const char*)(gbase) + (voff)[_i]), (PG8_LAS unsigned*)(lds + (bufoff) + ldsw + _i * 8192), 16, 0, 0); } while (0)
; #define PG8_BAR __builtin_amdgcn_s_barrier()
;     __device__ __forceinline__ long arow(int pm) const { if (pm < 132) { const int b = pm / 33, i = pm - b * 33; return (long)b * 8192 + 254 * i - 1; } return 32768 + (long)(pm - 132) * 256; }
; template <class Epi, class Sched, bool ALIGN_EPI = false, bool SP2 = false>
; __device__ __forceinline__ void gemm_phase(PG8_LAS unsigned char* lds, const Gemm g, const Sched& S, const Epi& E) {
;     ...
;     for (int i = 0; i < 2; ++i) { int R, C; stage_rc(tid * 16 + i * 8192, R, C); const int Rb = Epi::PERM ? ((R & ~31) + perm32(R & 31)) : R;
;         voffA[i] = (unsigned)(R * LD + C) * 2u; voffB[i] = (unsigned)(Rb * LD + C) * 2u; }
;     ...
;     const char* cA = (const char*)g.A + S.arow(cur.pm) * rowb; const char* cB = (const char*)g.Bt + (size_t)cur.pn * tstep;
;     S.a_ready(cur);
;     if constexpr (SP2) {
;         PG8_STAGE(PG8_SB(0, 0), cB, voffB); PG8_STAGE(PG8_SB(0, 1), cB + hstep, voffB); PG8_STAGE(PG8_SA(0, 0), cA, voffA); PG8_STAGE(PG8_SA(0, 1), cA + hstep, voffA);
;         if (wr == 1) PG8_BAR;
.LBB0_683:
	v_ashrrev_i32_e32 v3, 31, v10
	v_lshrrev_b32_e32 v3, 26, v3
	v_add_u32_e32 v3, v10, v3
	v_ashrrev_i32_e32 v11, 6, v3
	v_bfe_i32 v3, v10, 27, 1
	v_lshlrev_b32_e32 v2, 4, v10
	v_lshrrev_b32_e32 v3, 22, v3
	v_add_u32_e32 v3, v2, v3
	v_and_b32_e32 v3, 0xfffffc00, v3
	v_sub_u32_e32 v3, v2, v3
	v_lshrrev_b32_e32 v4, 4, v3
	v_bitop3_b32 v3, v4, v3, 32 bitop3:0x6c
	v_ashrrev_i32_e32 v5, 31, v3
	v_lshrrev_b32_e32 v5, 26, v5
	v_add_u32_e32 v5, v3, v5
	v_readlane_b32 s4, v254, 27
	v_lshlrev_b32_e32 v4, 3, v11
	v_ashrrev_i32_e32 v12, 6, v5
	v_and_b32_e32 v5, 0xc0, v5
	v_readlane_b32 s5, v254, 28
	s_mul_i32 s3, s4, 0xb00000
	v_readlane_b32 s4, v253, 44
	v_and_b32_e32 v4, -16, v4
	v_sub_u32_e32 v3, v3, v5
	v_mov_b32_e32 v8, 1
	s_add_u32 s5, s4, s3
	v_readlane_b32 s3, v253, 45
	v_add_u32_e32 v4, v12, v4
	v_ashrrev_i16_sdwa v3, v8, sext(v3) dst_sel:DWORD dst_unused:UNUSED_PAD src0_sel:DWORD src1_sel:BYTE_0
	s_addc_u32 s12, s3, 0
	v_lshlrev_b32_e32 v6, 5, v11
	v_bfe_i32 v13, v3, 0, 16
	v_lshlrev_b32_e32 v3, 1, v4
	v_lshrrev_b32_e32 v5, 2, v4
	v_and_b32_e32 v7, 3, v12
	s_mov_b32 s3, 0x1fffe0
	v_and_b32_e32 v6, 32, v6
	v_and_b32_e32 v3, 24, v3
	v_and_b32_e32 v5, 4, v5
	v_and_or_b32 v7, v4, s3, v7
	v_or3_b32 v3, v7, v5, v3
	v_add_lshl_u32 v5, v6, v13, 1
	v_add_u32_e32 v2, 0x2000, v2
	v_lshl_add_u32 v34, v3, 11, v5
	v_ashrrev_i32_e32 v3, 31, v2
	v_lshrrev_b32_e32 v3, 22, v3
	v_add_u32_e32 v3, v2, v3
	v_ashrrev_i32_e32 v14, 10, v3
	v_mul_i32_i24_e32 v3, 0x400, v14
	v_sub_u32_e32 v2, v2, v3
	v_lshrrev_b32_e32 v3, 4, v2
	v_bitop3_b32 v2, v3, v2, 32 bitop3:0x6c
	v_lshl_add_u32 v36, v4, 11, v5
	v_ashrrev_i32_e32 v4, 31, v2
	v_lshrrev_b32_e32 v4, 26, v4
	v_lshlrev_b32_e32 v3, 3, v14
	v_add_u32_e32 v4, v2, v4
	v_and_b32_e32 v3, -16, v3
	v_ashrrev_i32_e32 v15, 6, v4
	v_add_u32_e32 v3, v15, v3
	v_and_b32_e32 v6, 3, v15
	s_ashr_i32 s4, s6, 6
	v_and_b32_e32 v4, 0xc0, v4
	v_and_or_b32 v6, v3, s3, v6
	s_ashr_i32 s3, s2, 31
	v_sub_u32_e32 v2, v2, v4
	s_ashr_i32 s15, s6, 8
	s_lshl_b32 s59, s4, 10
	s_lshl_b64 s[0:1], s[0:1], 11
	s_lshl_b64 s[10:11], s[2:3], 19
	v_ashrrev_i16_sdwa v2, v8, sext(v2) dst_sel:DWORD dst_unused:UNUSED_PAD src0_sel:DWORD src1_sel:BYTE_0
	s_add_u32 s10, s5, s10
	v_lshlrev_b32_e32 v5, 5, v14
	v_bfe_i32 v16, v2, 0, 16
	v_lshlrev_b32_e32 v2, 1, v3
	v_lshrrev_b32_e32 v4, 2, v3
	s_addc_u32 s11, s12, s11
	s_add_i32 s80, s59, 0
	v_and_b32_e32 v5, 32, v5
	v_and_b32_e32 v2, 24, v2
	v_and_b32_e32 v4, 4, v4
	s_add_i32 m0, s80, 0x10000
	v_or3_b32 v2, v6, v4, v2
	v_add_lshl_u32 v4, v5, v16, 1
	v_writelane_b32 v255, s5, 9
	global_load_lds_dwordx4 v34, s[10:11]
	s_add_i32 m0, s80, 0x12000
	v_lshl_add_u32 v188, v2, 11, v4
	v_writelane_b32 v255, s12, 11
	s_add_u32 s12, s10, 0x40000
	global_load_lds_dwordx4 v188, s[10:11]
	s_addc_u32 s13, s11, 0
	s_add_i32 m0, s80, 0x14000
	v_lshl_add_u32 v186, v3, 11, v4
	global_load_lds_dwordx4 v34, s[12:13]
	s_add_i32 m0, s80, 0x16000
	v_mov_b32_e32 v189, v35
	global_load_lds_dwordx4 v188, s[12:13]
	s_add_u32 s12, s90, s0
	s_addc_u32 s13, s91, s1
	s_add_i32 s81, s80, 0x2000
	s_mov_b32 m0, s80
	s_add_u32 s0, s12, 0x40000
	global_load_lds_dwordx4 v36, s[12:13]
	s_mov_b32 m0, s81
	s_addc_u32 s1, s13, 0
	s_add_i32 s76, s80, 0x4000
	global_load_lds_dwordx4 v186, s[12:13]
	s_mov_b32 m0, s76
	s_add_i32 s77, s80, 0x6000
	global_load_lds_dwordx4 v36, s[0:1]
	s_mov_b32 m0, s77
	s_cmp_eq_u32 s15, 1
	global_load_lds_dwordx4 v186, s[0:1]
	s_cselect_b64 s[0:1], -1, 0
	v_mov_b32_e32 v37, v35
	v_mov_b32_e32 v187, v35
	v_writelane_b32 v255, s0, 23
	v_mov_b32_e32 v214, 1
	v_lshl_add_u64 v[6:7], s[10:11], 0, v[34:35]
	v_lshl_add_u64 v[4:5], s[10:11], 0, v[188:189]
	v_lshl_add_u64 v[2:3], s[12:13], 0, v[36:37]
	v_writelane_b32 v255, s1, 24
	s_cmp_lg_u32 s15, 1
	v_lshl_add_u64 v[8:9], s[12:13], 0, v[186:187]
	s_cbranch_scc1 .LBB0_685
	s_barrier
	s_setprio 1

; #define PG8_STAGE(bufoff, gbase, voff) do { _Pragma("unroll") for (int _i = 0; _i < 2; ++_i) \
;         __builtin_amdgcn_global_load_lds((const unsigned*)((const char*)(gbase) + (voff)[_i]), (PG8_LAS unsigned*)(lds + (bufoff) + ldsw + _i * 8192), 16, 0, 0); } while (0)
; #define PG8_LDA(dst, b, h) do { _Pragma("unroll") for (int m = 0; m < 4; ++m) _Pragma("unroll") for (int k = 0; k < 2; ++k) dst[m][k] = *(const PG8_LAS bf16x8*)(lds + PG8_SA(b, h) + aoff + m * 2048 + k * 1024); } while (0)
; #define PG8_LDB(dst, b, h) do { _Pragma("unroll") for (int n = 0; n < 2; ++n) _Pragma("unroll") for (int k = 0; k < 2; ++k) dst[n][k] = *(const PG8_LAS bf16x8*)(lds + PG8_SB(b, h) + boff + n * 2048 + k * 1024); } while (0)
; #define PG8_MMA(ai, bj, At, Bt) do { __builtin_amdgcn_s_setprio(1); _Pragma("unroll") for (int m = 0; m < 4; ++m) _Pragma("unroll") for (int n = 0; n < 2; ++n) _Pragma("unroll") for (int k = 0; k < 2; ++k) \
;         acc[ai][bj][m][n] = __builtin_amdgcn_mfma_f32_16x16x32_bf16(Bt[n][k], At[m][k], acc[ai][bj][m][n], 0, 0, 0); __builtin_amdgcn_s_setprio(0); } while (0)
; #define PG8_WAIT_V(n) asm volatile("s_waitcnt vmcnt(" #n ")" ::: "memory")
; #define PG8_WAIT_L(n) asm volatile("s_waitcnt lgkmcnt(" #n ")" ::: "memory")
; template <class Epi, class Sched, bool ALIGN_EPI = false, bool SP2 = false>
; __device__ __forceinline__ void gemm_phase(PG8_LAS unsigned char* lds, const Gemm g, const Sched& S, const Epi& E) {
;     ...
;             const bool last = (t == nt - 2);
;             const char* a1 = cA + (size_t)(t + 1) * kstep;
;             const char* a2 = last ? nA : cA + (size_t)(t + 2) * kstep; const char* b2 = last ? nB : cB + (size_t)(t + 2) * kstep;
;             const char* a3 = a2 + kstep; const char* b3 = b2 + kstep;
;             if (last && has_next) S.a_ready(nxt);
;             if constexpr (SP2) {
;             PG8_LDB(B0, 0, 0); PG8_LDB(B1, 0, 1); PG8_SCHED; PG8_LDA(At, 0, 0); PG8_STAGE(PG8_SA(1, 1), a1 + hstep, voffA);
;             PG8_WAIT_V(8); PG8_WAIT_L(0); PG8_BAR; PG8_MMA(0, 0, At, B0); PG8_MMA(0, 1, At, B1); PG8_BAR; PG8_SCHED;
;             PG8_LDA(At, 0, 1); PG8_STAGE(PG8_SB(0, 0), b2, voffB); PG8_STAGE(PG8_SB(0, 1), b2 + hstep, voffB); PG8_STAGE(PG8_SA(0, 0), a2, voffA);
;             PG8_WAIT_V(8); PG8_WAIT_L(0); PG8_BAR; PG8_MMA(1, 0, At, B0); PG8_MMA(1, 1, At, B1); PG8_BAR; PG8_SCHED;
.LBB0_697:
	s_add_u32 s10, s0, 0xfffc0080
	s_addc_u32 s11, s1, -1
	s_add_i32 s19, 0, 0x10000
	s_cmp_eq_u32 s17, 12
	s_cselect_b32 s13, s95, s11
	s_cselect_b32 s12, s94, s10
	v_add_u32_e32 v38, s19, v228
	s_cselect_b32 s11, s3, s16
	s_cselect_b32 s10, s14, s15
	s_add_i32 s22, 0, 0x14000
	ds_read_b128 v[106:109], v38
	ds_read_b128 v[110:113], v38 offset:1024
	ds_read_b128 v[114:117], v38 offset:2048
	ds_read_b128 v[118:121], v38 offset:3072
	v_add_u32_e32 v38, s22, v228
	ds_read_b128 v[122:125], v38
	ds_read_b128 v[126:129], v38 offset:1024
	ds_read_b128 v[130:133], v38 offset:2048
	ds_read_b128 v[134:137], v38 offset:3072
	v_lshl_add_u64 v[202:203], s[0:1], 0, v[190:191]
	s_add_i32 m0, s80, 0xc000
	ds_read_b128 v[170:173], v242
	ds_read_b128 v[174:177], v242 offset:1024
	ds_read_b128 v[178:181], v242 offset:2048
	ds_read_b128 v[194:197], v242 offset:3072
	ds_read_b128 v[198:201], v242 offset:4096
	ds_read_b128 v[208:211], v242 offset:5120
	ds_read_b128 v[218:221], v242 offset:6144
	ds_read_b128 v[244:247], v242 offset:7168
	global_load_lds_dwordx4 v[202:203], off
	v_lshl_add_u64 v[202:203], s[0:1], 0, v[192:193]
	s_add_i32 m0, s80, 0xe000
	s_nop 0
	global_load_lds_dwordx4 v[202:203], off
	s_waitcnt vmcnt(8)
	s_waitcnt lgkmcnt(0)
	s_barrier
	s_waitcnt lgkmcnt(0)
	v_mfma_f32_16x16x32_bf16 v[166:169], v[106:109], v[170:173], v[166:169]
	v_mfma_f32_16x16x32_bf16 v[70:73], v[114:117], v[170:173], v[70:73]
	v_mfma_f32_16x16x32_bf16 v[158:161], v[106:109], v[178:181], v[158:161]
	v_mfma_f32_16x16x32_bf16 v[62:65], v[114:117], v[178:181], v[62:65]
	v_mfma_f32_16x16x32_bf16 v[150:153], v[106:109], v[198:201], v[150:153]
	v_mfma_f32_16x16x32_bf16 v[54:57], v[114:117], v[198:201], v[54:57]
	v_mfma_f32_16x16x32_bf16 v[142:145], v[106:109], v[218:221], v[142:145]
	v_mfma_f32_16x16x32_bf16 v[46:49], v[114:117], v[218:221], v[46:49]
	v_mfma_f32_16x16x32_bf16 v[166:169], v[110:113], v[174:177], v[166:169]
	v_mfma_f32_16x16x32_bf16 v[70:73], v[118:121], v[174:177], v[70:73]
	v_mfma_f32_16x16x32_bf16 v[158:161], v[110:113], v[194:197], v[158:161]
	v_mfma_f32_16x16x32_bf16 v[62:65], v[118:121], v[194:197], v[62:65]
	v_mfma_f32_16x16x32_bf16 v[150:153], v[110:113], v[208:211], v[150:153]
	v_mfma_f32_16x16x32_bf16 v[54:57], v[118:121], v[208:211], v[54:57]
	v_mfma_f32_16x16x32_bf16 v[142:145], v[110:113], v[244:247], v[142:145]
	v_mfma_f32_16x16x32_bf16 v[46:49], v[118:121], v[244:247], v[46:49]
	v_mfma_f32_16x16x32_bf16 v[162:165], v[122:125], v[170:173], v[162:165]
	v_mfma_f32_16x16x32_bf16 v[66:69], v[130:133], v[170:173], v[66:69]
	v_mfma_f32_16x16x32_bf16 v[154:157], v[122:125], v[178:181], v[154:157]
	v_mfma_f32_16x16x32_bf16 v[58:61], v[130:133], v[178:181], v[58:61]
	v_mfma_f32_16x16x32_bf16 v[146:149], v[122:125], v[198:201], v[146:149]
	v_mfma_f32_16x16x32_bf16 v[50:53], v[130:133], v[198:201], v[50:53]
	v_mfma_f32_16x16x32_bf16 v[138:141], v[122:125], v[218:221], v[138:141]
	v_mfma_f32_16x16x32_bf16 v[42:45], v[130:133], v[218:221], v[42:45]
	v_mfma_f32_16x16x32_bf16 v[162:165], v[126:129], v[174:177], v[162:165]
	v_mfma_f32_16x16x32_bf16 v[66:69], v[134:137], v[174:177], v[66:69]
	v_mfma_f32_16x16x32_bf16 v[154:157], v[126:129], v[194:197], v[154:157]
	v_mfma_f32_16x16x32_bf16 v[58:61], v[134:137], v[194:197], v[58:61]
	v_mfma_f32_16x16x32_bf16 v[146:149], v[126:129], v[208:211], v[146:149]
	v_mfma_f32_16x16x32_bf16 v[50:53], v[134:137], v[208:211], v[50:53]
	v_mfma_f32_16x16x32_bf16 v[138:141], v[126:129], v[244:247], v[138:141]
	v_mfma_f32_16x16x32_bf16 v[42:45], v[134:137], v[244:247], v[42:45]
	s_barrier
	s_add_i32 s19, s19, s59
	v_lshl_add_u64 v[202:203], s[10:11], 0, v[34:35]
	s_mov_b32 m0, s19
	ds_read_b128 v[170:173], v242 offset:16384
	ds_read_b128 v[174:177], v242 offset:17408
	ds_read_b128 v[178:181], v242 offset:18432
	ds_read_b128 v[194:197], v242 offset:19456
	ds_read_b128 v[198:201], v242 offset:20480
	ds_read_b128 v[208:211], v242 offset:21504
	ds_read_b128 v[218:221], v242 offset:22528
	ds_read_b128 v[244:247], v242 offset:23552
	global_load_lds_dwordx4 v[202:203], off
	s_add_i32 m0, s19, 0x2000
	s_add_u32 s20, s10, 0x40000
	v_lshl_add_u64 v[212:213], s[10:11], 0, v[188:189]
	s_addc_u32 s21, s11, 0
	s_add_i32 s19, s22, s59
	global_load_lds_dwordx4 v[212:213], off
	v_lshl_add_u64 v[248:249], s[20:21], 0, v[34:35]
	s_mov_b32 m0, s19
	v_lshl_add_u64 v[250:251], s[12:13], 0, v[186:187]
	global_load_lds_dwordx4 v[248:249], off
	v_lshl_add_u64 v[248:249], s[20:21], 0, v[188:189]
	s_add_i32 m0, s19, 0x2000
	s_nop 0
	global_load_lds_dwordx4 v[248:249], off
	v_lshl_add_u64 v[248:249], s[12:13], 0, v[36:37]
	s_mov_b32 m0, s80
	s_nop 0
	global_load_lds_dwordx4 v[248:249], off
	s_mov_b32 m0, s81
	s_nop 0
	global_load_lds_dwordx4 v[250:251], off
	s_waitcnt vmcnt(8)
	s_waitcnt lgkmcnt(0)
	s_barrier
; #define PG8_STAGE(bufoff, gbase, voff) do { _Pragma("unroll") for (int _i = 0; _i < 2; ++_i) \
;         __builtin_amdgcn_global_load_lds((const unsigned*)((const char*)(gbase) + (voff)[_i]), (PG8_LAS unsigned*)(lds + (bufoff) + ldsw + _i * 8192), 16, 0, 0); } while (0)
; #define PG8_LDA(dst, b, h) do { _Pragma("unroll") for (int m = 0; m < 4; ++m) _Pragma("unroll") for (int k = 0; k < 2; ++k) dst[m][k] = *(const PG8_LAS bf16x8*)(lds + PG8_SA(b, h) + aoff + m * 2048 + k * 1024); } while (0)
; #define PG8_LDB(dst, b, h) do { _Pragma("unroll") for (int n = 0; n < 2; ++n) _Pragma("unroll") for (int k = 0; k < 2; ++k) dst[n][k] = *(const PG8_LAS bf16x8*)(lds + PG8_SB(b, h) + boff + n * 2048 + k * 1024); } while (0)
; #define PG8_MMA(ai, bj, At, Bt) do { __builtin_amdgcn_s_setprio(1); _Pragma("unroll") for (int m = 0; m < 4; ++m) _Pragma("unroll") for (int n = 0; n < 2; ++n) _Pragma("unroll") for (int k = 0; k < 2; ++k) \
;         acc[ai][bj][m][n] = __builtin_amdgcn_mfma_f32_16x16x32_bf16(Bt[n][k], At[m][k], acc[ai][bj][m][n], 0, 0, 0); __builtin_amdgcn_s_setprio(0); } while (0)
; #define PG8_WAIT_V(n) asm volatile("s_waitcnt vmcnt(" #n ")" ::: "memory")
; #define PG8_WAIT_L(n) asm volatile("s_waitcnt lgkmcnt(" #n ")" ::: "memory")
; #define PG8_BAR __builtin_amdgcn_s_barrier()
; #define PG8_SCHED __builtin_amdgcn_sched_barrier(0)
; template <class Epi, class Sched, bool ALIGN_EPI = false, bool SP2 = false>
; __device__ __forceinline__ void gemm_phase(PG8_LAS unsigned char* lds, const Gemm g, const Sched& S, const Epi& E) {
;     ...
;             PG8_WAIT_V(8); PG8_WAIT_L(0); PG8_BAR; PG8_MMA(1, 0, At, B0); PG8_MMA(1, 1, At, B1); PG8_BAR; PG8_SCHED;
;             PG8_LDB(B0, 1, 0); PG8_LDB(B1, 1, 1); PG8_SCHED; PG8_LDA(At, 1, 0); PG8_STAGE(PG8_SA(0, 1), a2 + hstep, voffA);
;             PG8_WAIT_V(8); PG8_WAIT_L(0); PG8_BAR; PG8_MMA(0, 0, At, B0); PG8_MMA(0, 1, At, B1); PG8_BAR; PG8_SCHED;
	s_waitcnt lgkmcnt(0)
	v_mfma_f32_16x16x32_bf16 v[102:105], v[106:109], v[170:173], v[102:105]
	v_mfma_f32_16x16x32_bf16 v[30:33], v[114:117], v[170:173], v[30:33]
	v_mfma_f32_16x16x32_bf16 v[94:97], v[106:109], v[178:181], v[94:97]
	v_mfma_f32_16x16x32_bf16 v[22:25], v[114:117], v[178:181], v[22:25]
	v_mfma_f32_16x16x32_bf16 v[86:89], v[106:109], v[198:201], v[86:89]
	v_mfma_f32_16x16x32_bf16 v[14:17], v[114:117], v[198:201], v[14:17]
	v_mfma_f32_16x16x32_bf16 v[78:81], v[106:109], v[218:221], v[78:81]
	v_mfma_f32_16x16x32_bf16 v[6:9], v[114:117], v[218:221], v[6:9]
	v_mfma_f32_16x16x32_bf16 v[102:105], v[110:113], v[174:177], v[102:105]
	v_mfma_f32_16x16x32_bf16 v[30:33], v[118:121], v[174:177], v[30:33]
	v_mfma_f32_16x16x32_bf16 v[94:97], v[110:113], v[194:197], v[94:97]
	v_mfma_f32_16x16x32_bf16 v[22:25], v[118:121], v[194:197], v[22:25]
	v_mfma_f32_16x16x32_bf16 v[86:89], v[110:113], v[208:211], v[86:89]
	v_mfma_f32_16x16x32_bf16 v[14:17], v[118:121], v[208:211], v[14:17]
	v_mfma_f32_16x16x32_bf16 v[78:81], v[110:113], v[244:247], v[78:81]
	v_mfma_f32_16x16x32_bf16 v[6:9], v[118:121], v[244:247], v[6:9]
	v_mfma_f32_16x16x32_bf16 v[98:101], v[122:125], v[170:173], v[98:101]
	v_mfma_f32_16x16x32_bf16 v[26:29], v[130:133], v[170:173], v[26:29]
	v_mfma_f32_16x16x32_bf16 v[90:93], v[122:125], v[178:181], v[90:93]
	v_mfma_f32_16x16x32_bf16 v[18:21], v[130:133], v[178:181], v[18:21]
	v_mfma_f32_16x16x32_bf16 v[82:85], v[122:125], v[198:201], v[82:85]
	v_mfma_f32_16x16x32_bf16 v[10:13], v[130:133], v[198:201], v[10:13]
	v_mfma_f32_16x16x32_bf16 v[74:77], v[122:125], v[218:221], v[74:77]
	v_mfma_f32_16x16x32_bf16 v[2:5], v[130:133], v[218:221], v[2:5]
	v_mfma_f32_16x16x32_bf16 v[98:101], v[126:129], v[174:177], v[98:101]
	v_mfma_f32_16x16x32_bf16 v[26:29], v[134:137], v[174:177], v[26:29]
	v_mfma_f32_16x16x32_bf16 v[90:93], v[126:129], v[194:197], v[90:93]
	v_mfma_f32_16x16x32_bf16 v[18:21], v[134:137], v[194:197], v[18:21]
	v_mfma_f32_16x16x32_bf16 v[82:85], v[126:129], v[208:211], v[82:85]
	v_mfma_f32_16x16x32_bf16 v[10:13], v[134:137], v[208:211], v[10:13]
	v_mfma_f32_16x16x32_bf16 v[74:77], v[126:129], v[244:247], v[74:77]
	v_mfma_f32_16x16x32_bf16 v[2:5], v[134:137], v[244:247], v[2:5]
	s_barrier
	s_add_i32 s19, 0, 0x18000
	v_add_u32_e32 v38, s19, v228
	s_add_i32 s20, 0, 0x1c000
	ds_read_b128 v[106:109], v38
	ds_read_b128 v[110:113], v38 offset:1024
	ds_read_b128 v[114:117], v38 offset:2048
	ds_read_b128 v[118:121], v38 offset:3072
	v_add_u32_e32 v38, s20, v228
	ds_read_b128 v[122:125], v38
	ds_read_b128 v[126:129], v38 offset:1024
	ds_read_b128 v[130:133], v38 offset:2048
	ds_read_b128 v[134:137], v38 offset:3072
	s_add_u32 s12, s12, 0x40000
	s_addc_u32 s13, s13, 0
	s_mov_b32 m0, s76
	v_lshl_add_u64 v[38:39], s[12:13], 0, v[36:37]
	ds_read_b128 v[170:173], v242 offset:32768
	ds_read_b128 v[174:177], v242 offset:33792
	ds_read_b128 v[178:181], v242 offset:34816
	ds_read_b128 v[194:197], v242 offset:35840
	ds_read_b128 v[198:201], v242 offset:36864
	ds_read_b128 v[208:211], v242 offset:37888
	ds_read_b128 v[218:221], v242 offset:38912
	ds_read_b128 v[244:247], v242 offset:39936
	global_load_lds_dwordx4 v[38:39], off
	v_lshl_add_u64 v[38:39], s[12:13], 0, v[186:187]
	s_mov_b32 m0, s77
	s_nop 0
	global_load_lds_dwordx4 v[38:39], off
	s_waitcnt vmcnt(8)
	s_waitcnt lgkmcnt(0)
	s_barrier
	s_waitcnt lgkmcnt(0)
	v_mfma_f32_16x16x32_bf16 v[166:169], v[106:109], v[170:173], v[166:169]
	v_mfma_f32_16x16x32_bf16 v[70:73], v[114:117], v[170:173], v[70:73]
	v_mfma_f32_16x16x32_bf16 v[158:161], v[106:109], v[178:181], v[158:161]
	v_mfma_f32_16x16x32_bf16 v[62:65], v[114:117], v[178:181], v[62:65]
	v_mfma_f32_16x16x32_bf16 v[150:153], v[106:109], v[198:201], v[150:153]
	v_mfma_f32_16x16x32_bf16 v[54:57], v[114:117], v[198:201], v[54:57]
	v_mfma_f32_16x16x32_bf16 v[142:145], v[106:109], v[218:221], v[142:145]
	v_mfma_f32_16x16x32_bf16 v[46:49], v[114:117], v[218:221], v[46:49]
	v_mfma_f32_16x16x32_bf16 v[166:169], v[110:113], v[174:177], v[166:169]
	v_mfma_f32_16x16x32_bf16 v[70:73], v[118:121], v[174:177], v[70:73]
	v_mfma_f32_16x16x32_bf16 v[158:161], v[110:113], v[194:197], v[158:161]
	v_mfma_f32_16x16x32_bf16 v[62:65], v[118:121], v[194:197], v[62:65]
	v_mfma_f32_16x16x32_bf16 v[150:153], v[110:113], v[208:211], v[150:153]
	v_mfma_f32_16x16x32_bf16 v[54:57], v[118:121], v[208:211], v[54:57]
	v_mfma_f32_16x16x32_bf16 v[142:145], v[110:113], v[244:247], v[142:145]
	v_mfma_f32_16x16x32_bf16 v[46:49], v[118:121], v[244:247], v[46:49]
	v_mfma_f32_16x16x32_bf16 v[162:165], v[122:125], v[170:173], v[162:165]
	v_mfma_f32_16x16x32_bf16 v[66:69], v[130:133], v[170:173], v[66:69]
	v_mfma_f32_16x16x32_bf16 v[154:157], v[122:125], v[178:181], v[154:157]
	v_mfma_f32_16x16x32_bf16 v[58:61], v[130:133], v[178:181], v[58:61]
	v_mfma_f32_16x16x32_bf16 v[146:149], v[122:125], v[198:201], v[146:149]
	v_mfma_f32_16x16x32_bf16 v[50:53], v[130:133], v[198:201], v[50:53]
	v_mfma_f32_16x16x32_bf16 v[138:141], v[122:125], v[218:221], v[138:141]
	v_mfma_f32_16x16x32_bf16 v[42:45], v[130:133], v[218:221], v[42:45]
	v_mfma_f32_16x16x32_bf16 v[162:165], v[126:129], v[174:177], v[162:165]
	v_mfma_f32_16x16x32_bf16 v[66:69], v[134:137], v[174:177], v[66:69]
	v_mfma_f32_16x16x32_bf16 v[154:157], v[126:129], v[194:197], v[154:157]
	v_mfma_f32_16x16x32_bf16 v[58:61], v[134:137], v[194:197], v[58:61]
	v_mfma_f32_16x16x32_bf16 v[146:149], v[126:129], v[208:211], v[146:149]
	v_mfma_f32_16x16x32_bf16 v[50:53], v[134:137], v[208:211], v[50:53]
	v_mfma_f32_16x16x32_bf16 v[138:141], v[126:129], v[244:247], v[138:141]
	v_mfma_f32_16x16x32_bf16 v[42:45], v[134:137], v[244:247], v[42:45]
	s_barrier
; #define PG8_STAGE(bufoff, gbase, voff) do { _Pragma("unroll") for (int _i = 0; _i < 2; ++_i) \
;         __builtin_amdgcn_global_load_lds((const unsigned*)((const char*)(gbase) + (voff)[_i]), (PG8_LAS unsigned*)(lds + (bufoff) + ldsw + _i * 8192), 16, 0, 0); } while (0)
; #define PG8_LDA(dst, b, h) do { _Pragma("unroll") for (int m = 0; m < 4; ++m) _Pragma("unroll") for (int k = 0; k < 2; ++k) dst[m][k] = *(const PG8_LAS bf16x8*)(lds + PG8_SA(b, h) + aoff + m * 2048 + k * 1024); } while (0)
; #define PG8_MMA(ai, bj, At, Bt) do { __builtin_amdgcn_s_setprio(1); _Pragma("unroll") for (int m = 0; m < 4; ++m) _Pragma("unroll") for (int n = 0; n < 2; ++n) _Pragma("unroll") for (int k = 0; k < 2; ++k) \
;         acc[ai][bj][m][n] = __builtin_amdgcn_mfma_f32_16x16x32_bf16(Bt[n][k], At[m][k], acc[ai][bj][m][n], 0, 0, 0); __builtin_amdgcn_s_setprio(0); } while (0)
; #define PG8_WAIT_V(n) asm volatile("s_waitcnt vmcnt(" #n ")" ::: "memory")
; #define PG8_WAIT_L(n) asm volatile("s_waitcnt lgkmcnt(" #n ")" ::: "memory")
; #define PG8_BAR __builtin_amdgcn_s_barrier()
; #define PG8_SCHED __builtin_amdgcn_sched_barrier(0)
;     __device__ __forceinline__ void operator()(const f32x4 (&acc)[2][2][4][2], const Unit& u, int wr, int wc, int fr, int fq) const {
;     ...
;         if (u.pm < 132) { const int b = u.pm / 33, i = u.pm - b * 33; seqrow = b * 8192; tstart = 254 * i - 1; T = 8192; vlo = 1; vhi = 255; }
; template <class Epi, class Sched, bool ALIGN_EPI = false, bool SP2 = false>
; __device__ __forceinline__ void gemm_phase(PG8_LAS unsigned char* lds, const Gemm g, const Sched& S, const Epi& E) {
;     ...
;             PG8_LDA(At, 1, 1); PG8_STAGE(PG8_SB(1, 0), b3, voffB); PG8_STAGE(PG8_SB(1, 1), b3 + hstep, voffB); PG8_STAGE(PG8_SA(1, 0), a3, voffA);
;             PG8_WAIT_V(8); PG8_WAIT_L(0); PG8_BAR; PG8_MMA(1, 0, At, B0); PG8_MMA(1, 1, At, B1); PG8_BAR; PG8_SCHED;
	s_add_i32 s12, s19, s59
	v_lshl_add_u64 v[38:39], v[202:203], 0, s[70:71]
	s_mov_b32 m0, s12
	ds_read_b128 v[170:173], v242 offset:49152
	ds_read_b128 v[174:177], v242 offset:50176
	ds_read_b128 v[178:181], v242 offset:51200
	ds_read_b128 v[194:197], v242 offset:52224
	ds_read_b128 v[198:201], v242 offset:53248
	ds_read_b128 v[208:211], v242 offset:54272
	ds_read_b128 v[218:221], v242 offset:55296
	ds_read_b128 v[244:247], v242 offset:56320
	global_load_lds_dwordx4 v[38:39], off
	s_add_i32 m0, s12, 0x2000
	s_add_u32 s10, s10, 0x40080
	v_lshl_add_u64 v[38:39], v[212:213], 0, s[70:71]
	s_addc_u32 s11, s11, 0
	s_add_i32 s12, s20, s59
	global_load_lds_dwordx4 v[38:39], off
	v_lshl_add_u64 v[38:39], s[10:11], 0, v[34:35]
	s_mov_b32 m0, s12
	s_nop 0
	global_load_lds_dwordx4 v[38:39], off
	v_lshl_add_u64 v[38:39], s[10:11], 0, v[188:189]
	s_add_i32 m0, s12, 0x2000
	s_nop 0
	global_load_lds_dwordx4 v[38:39], off
	v_lshl_add_u64 v[38:39], v[248:249], 0, s[70:71]
	s_mov_b32 m0, s82
	s_nop 0
	global_load_lds_dwordx4 v[38:39], off
	v_lshl_add_u64 v[38:39], v[250:251], 0, s[70:71]
	s_mov_b32 m0, s83
	s_nop 0
	global_load_lds_dwordx4 v[38:39], off
	s_waitcnt vmcnt(8)
	s_waitcnt lgkmcnt(0)
	s_barrier
	s_waitcnt lgkmcnt(0)
	v_mfma_f32_16x16x32_bf16 v[102:105], v[106:109], v[170:173], v[102:105]
	v_mfma_f32_16x16x32_bf16 v[30:33], v[114:117], v[170:173], v[30:33]
	v_mfma_f32_16x16x32_bf16 v[94:97], v[106:109], v[178:181], v[94:97]
	v_mfma_f32_16x16x32_bf16 v[22:25], v[114:117], v[178:181], v[22:25]
	v_mfma_f32_16x16x32_bf16 v[86:89], v[106:109], v[198:201], v[86:89]
	v_mfma_f32_16x16x32_bf16 v[14:17], v[114:117], v[198:201], v[14:17]
	v_mfma_f32_16x16x32_bf16 v[78:81], v[106:109], v[218:221], v[78:81]
	v_mfma_f32_16x16x32_bf16 v[6:9], v[114:117], v[218:221], v[6:9]
	v_mfma_f32_16x16x32_bf16 v[102:105], v[110:113], v[174:177], v[102:105]
	v_mfma_f32_16x16x32_bf16 v[30:33], v[118:121], v[174:177], v[30:33]
	v_mfma_f32_16x16x32_bf16 v[94:97], v[110:113], v[194:197], v[94:97]
	v_mfma_f32_16x16x32_bf16 v[22:25], v[118:121], v[194:197], v[22:25]
	v_mfma_f32_16x16x32_bf16 v[86:89], v[110:113], v[208:211], v[86:89]
	v_mfma_f32_16x16x32_bf16 v[14:17], v[118:121], v[208:211], v[14:17]
	v_mfma_f32_16x16x32_bf16 v[78:81], v[110:113], v[244:247], v[78:81]
	v_mfma_f32_16x16x32_bf16 v[6:9], v[118:121], v[244:247], v[6:9]
	v_mfma_f32_16x16x32_bf16 v[98:101], v[122:125], v[170:173], v[98:101]
	v_mfma_f32_16x16x32_bf16 v[26:29], v[130:133], v[170:173], v[26:29]
	v_mfma_f32_16x16x32_bf16 v[90:93], v[122:125], v[178:181], v[90:93]
	v_mfma_f32_16x16x32_bf16 v[18:21], v[130:133], v[178:181], v[18:21]
	v_mfma_f32_16x16x32_bf16 v[82:85], v[122:125], v[198:201], v[82:85]
	v_mfma_f32_16x16x32_bf16 v[10:13], v[130:133], v[198:201], v[10:13]
	v_mfma_f32_16x16x32_bf16 v[74:77], v[122:125], v[218:221], v[74:77]
	v_mfma_f32_16x16x32_bf16 v[2:5], v[130:133], v[218:221], v[2:5]
	v_mfma_f32_16x16x32_bf16 v[98:101], v[126:129], v[174:177], v[98:101]
	v_mfma_f32_16x16x32_bf16 v[26:29], v[134:137], v[174:177], v[26:29]
	v_mfma_f32_16x16x32_bf16 v[90:93], v[126:129], v[194:197], v[90:93]
	v_mfma_f32_16x16x32_bf16 v[18:21], v[134:137], v[194:197], v[18:21]
	v_mfma_f32_16x16x32_bf16 v[82:85], v[126:129], v[208:211], v[82:85]
	v_mfma_f32_16x16x32_bf16 v[10:13], v[134:137], v[208:211], v[10:13]
	v_mfma_f32_16x16x32_bf16 v[74:77], v[126:129], v[244:247], v[74:77]
	v_mfma_f32_16x16x32_bf16 v[2:5], v[134:137], v[244:247], v[2:5]
	s_barrier
	s_add_i32 s17, s17, 2
	s_add_u32 s0, s0, 0x100
	s_addc_u32 s1, s1, 0
	s_add_u32 s15, s15, 0x100
	s_addc_u32 s16, s16, 0
	s_cmp_gt_u32 s17, 13
	s_cbranch_scc0 .LBB0_697
	v_readlane_b32 s0, v255, 13
	v_readlane_b32 s1, v255, 14
	s_and_b64 vcc, exec, s[0:1]
	s_cbranch_vccz .LBB0_702
	s_barrier
	s_cmpk_gt_i32 s18, 0x83
	s_mov_b64 s[0:1], -1
	s_cbranch_scc1 .LBB0_703

; __device__ __forceinline__ void xcd_barrier(const XcdBarrier& b) {
;     asm volatile("s_waitcnt vmcnt(0)" ::: "memory");
;     __syncthreads();
;     if (threadIdx.x == 0) {
;         unsigned* bar = b.bar;
;         __builtin_amdgcn_s_waitcnt(0);
;         unsigned nloc = b.st[0], nx = b.st[1];
;         if (nloc == 0u) { xcd_barrier_complete(bar, b.x, nloc, nx); b.st[0] = nloc; b.st[1] = nx; }
.LBB0_920:
	ds_read_b64 v[2:3], v204
	s_setprio 0
	s_getreg_b32 s4, hwreg(HW_REG_XCC_ID, 0, 4)
	s_waitcnt vmcnt(0)
	s_waitcnt lgkmcnt(0)
	s_barrier
	v_readfirstlane_b32 s3, v3
	v_readfirstlane_b32 s2, v2
	s_and_saveexec_b64 s[0:1], s[76:77]
	s_xor_b64 s[0:1], exec, s[0:1]
	s_cbranch_execz .LBB0_973
	v_readlane_b32 s5, v254, 24
	s_waitcnt vmcnt(0) expcnt(0) lgkmcnt(0)
	s_and_b32 s46, s4, 15
	v_mov_b32_e32 v2, s5
	ds_read_b32 v4, v2
	v_readlane_b32 s5, v254, 25
	s_waitcnt lgkmcnt(0)
	v_cmp_ne_u32_e32 vcc, 0, v4
	v_mov_b32_e32 v2, s5
	ds_read_b32 v2, v2
	s_cbranch_vccnz .LBB0_936
	v_readlane_b32 s4, v253, 0
	v_readlane_b32 s5, v253, 1
	s_load_dwordx2 s[8:9], s[4:5], 0x4
	s_add_u32 s4, s2, 0x1200
	s_addc_u32 s5, s3, 0
	s_add_u32 s6, s2, 0x1400
	s_addc_u32 s7, s3, 0
	s_waitcnt lgkmcnt(0)
	s_mul_i32 s47, s8, s84
	s_add_u32 s8, s2, 0x1500
	s_mul_i32 s47, s47, s9
	s_addc_u32 s9, s3, 0
	s_add_u32 s10, s2, 0x1600
	s_addc_u32 s11, s3, 0
	s_add_u32 s12, s2, 0x1700
	s_addc_u32 s13, s3, 0
	s_add_u32 s14, s2, 0x1800
	s_addc_u32 s15, s3, 0
	s_add_u32 s16, s2, 0x1900
	s_addc_u32 s17, s3, 0
	s_add_u32 s18, s2, 0x1a00
	s_addc_u32 s19, s3, 0
	s_add_u32 s20, s2, 0x1b00
	s_addc_u32 s21, s3, 0
	s_add_u32 s22, s2, 0x1c00
	s_addc_u32 s23, s3, 0
	s_add_u32 s24, s2, 0x1d00
	s_addc_u32 s25, s3, 0
	s_add_u32 s26, s2, 0x1e00
	s_addc_u32 s27, s3, 0
	s_add_u32 s28, s2, 0x1f00
	s_addc_u32 s29, s3, 0
	s_add_u32 s30, s2, 0x2000
	s_addc_u32 s31, s3, 0
	s_add_u32 s34, s2, 0x2100
	s_addc_u32 s35, s3, 0
	s_add_u32 s36, s2, 0x2200
	s_addc_u32 s37, s3, 0
	s_add_u32 s38, s2, 0x2300
	s_addc_u32 s39, s3, 0
	s_mov_b32 s48, 1
	s_branch .LBB0_924

;     __device__ __forceinline__ long arow(int pm) const { return (long)pm * BM; }
;     __device__ __forceinline__ long arow(int pm) const { if (pm < 132) { const int b = pm / 33, i = pm - b * 33; return (long)b * 8192 + 254 * i - 1; } return 32768 + (long)(pm - 132) * 256; }
;     __device__ __forceinline__ long arow(int p) const { return (long)p * BM; }
; #define PG8_STAGE(bufoff, gbase, voff) do { _Pragma("unroll") for (int _i = 0; _i < 2; ++_i) \
;         __builtin_amdgcn_global_load_lds((const unsigned*)((const char*)(gbase) + (voff)[_i]), (PG8_LAS unsigned*)(lds + (bufoff) + ldsw + _i * 8192), 16, 0, 0); } while (0)
; #define PG8_BAR __builtin_amdgcn_s_barrier()
;     __device__ __forceinline__ float* out() const { return (float*)(__attribute__((address_space(1))) float*)ld(22); }
; template <class Epi, class Sched, bool ALIGN_EPI = false, bool SP2 = false>
; __device__ __forceinline__ void gemm_phase(PG8_LAS unsigned char* lds, const Gemm g, const Sched& S, const Epi& E) {
;     ...
;     for (int i = 0; i < 2; ++i) { int R, C; stage_rc(tid * 16 + i * 8192, R, C); const int Rb = Epi::PERM ? ((R & ~31) + perm32(R & 31)) : R;
;         voffA[i] = (unsigned)(R * LD + C) * 2u; voffB[i] = (unsigned)(Rb * LD + C) * 2u; }
;     ...
;     const char* cA = (const char*)g.A + S.arow(cur.pm) * rowb; const char* cB = (const char*)g.Bt + (size_t)cur.pn * tstep;
;     S.a_ready(cur);
;     if constexpr (SP2) {
;         PG8_STAGE(PG8_SB(0, 0), cB, voffB); PG8_STAGE(PG8_SB(0, 1), cB + hstep, voffB); PG8_STAGE(PG8_SA(0, 0), cA, voffA); PG8_STAGE(PG8_SA(0, 1), cA + hstep, voffA);
;         if (wr == 1) PG8_BAR;
; __global__ void __launch_bounds__(512, 2) fwd_kernel(KP kparg) {
;     ...
;           pg8::EpiRes E{kp.out(), CTXB, kp.out(), CTXB, mod + 5120};
.LBB0_973:
	s_or_b64 exec, exec, s[0:1]
	v_mov_b32_e32 v4, 0x264b0
	s_waitcnt lgkmcnt(0)
	s_barrier
	ds_read_b64 v[2:3], v4
	ds_read_b64 v[4:5], v4
	v_readlane_b32 s0, v255, 7
	v_mov_b32_e32 v10, v225
	v_readlane_b32 s1, v255, 8
	v_mov_b32_e32 v217, 0x264b0
	s_waitcnt lgkmcnt(1)
	v_readfirstlane_b32 s20, v3
	v_readfirstlane_b32 s21, v2
	s_waitcnt lgkmcnt(0)
	v_readfirstlane_b32 s22, v5
	v_readfirstlane_b32 s23, v4
	s_and_b64 vcc, exec, s[0:1]
	v_readfirstlane_b32 s0, v10
	s_cbranch_vccnz .LBB0_1001
	v_lshlrev_b32_e32 v2, 4, v10
	v_add_u32_e32 v3, 0x2000, v2
	v_ashrrev_i32_e32 v4, 31, v3
	v_lshrrev_b32_e32 v4, 22, v4
	v_add_u32_e32 v4, v3, v4
	v_ashrrev_i32_e32 v6, 10, v4
	v_mul_i32_i24_e32 v4, 0x400, v6
	v_sub_u32_e32 v3, v3, v4
	v_lshrrev_b32_e32 v4, 4, v3
	v_bitop3_b32 v3, v4, v3, 32 bitop3:0x6c
	v_ashrrev_i32_e32 v4, 31, v3
	v_lshrrev_b32_e32 v4, 26, v4
	v_add_u32_e32 v4, v3, v4
	v_ashrrev_i32_e32 v7, 6, v4
	v_and_b32_e32 v4, 0xc0, v4
	v_sub_u32_e32 v3, v3, v4
	v_mov_b32_e32 v14, 1
	v_ashrrev_i16_sdwa v3, v14, sext(v3) dst_sel:DWORD dst_unused:UNUSED_PAD src0_sel:DWORD src1_sel:BYTE_0
	v_bfe_i32 v9, v3, 0, 16
	v_bfe_i32 v3, v10, 27, 1
	v_lshrrev_b32_e32 v3, 22, v3
	v_add_u32_e32 v3, v2, v3
	v_and_b32_e32 v3, 0xfffffc00, v3
	v_sub_u32_e32 v2, v2, v3
	v_lshrrev_b32_e32 v3, 4, v2
	v_ashrrev_i32_e32 v4, 31, v10
	v_bitop3_b32 v2, v3, v2, 32 bitop3:0x6c
	v_lshrrev_b32_e32 v4, 26, v4
	v_readlane_b32 s2, v254, 27
	v_lshlrev_b32_e32 v5, 3, v6
	v_ashrrev_i32_e32 v3, 31, v2
	v_add_u32_e32 v4, v10, v4
	s_mul_i32 s1, s2, 0x580000
	v_readlane_b32 s2, v253, 50
	v_and_b32_e32 v5, 0xfffff0, v5
	v_lshrrev_b32_e32 v3, 26, v3
	v_ashrrev_i32_e32 v12, 6, v4
	s_add_u32 s24, s2, s1
	v_add_u32_e32 v5, v7, v5
	s_movk_i32 s2, 0xb00
	v_lshlrev_b32_e32 v8, 5, v6
	v_add_u32_e32 v3, v2, v3
	v_lshlrev_b32_e32 v4, 3, v12
	v_readlane_b32 s3, v254, 28
	v_readlane_b32 s1, v253, 52
	v_mul_lo_u32 v5, v5, s2
	v_and_b32_e32 v8, 32, v8
	v_ashrrev_i32_e32 v11, 6, v3
	v_and_b32_e32 v4, 0xfffff0, v4
	s_addc_u32 s25, s1, 0
	s_ashr_i32 s4, s0, 6
	v_or_b32_e32 v5, v5, v8
	v_add_u32_e32 v4, v11, v4
	v_and_b32_e32 v3, 0xc0, v3
	v_readlane_b32 s3, v253, 57
	s_ashr_i32 s1, s0, 8
	s_lshl_b32 s26, s4, 10
	v_add_lshl_u32 v36, v5, v9, 1
	v_mul_lo_u32 v4, v4, s2
	v_lshlrev_b32_e32 v5, 5, v12
	v_sub_u32_e32 v2, v2, v3
	s_mul_i32 s2, s3, 0x160000
	v_and_b32_e32 v13, 32, v5
	v_ashrrev_i16_sdwa v2, v14, sext(v2) dst_sel:DWORD dst_unused:UNUSED_PAD src0_sel:DWORD src1_sel:BYTE_0
	s_add_u32 s14, s24, s2
	s_mul_hi_i32 s2, s3, 0x160000
	v_or_b32_e32 v4, v4, v13
	v_bfe_i32 v14, v2, 0, 16
	s_addc_u32 s15, s25, s2
	s_add_i32 s27, s26, 0
	v_add_lshl_u32 v34, v4, v14, 1
	s_add_i32 m0, s27, 0x10000
	v_mov_b32_e32 v37, v35
	global_load_lds_dwordx4 v34, s[14:15]
	s_add_i32 m0, s27, 0x12000
	s_add_u32 s2, s14, 0xb0000
	global_load_lds_dwordx4 v36, s[14:15]
	s_addc_u32 s3, s15, 0
	s_add_i32 m0, s27, 0x14000
	s_add_i32 s28, s27, 0x2000
	global_load_lds_dwordx4 v34, s[2:3]
	s_add_i32 m0, s27, 0x16000
	s_add_i32 s29, s27, 0x4000
	global_load_lds_dwordx4 v36, s[2:3]
	v_readlane_b32 s2, v254, 6
	s_mov_b32 m0, s27
	v_readlane_b32 s3, v254, 7
	s_add_i32 s30, s27, 0x6000
	s_cmp_eq_u32 s1, 1
	v_mov_b32_e32 v214, 1
	v_lshl_add_u64 v[2:3], s[14:15], 0, v[34:35]
	v_lshl_add_u64 v[4:5], s[14:15], 0, v[36:37]
	global_load_lds_dwordx4 v34, s[2:3]
	s_mov_b32 m0, s28
	s_nop 0
	global_load_lds_dwordx4 v36, s[2:3]
	v_readlane_b32 s2, v254, 8
	s_mov_b32 m0, s29
	v_readlane_b32 s3, v254, 9
	s_nop 4
	global_load_lds_dwordx4 v34, s[2:3]
	s_mov_b32 m0, s30
	s_nop 0
	global_load_lds_dwordx4 v36, s[2:3]
	s_cselect_b64 s[2:3], -1, 0
	s_cmp_lg_u32 s1, 1
	s_cbranch_scc1 .LBB0_976
	s_barrier
	s_setprio 1

; #define PG8_STAGE(bufoff, gbase, voff) do { _Pragma("unroll") for (int _i = 0; _i < 2; ++_i) \
;         __builtin_amdgcn_global_load_lds((const unsigned*)((const char*)(gbase) + (voff)[_i]), (PG8_LAS unsigned*)(lds + (bufoff) + ldsw + _i * 8192), 16, 0, 0); } while (0)
; #define PG8_LDA(dst, b, h) do { _Pragma("unroll") for (int m = 0; m < 4; ++m) _Pragma("unroll") for (int k = 0; k < 2; ++k) dst[m][k] = *(const PG8_LAS bf16x8*)(lds + PG8_SA(b, h) + aoff + m * 2048 + k * 1024); } while (0)
; #define PG8_LDB(dst, b, h) do { _Pragma("unroll") for (int n = 0; n < 2; ++n) _Pragma("unroll") for (int k = 0; k < 2; ++k) dst[n][k] = *(const PG8_LAS bf16x8*)(lds + PG8_SB(b, h) + boff + n * 2048 + k * 1024); } while (0)
; #define PG8_MMA(ai, bj, At, Bt) do { __builtin_amdgcn_s_setprio(1); _Pragma("unroll") for (int m = 0; m < 4; ++m) _Pragma("unroll") for (int n = 0; n < 2; ++n) _Pragma("unroll") for (int k = 0; k < 2; ++k) \
;         acc[ai][bj][m][n] = __builtin_amdgcn_mfma_f32_16x16x32_bf16(Bt[n][k], At[m][k], acc[ai][bj][m][n], 0, 0, 0); __builtin_amdgcn_s_setprio(0); } while (0)
; #define PG8_WAIT_V(n) asm volatile("s_waitcnt vmcnt(" #n ")" ::: "memory")
; #define PG8_WAIT_L(n) asm volatile("s_waitcnt lgkmcnt(" #n ")" ::: "memory")
; template <class Epi, class Sched, bool ALIGN_EPI = false, bool SP2 = false>
; __device__ __forceinline__ void gemm_phase(PG8_LAS unsigned char* lds, const Gemm g, const Sched& S, const Epi& E) {
;     ...
;             const bool last = (t == nt - 2);
;             const char* a1 = cA + (size_t)(t + 1) * kstep;
;             const char* a2 = last ? nA : cA + (size_t)(t + 2) * kstep; const char* b2 = last ? nB : cB + (size_t)(t + 2) * kstep;
;             const char* a3 = a2 + kstep; const char* b3 = b2 + kstep;
;             if (last && has_next) S.a_ready(nxt);
;             if constexpr (SP2) {
;             PG8_LDB(B0, 0, 0); PG8_LDB(B1, 0, 1); PG8_SCHED; PG8_LDA(At, 0, 0); PG8_STAGE(PG8_SA(1, 1), a1 + hstep, voffA);
;             PG8_WAIT_V(8); PG8_WAIT_L(0); PG8_BAR; PG8_MMA(0, 0, At, B0); PG8_MMA(0, 1, At, B1); PG8_BAR; PG8_SCHED;
;             PG8_LDA(At, 0, 1); PG8_STAGE(PG8_SB(0, 0), b2, voffB); PG8_STAGE(PG8_SB(0, 1), b2 + hstep, voffB); PG8_STAGE(PG8_SA(0, 0), a2, voffA);
;             PG8_WAIT_V(8); PG8_WAIT_L(0); PG8_BAR; PG8_MMA(1, 0, At, B0); PG8_MMA(1, 1, At, B1); PG8_BAR; PG8_SCHED;
.LBB0_990:
	s_add_u32 s14, s12, 0x100
	s_addc_u32 s15, s13, 0
	s_add_i32 s43, 0, 0x10000
	s_cmp_eq_u32 s42, 40
	s_cselect_b32 s19, s1, s15
	s_cselect_b32 s18, s0, s14
	v_add_u32_e32 v38, s43, v168
	s_cselect_b32 s17, s9, s41
	s_cselect_b32 s16, s8, s11
	s_add_i32 s44, 0, 0x14000
	ds_read_b128 v[138:141], v38
	ds_read_b128 v[162:165], v38 offset:1024
	ds_read_b128 v[172:175], v38 offset:2048
	ds_read_b128 v[176:179], v38 offset:3072
	v_add_u32_e32 v38, s44, v168
	ds_read_b128 v[186:189], v38
	ds_read_b128 v[190:193], v38 offset:1024
	ds_read_b128 v[194:197], v38 offset:2048
	ds_read_b128 v[198:201], v38 offset:3072
	v_lshl_add_u64 v[166:167], s[12:13], 0, v[158:159]
	s_add_i32 m0, s27, 0xc000
	ds_read_b128 v[208:211], v170
	ds_read_b128 v[218:221], v170 offset:1024
	ds_read_b128 v[226:229], v170 offset:2048
	ds_read_b128 v[230:233], v170 offset:3072
	ds_read_b128 v[234:237], v170 offset:4096
	ds_read_b128 v[238:241], v170 offset:5120
	ds_read_b128 v[242:245], v170 offset:6144
	ds_read_b128 v[246:249], v170 offset:7168
	global_load_lds_dwordx4 v[166:167], off
	v_lshl_add_u64 v[166:167], s[12:13], 0, v[160:161]
	s_add_i32 m0, s27, 0xe000
	s_nop 0
	global_load_lds_dwordx4 v[166:167], off
	s_waitcnt vmcnt(8)
	s_waitcnt lgkmcnt(0)
	s_barrier
	s_waitcnt lgkmcnt(0)
	v_mfma_f32_16x16x32_bf16 v[134:137], v[138:141], v[208:211], v[134:137]
	v_mfma_f32_16x16x32_bf16 v[106:109], v[172:175], v[208:211], v[106:109]
	v_mfma_f32_16x16x32_bf16 v[130:133], v[138:141], v[226:229], v[130:133]
	v_mfma_f32_16x16x32_bf16 v[102:105], v[172:175], v[226:229], v[102:105]
	v_mfma_f32_16x16x32_bf16 v[126:129], v[138:141], v[234:237], v[126:129]
	v_mfma_f32_16x16x32_bf16 v[98:101], v[172:175], v[234:237], v[98:101]
	v_mfma_f32_16x16x32_bf16 v[122:125], v[138:141], v[242:245], v[122:125]
	v_mfma_f32_16x16x32_bf16 v[90:93], v[172:175], v[242:245], v[90:93]
	v_mfma_f32_16x16x32_bf16 v[134:137], v[162:165], v[218:221], v[134:137]
	v_mfma_f32_16x16x32_bf16 v[106:109], v[176:179], v[218:221], v[106:109]
	v_mfma_f32_16x16x32_bf16 v[130:133], v[162:165], v[230:233], v[130:133]
	v_mfma_f32_16x16x32_bf16 v[102:105], v[176:179], v[230:233], v[102:105]
	v_mfma_f32_16x16x32_bf16 v[126:129], v[162:165], v[238:241], v[126:129]
	v_mfma_f32_16x16x32_bf16 v[98:101], v[176:179], v[238:241], v[98:101]
	v_mfma_f32_16x16x32_bf16 v[122:125], v[162:165], v[246:249], v[122:125]
	v_mfma_f32_16x16x32_bf16 v[90:93], v[176:179], v[246:249], v[90:93]
	v_mfma_f32_16x16x32_bf16 v[82:85], v[186:189], v[208:211], v[82:85]
	v_mfma_f32_16x16x32_bf16 v[54:57], v[194:197], v[208:211], v[54:57]
	v_mfma_f32_16x16x32_bf16 v[74:77], v[186:189], v[226:229], v[74:77]
	v_mfma_f32_16x16x32_bf16 v[46:49], v[194:197], v[226:229], v[46:49]
	v_mfma_f32_16x16x32_bf16 v[66:69], v[186:189], v[234:237], v[66:69]
	v_mfma_f32_16x16x32_bf16 v[30:33], v[194:197], v[234:237], v[30:33]
	v_mfma_f32_16x16x32_bf16 v[58:61], v[186:189], v[242:245], v[58:61]
	v_mfma_f32_16x16x32_bf16 v[22:25], v[194:197], v[242:245], v[22:25]
	v_mfma_f32_16x16x32_bf16 v[82:85], v[190:193], v[218:221], v[82:85]
	v_mfma_f32_16x16x32_bf16 v[54:57], v[198:201], v[218:221], v[54:57]
	v_mfma_f32_16x16x32_bf16 v[74:77], v[190:193], v[230:233], v[74:77]
	v_mfma_f32_16x16x32_bf16 v[46:49], v[198:201], v[230:233], v[46:49]
	v_mfma_f32_16x16x32_bf16 v[66:69], v[190:193], v[238:241], v[66:69]
	v_mfma_f32_16x16x32_bf16 v[30:33], v[198:201], v[238:241], v[30:33]
	v_mfma_f32_16x16x32_bf16 v[58:61], v[190:193], v[246:249], v[58:61]
	v_mfma_f32_16x16x32_bf16 v[22:25], v[198:201], v[246:249], v[22:25]
	s_barrier
	s_add_i32 s12, s43, s26
	v_lshl_add_u64 v[166:167], s[16:17], 0, v[34:35]
	s_mov_b32 m0, s12
	ds_read_b128 v[208:211], v170 offset:16384
	ds_read_b128 v[218:221], v170 offset:17408
	ds_read_b128 v[226:229], v170 offset:18432
	ds_read_b128 v[230:233], v170 offset:19456
	ds_read_b128 v[234:237], v170 offset:20480
	ds_read_b128 v[238:241], v170 offset:21504
	ds_read_b128 v[242:245], v170 offset:22528
	ds_read_b128 v[246:249], v170 offset:23552
	global_load_lds_dwordx4 v[166:167], off
	s_add_i32 m0, s12, 0x2000
	s_add_u32 s12, s16, 0xb0000
	v_lshl_add_u64 v[180:181], s[16:17], 0, v[36:37]
	s_addc_u32 s13, s17, 0
	s_add_i32 s43, s44, s26
	global_load_lds_dwordx4 v[180:181], off
	v_lshl_add_u64 v[202:203], s[12:13], 0, v[34:35]
	s_mov_b32 m0, s43
	v_lshl_add_u64 v[212:213], s[18:19], 0, v[36:37]
	global_load_lds_dwordx4 v[202:203], off
	v_lshl_add_u64 v[202:203], s[12:13], 0, v[36:37]
	s_add_i32 m0, s43, 0x2000
	s_nop 0
	global_load_lds_dwordx4 v[202:203], off
	v_lshl_add_u64 v[202:203], s[18:19], 0, v[34:35]
	s_mov_b32 m0, s27
	s_nop 0
	global_load_lds_dwordx4 v[202:203], off
	s_mov_b32 m0, s28
	s_nop 0
	global_load_lds_dwordx4 v[212:213], off
	s_waitcnt vmcnt(8)
	s_waitcnt lgkmcnt(0)
	s_barrier
; #define PG8_STAGE(bufoff, gbase, voff) do { _Pragma("unroll") for (int _i = 0; _i < 2; ++_i) \
;         __builtin_amdgcn_global_load_lds((const unsigned*)((const char*)(gbase) + (voff)[_i]), (PG8_LAS unsigned*)(lds + (bufoff) + ldsw + _i * 8192), 16, 0, 0); } while (0)
; #define PG8_LDA(dst, b, h) do { _Pragma("unroll") for (int m = 0; m < 4; ++m) _Pragma("unroll") for (int k = 0; k < 2; ++k) dst[m][k] = *(const PG8_LAS bf16x8*)(lds + PG8_SA(b, h) + aoff + m * 2048 + k * 1024); } while (0)
; #define PG8_LDB(dst, b, h) do { _Pragma("unroll") for (int n = 0; n < 2; ++n) _Pragma("unroll") for (int k = 0; k < 2; ++k) dst[n][k] = *(const PG8_LAS bf16x8*)(lds + PG8_SB(b, h) + boff + n * 2048 + k * 1024); } while (0)
; #define PG8_MMA(ai, bj, At, Bt) do { __builtin_amdgcn_s_setprio(1); _Pragma("unroll") for (int m = 0; m < 4; ++m) _Pragma("unroll") for (int n = 0; n < 2; ++n) _Pragma("unroll") for (int k = 0; k < 2; ++k) \
;         acc[ai][bj][m][n] = __builtin_amdgcn_mfma_f32_16x16x32_bf16(Bt[n][k], At[m][k], acc[ai][bj][m][n], 0, 0, 0); __builtin_amdgcn_s_setprio(0); } while (0)
; #define PG8_WAIT_V(n) asm volatile("s_waitcnt vmcnt(" #n ")" ::: "memory")
; #define PG8_WAIT_L(n) asm volatile("s_waitcnt lgkmcnt(" #n ")" ::: "memory")
; #define PG8_BAR __builtin_amdgcn_s_barrier()
; #define PG8_SCHED __builtin_amdgcn_sched_barrier(0)
; template <class Epi, class Sched, bool ALIGN_EPI = false, bool SP2 = false>
; __device__ __forceinline__ void gemm_phase(PG8_LAS unsigned char* lds, const Gemm g, const Sched& S, const Epi& E) {
;     ...
;             PG8_WAIT_V(8); PG8_WAIT_L(0); PG8_BAR; PG8_MMA(1, 0, At, B0); PG8_MMA(1, 1, At, B1); PG8_BAR; PG8_SCHED;
;             PG8_LDB(B0, 1, 0); PG8_LDB(B1, 1, 1); PG8_SCHED; PG8_LDA(At, 1, 0); PG8_STAGE(PG8_SA(0, 1), a2 + hstep, voffA);
;             PG8_WAIT_V(8); PG8_WAIT_L(0); PG8_BAR; PG8_MMA(0, 0, At, B0); PG8_MMA(0, 1, At, B1); PG8_BAR; PG8_SCHED;
	s_waitcnt lgkmcnt(0)
	v_mfma_f32_16x16x32_bf16 v[118:121], v[138:141], v[208:211], v[118:121]
	v_mfma_f32_16x16x32_bf16 v[86:89], v[172:175], v[208:211], v[86:89]
	v_mfma_f32_16x16x32_bf16 v[114:117], v[138:141], v[226:229], v[114:117]
	v_mfma_f32_16x16x32_bf16 v[78:81], v[172:175], v[226:229], v[78:81]
	v_mfma_f32_16x16x32_bf16 v[110:113], v[138:141], v[234:237], v[110:113]
	v_mfma_f32_16x16x32_bf16 v[70:73], v[172:175], v[234:237], v[70:73]
	v_mfma_f32_16x16x32_bf16 v[94:97], v[138:141], v[242:245], v[94:97]
	v_mfma_f32_16x16x32_bf16 v[62:65], v[172:175], v[242:245], v[62:65]
	v_mfma_f32_16x16x32_bf16 v[118:121], v[162:165], v[218:221], v[118:121]
	v_mfma_f32_16x16x32_bf16 v[86:89], v[176:179], v[218:221], v[86:89]
	v_mfma_f32_16x16x32_bf16 v[114:117], v[162:165], v[230:233], v[114:117]
	v_mfma_f32_16x16x32_bf16 v[78:81], v[176:179], v[230:233], v[78:81]
	v_mfma_f32_16x16x32_bf16 v[110:113], v[162:165], v[238:241], v[110:113]
	v_mfma_f32_16x16x32_bf16 v[70:73], v[176:179], v[238:241], v[70:73]
	v_mfma_f32_16x16x32_bf16 v[94:97], v[162:165], v[246:249], v[94:97]
	v_mfma_f32_16x16x32_bf16 v[62:65], v[176:179], v[246:249], v[62:65]
	v_mfma_f32_16x16x32_bf16 v[50:53], v[186:189], v[208:211], v[50:53]
	v_mfma_f32_16x16x32_bf16 v[14:17], v[194:197], v[208:211], v[14:17]
	v_mfma_f32_16x16x32_bf16 v[42:45], v[186:189], v[226:229], v[42:45]
	v_mfma_f32_16x16x32_bf16 v[10:13], v[194:197], v[226:229], v[10:13]
	v_mfma_f32_16x16x32_bf16 v[26:29], v[186:189], v[234:237], v[26:29]
	v_mfma_f32_16x16x32_bf16 v[6:9], v[194:197], v[234:237], v[6:9]
	v_mfma_f32_16x16x32_bf16 v[18:21], v[186:189], v[242:245], v[18:21]
	v_mfma_f32_16x16x32_bf16 v[2:5], v[194:197], v[242:245], v[2:5]
	v_mfma_f32_16x16x32_bf16 v[50:53], v[190:193], v[218:221], v[50:53]
	v_mfma_f32_16x16x32_bf16 v[14:17], v[198:201], v[218:221], v[14:17]
	v_mfma_f32_16x16x32_bf16 v[42:45], v[190:193], v[230:233], v[42:45]
	v_mfma_f32_16x16x32_bf16 v[10:13], v[198:201], v[230:233], v[10:13]
	v_mfma_f32_16x16x32_bf16 v[26:29], v[190:193], v[238:241], v[26:29]
	v_mfma_f32_16x16x32_bf16 v[6:9], v[198:201], v[238:241], v[6:9]
	v_mfma_f32_16x16x32_bf16 v[18:21], v[190:193], v[246:249], v[18:21]
	v_mfma_f32_16x16x32_bf16 v[2:5], v[198:201], v[246:249], v[2:5]
	s_barrier
	s_add_i32 s43, 0, 0x18000
	v_add_u32_e32 v38, s43, v168
	s_add_i32 s44, 0, 0x1c000
	ds_read_b128 v[138:141], v38
	ds_read_b128 v[162:165], v38 offset:1024
	ds_read_b128 v[172:175], v38 offset:2048
	ds_read_b128 v[176:179], v38 offset:3072
	v_add_u32_e32 v38, s44, v168
	ds_read_b128 v[186:189], v38
	ds_read_b128 v[190:193], v38 offset:1024
	ds_read_b128 v[194:197], v38 offset:2048
	ds_read_b128 v[198:201], v38 offset:3072
	s_add_u32 s12, s18, 0xb0000
	s_addc_u32 s13, s19, 0
	s_mov_b32 m0, s29
	v_lshl_add_u64 v[250:251], s[12:13], 0, v[34:35]
	ds_read_b128 v[208:211], v170 offset:32768
	ds_read_b128 v[218:221], v170 offset:33792
	ds_read_b128 v[226:229], v170 offset:34816
	ds_read_b128 v[230:233], v170 offset:35840
	ds_read_b128 v[234:237], v170 offset:36864
	ds_read_b128 v[238:241], v170 offset:37888
	ds_read_b128 v[242:245], v170 offset:38912
	ds_read_b128 v[246:249], v170 offset:39936
	global_load_lds_dwordx4 v[250:251], off
	v_lshl_add_u64 v[250:251], s[12:13], 0, v[36:37]
	s_mov_b32 m0, s30
	s_nop 0
	global_load_lds_dwordx4 v[250:251], off
	s_waitcnt vmcnt(8)
	s_waitcnt lgkmcnt(0)
	s_barrier
	s_waitcnt lgkmcnt(0)
	v_mfma_f32_16x16x32_bf16 v[134:137], v[138:141], v[208:211], v[134:137]
	v_mfma_f32_16x16x32_bf16 v[106:109], v[172:175], v[208:211], v[106:109]
	v_mfma_f32_16x16x32_bf16 v[130:133], v[138:141], v[226:229], v[130:133]
	v_mfma_f32_16x16x32_bf16 v[102:105], v[172:175], v[226:229], v[102:105]
	v_mfma_f32_16x16x32_bf16 v[126:129], v[138:141], v[234:237], v[126:129]
	v_mfma_f32_16x16x32_bf16 v[98:101], v[172:175], v[234:237], v[98:101]
	v_mfma_f32_16x16x32_bf16 v[122:125], v[138:141], v[242:245], v[122:125]
	v_mfma_f32_16x16x32_bf16 v[90:93], v[172:175], v[242:245], v[90:93]
	v_mfma_f32_16x16x32_bf16 v[134:137], v[162:165], v[218:221], v[134:137]
	v_mfma_f32_16x16x32_bf16 v[106:109], v[176:179], v[218:221], v[106:109]
	v_mfma_f32_16x16x32_bf16 v[130:133], v[162:165], v[230:233], v[130:133]
	v_mfma_f32_16x16x32_bf16 v[102:105], v[176:179], v[230:233], v[102:105]
	v_mfma_f32_16x16x32_bf16 v[126:129], v[162:165], v[238:241], v[126:129]
	v_mfma_f32_16x16x32_bf16 v[98:101], v[176:179], v[238:241], v[98:101]
	v_mfma_f32_16x16x32_bf16 v[122:125], v[162:165], v[246:249], v[122:125]
	v_mfma_f32_16x16x32_bf16 v[90:93], v[176:179], v[246:249], v[90:93]
	v_mfma_f32_16x16x32_bf16 v[82:85], v[186:189], v[208:211], v[82:85]
	v_mfma_f32_16x16x32_bf16 v[54:57], v[194:197], v[208:211], v[54:57]
	v_mfma_f32_16x16x32_bf16 v[74:77], v[186:189], v[226:229], v[74:77]
	v_mfma_f32_16x16x32_bf16 v[46:49], v[194:197], v[226:229], v[46:49]
	v_mfma_f32_16x16x32_bf16 v[66:69], v[186:189], v[234:237], v[66:69]
	v_mfma_f32_16x16x32_bf16 v[30:33], v[194:197], v[234:237], v[30:33]
	v_mfma_f32_16x16x32_bf16 v[58:61], v[186:189], v[242:245], v[58:61]
	v_mfma_f32_16x16x32_bf16 v[22:25], v[194:197], v[242:245], v[22:25]
	v_mfma_f32_16x16x32_bf16 v[82:85], v[190:193], v[218:221], v[82:85]
	v_mfma_f32_16x16x32_bf16 v[54:57], v[198:201], v[218:221], v[54:57]
	v_mfma_f32_16x16x32_bf16 v[74:77], v[190:193], v[230:233], v[74:77]
	v_mfma_f32_16x16x32_bf16 v[46:49], v[198:201], v[230:233], v[46:49]
	v_mfma_f32_16x16x32_bf16 v[66:69], v[190:193], v[238:241], v[66:69]
	v_mfma_f32_16x16x32_bf16 v[30:33], v[198:201], v[238:241], v[30:33]
	v_mfma_f32_16x16x32_bf16 v[58:61], v[190:193], v[246:249], v[58:61]
	v_mfma_f32_16x16x32_bf16 v[22:25], v[198:201], v[246:249], v[22:25]
	s_barrier
; #define PG8_STAGE(bufoff, gbase, voff) do { _Pragma("unroll") for (int _i = 0; _i < 2; ++_i) \
;         __builtin_amdgcn_global_load_lds((const unsigned*)((const char*)(gbase) + (voff)[_i]), (PG8_LAS unsigned*)(lds + (bufoff) + ldsw + _i * 8192), 16, 0, 0); } while (0)
; #define PG8_LDA(dst, b, h) do { _Pragma("unroll") for (int m = 0; m < 4; ++m) _Pragma("unroll") for (int k = 0; k < 2; ++k) dst[m][k] = *(const PG8_LAS bf16x8*)(lds + PG8_SA(b, h) + aoff + m * 2048 + k * 1024); } while (0)
; #define PG8_MMA(ai, bj, At, Bt) do { __builtin_amdgcn_s_setprio(1); _Pragma("unroll") for (int m = 0; m < 4; ++m) _Pragma("unroll") for (int n = 0; n < 2; ++n) _Pragma("unroll") for (int k = 0; k < 2; ++k) \
;         acc[ai][bj][m][n] = __builtin_amdgcn_mfma_f32_16x16x32_bf16(Bt[n][k], At[m][k], acc[ai][bj][m][n], 0, 0, 0); __builtin_amdgcn_s_setprio(0); } while (0)
; #define PG8_WAIT_V(n) asm volatile("s_waitcnt vmcnt(" #n ")" ::: "memory")
; #define PG8_WAIT_L(n) asm volatile("s_waitcnt lgkmcnt(" #n ")" ::: "memory")
; #define PG8_BAR __builtin_amdgcn_s_barrier()
; #define PG8_SCHED __builtin_amdgcn_sched_barrier(0)
;     __device__ __forceinline__ void operator()(const f32x4 (&acc)[2][2][4][2], const Unit& u, int wr, int wc, int fr, int fq) const {
;     ...
;         if (u.pm < 128) { src = src_lat + (size_t)u.pm * BM * 1024; dst = dst_lat + (size_t)u.pm * BM * 1024; b = u.pm >> 5; }
; template <class Epi, class Sched, bool ALIGN_EPI = false, bool SP2 = false>
; __device__ __forceinline__ void gemm_phase(PG8_LAS unsigned char* lds, const Gemm g, const Sched& S, const Epi& E) {
;     ...
;             PG8_LDA(At, 1, 1); PG8_STAGE(PG8_SB(1, 0), b3, voffB); PG8_STAGE(PG8_SB(1, 1), b3 + hstep, voffB); PG8_STAGE(PG8_SA(1, 0), a3, voffA);
;             PG8_WAIT_V(8); PG8_WAIT_L(0); PG8_BAR; PG8_MMA(1, 0, At, B0); PG8_MMA(1, 1, At, B1); PG8_BAR; PG8_SCHED;
	s_add_i32 s12, s43, s26
	v_lshl_add_u64 v[166:167], v[166:167], 0, s[70:71]
	s_mov_b32 m0, s12
	ds_read_b128 v[208:211], v170 offset:49152
	ds_read_b128 v[218:221], v170 offset:50176
	ds_read_b128 v[226:229], v170 offset:51200
	ds_read_b128 v[230:233], v170 offset:52224
	ds_read_b128 v[234:237], v170 offset:53248
	ds_read_b128 v[238:241], v170 offset:54272
	ds_read_b128 v[242:245], v170 offset:55296
	ds_read_b128 v[246:249], v170 offset:56320
	global_load_lds_dwordx4 v[166:167], off
	s_add_i32 m0, s12, 0x2000
	s_add_u32 s12, s16, 0xb0080
	v_lshl_add_u64 v[166:167], v[180:181], 0, s[70:71]
	s_addc_u32 s13, s17, 0
	s_add_i32 s16, s44, s26
	global_load_lds_dwordx4 v[166:167], off
	v_lshl_add_u64 v[166:167], s[12:13], 0, v[34:35]
	s_mov_b32 m0, s16
	s_nop 0
	global_load_lds_dwordx4 v[166:167], off
	v_lshl_add_u64 v[166:167], s[12:13], 0, v[36:37]
	s_add_i32 m0, s16, 0x2000
	s_nop 0
	global_load_lds_dwordx4 v[166:167], off
	v_lshl_add_u64 v[166:167], v[202:203], 0, s[70:71]
	s_mov_b32 m0, s35
	s_nop 0
	global_load_lds_dwordx4 v[166:167], off
	v_lshl_add_u64 v[166:167], v[212:213], 0, s[70:71]
	s_mov_b32 m0, s36
	s_nop 0
	global_load_lds_dwordx4 v[166:167], off
	s_waitcnt vmcnt(8)
	s_waitcnt lgkmcnt(0)
	s_barrier
	s_waitcnt lgkmcnt(0)
	v_mfma_f32_16x16x32_bf16 v[118:121], v[138:141], v[208:211], v[118:121]
	v_mfma_f32_16x16x32_bf16 v[86:89], v[172:175], v[208:211], v[86:89]
	v_mfma_f32_16x16x32_bf16 v[114:117], v[138:141], v[226:229], v[114:117]
	v_mfma_f32_16x16x32_bf16 v[78:81], v[172:175], v[226:229], v[78:81]
	v_mfma_f32_16x16x32_bf16 v[110:113], v[138:141], v[234:237], v[110:113]
	v_mfma_f32_16x16x32_bf16 v[70:73], v[172:175], v[234:237], v[70:73]
	v_mfma_f32_16x16x32_bf16 v[94:97], v[138:141], v[242:245], v[94:97]
	v_mfma_f32_16x16x32_bf16 v[62:65], v[172:175], v[242:245], v[62:65]
	v_mfma_f32_16x16x32_bf16 v[118:121], v[162:165], v[218:221], v[118:121]
	v_mfma_f32_16x16x32_bf16 v[86:89], v[176:179], v[218:221], v[86:89]
	v_mfma_f32_16x16x32_bf16 v[114:117], v[162:165], v[230:233], v[114:117]
	v_mfma_f32_16x16x32_bf16 v[78:81], v[176:179], v[230:233], v[78:81]
	v_mfma_f32_16x16x32_bf16 v[110:113], v[162:165], v[238:241], v[110:113]
	v_mfma_f32_16x16x32_bf16 v[70:73], v[176:179], v[238:241], v[70:73]
	v_mfma_f32_16x16x32_bf16 v[94:97], v[162:165], v[246:249], v[94:97]
	v_mfma_f32_16x16x32_bf16 v[62:65], v[176:179], v[246:249], v[62:65]
	v_mfma_f32_16x16x32_bf16 v[50:53], v[186:189], v[208:211], v[50:53]
	v_mfma_f32_16x16x32_bf16 v[14:17], v[194:197], v[208:211], v[14:17]
	v_mfma_f32_16x16x32_bf16 v[42:45], v[186:189], v[226:229], v[42:45]
	v_mfma_f32_16x16x32_bf16 v[10:13], v[194:197], v[226:229], v[10:13]
	v_mfma_f32_16x16x32_bf16 v[26:29], v[186:189], v[234:237], v[26:29]
	v_mfma_f32_16x16x32_bf16 v[6:9], v[194:197], v[234:237], v[6:9]
	v_mfma_f32_16x16x32_bf16 v[18:21], v[186:189], v[242:245], v[18:21]
	v_mfma_f32_16x16x32_bf16 v[2:5], v[194:197], v[242:245], v[2:5]
	v_mfma_f32_16x16x32_bf16 v[50:53], v[190:193], v[218:221], v[50:53]
	v_mfma_f32_16x16x32_bf16 v[14:17], v[198:201], v[218:221], v[14:17]
	v_mfma_f32_16x16x32_bf16 v[42:45], v[190:193], v[230:233], v[42:45]
	v_mfma_f32_16x16x32_bf16 v[10:13], v[198:201], v[230:233], v[10:13]
	v_mfma_f32_16x16x32_bf16 v[26:29], v[190:193], v[238:241], v[26:29]
	v_mfma_f32_16x16x32_bf16 v[6:9], v[198:201], v[238:241], v[6:9]
	v_mfma_f32_16x16x32_bf16 v[18:21], v[190:193], v[246:249], v[18:21]
	v_mfma_f32_16x16x32_bf16 v[2:5], v[198:201], v[246:249], v[2:5]
	s_barrier
	s_add_i32 s42, s42, 2
	s_add_u32 s11, s11, 0x100
	s_addc_u32 s41, s41, 0
	s_cmp_gt_u32 s42, 41
	s_mov_b64 s[12:13], s[14:15]
	s_cbranch_scc0 .LBB0_990
	s_and_b64 vcc, exec, s[6:7]
	s_cbranch_vccz .LBB0_998
	s_barrier
	s_cmpk_gt_i32 s10, 0x7f
	s_mov_b64 s[14:15], -1
	s_cbranch_scc1 .LBB0_999

; #define PG8_STAGE(bufoff, gbase, voff) do { _Pragma("unroll") for (int _i = 0; _i < 2; ++_i) \
;         __builtin_amdgcn_global_load_lds((const unsigned*)((const char*)(gbase) + (voff)[_i]), (PG8_LAS unsigned*)(lds + (bufoff) + ldsw + _i * 8192), 16, 0, 0); } while (0)
; #define PG8_LDA(dst, b, h) do { _Pragma("unroll") for (int m = 0; m < 4; ++m) _Pragma("unroll") for (int k = 0; k < 2; ++k) dst[m][k] = *(const PG8_LAS bf16x8*)(lds + PG8_SA(b, h) + aoff + m * 2048 + k * 1024); } while (0)
; #define PG8_LDB(dst, b, h) do { _Pragma("unroll") for (int n = 0; n < 2; ++n) _Pragma("unroll") for (int k = 0; k < 2; ++k) dst[n][k] = *(const PG8_LAS bf16x8*)(lds + PG8_SB(b, h) + boff + n * 2048 + k * 1024); } while (0)
; #define PG8_MMA(ai, bj, At, Bt) do { __builtin_amdgcn_s_setprio(1); _Pragma("unroll") for (int m = 0; m < 4; ++m) _Pragma("unroll") for (int n = 0; n < 2; ++n) _Pragma("unroll") for (int k = 0; k < 2; ++k) \
;         acc[ai][bj][m][n] = __builtin_amdgcn_mfma_f32_16x16x32_bf16(Bt[n][k], At[m][k], acc[ai][bj][m][n], 0, 0, 0); __builtin_amdgcn_s_setprio(0); } while (0)
; #define PG8_WAIT_V(n) asm volatile("s_waitcnt vmcnt(" #n ")" ::: "memory")
; #define PG8_WAIT_L(n) asm volatile("s_waitcnt lgkmcnt(" #n ")" ::: "memory")
; template <class Epi, class Sched, bool ALIGN_EPI = false, bool SP2 = false>
; __device__ __forceinline__ void gemm_phase(PG8_LAS unsigned char* lds, const Gemm g, const Sched& S, const Epi& E) {
;     ...
;             const bool last = (t == nt - 2);
;             const char* a1 = cA + (size_t)(t + 1) * kstep;
;             const char* a2 = last ? nA : cA + (size_t)(t + 2) * kstep; const char* b2 = last ? nB : cB + (size_t)(t + 2) * kstep;
;             const char* a3 = a2 + kstep; const char* b3 = b2 + kstep;
;             if (last && has_next) S.a_ready(nxt);
;             if constexpr (SP2) {
;             PG8_LDB(B0, 0, 0); PG8_LDB(B1, 0, 1); PG8_SCHED; PG8_LDA(At, 0, 0); PG8_STAGE(PG8_SA(1, 1), a1 + hstep, voffA);
;             PG8_WAIT_V(8); PG8_WAIT_L(0); PG8_BAR; PG8_MMA(0, 0, At, B0); PG8_MMA(0, 1, At, B1); PG8_BAR; PG8_SCHED;
;             PG8_LDA(At, 0, 1); PG8_STAGE(PG8_SB(0, 0), b2, voffB); PG8_STAGE(PG8_SB(0, 1), b2 + hstep, voffB); PG8_STAGE(PG8_SA(0, 0), a2, voffA);
;             PG8_WAIT_V(8); PG8_WAIT_L(0); PG8_BAR; PG8_MMA(1, 0, At, B0); PG8_MMA(1, 1, At, B1); PG8_BAR; PG8_SCHED;
.LBB0_1010:
	s_add_i32 s21, s8, 2
	s_add_u32 s6, s4, 0x100
	s_addc_u32 s7, s5, 0
	s_cmp_lg_u32 s55, s8
	s_cselect_b32 s8, s6, 0
	s_cselect_b32 s9, s7, 0
	s_add_u32 s10, s2, s8
	s_addc_u32 s11, s3, s9
	s_add_i32 s22, 0, 0x10000
	s_add_u32 s8, s0, s8
	v_add_u32_e32 v38, s22, v144
	s_addc_u32 s9, s1, s9
	s_add_i32 s23, 0, 0x14000
	ds_read_b128 v[146:149], v38
	ds_read_b128 v[150:153], v38 offset:1024
	ds_read_b128 v[154:157], v38 offset:2048
	ds_read_b128 v[158:161], v38 offset:3072
	v_add_u32_e32 v38, s23, v144
	ds_read_b128 v[162:165], v38
	ds_read_b128 v[166:169], v38 offset:1024
	ds_read_b128 v[170:173], v38 offset:2048
	ds_read_b128 v[174:177], v38 offset:3072
	v_lshl_add_u64 v[38:39], v[138:139], 0, s[4:5]
	s_add_i32 m0, s14, 0xc000
	ds_read_b128 v[178:181], v145
	ds_read_b128 v[186:189], v145 offset:1024
	ds_read_b128 v[190:193], v145 offset:2048
	ds_read_b128 v[194:197], v145 offset:3072
	ds_read_b128 v[198:201], v145 offset:4096
	ds_read_b128 v[208:211], v145 offset:5120
	ds_read_b128 v[218:221], v145 offset:6144
	ds_read_b128 v[226:229], v145 offset:7168
	global_load_lds_dwordx4 v[38:39], off
	v_lshl_add_u64 v[38:39], v[140:141], 0, s[4:5]
	s_add_i32 m0, s14, 0xe000
	s_nop 0
	global_load_lds_dwordx4 v[38:39], off
	s_waitcnt vmcnt(8)
	s_waitcnt lgkmcnt(0)
	s_barrier
	s_waitcnt lgkmcnt(0)
	v_mfma_f32_16x16x32_bf16 v[134:137], v[146:149], v[178:181], v[134:137]
	v_mfma_f32_16x16x32_bf16 v[102:105], v[154:157], v[178:181], v[102:105]
	v_mfma_f32_16x16x32_bf16 v[130:133], v[146:149], v[190:193], v[130:133]
	v_mfma_f32_16x16x32_bf16 v[98:101], v[154:157], v[190:193], v[98:101]
	v_mfma_f32_16x16x32_bf16 v[126:129], v[146:149], v[198:201], v[126:129]
	v_mfma_f32_16x16x32_bf16 v[94:97], v[154:157], v[198:201], v[94:97]
	v_mfma_f32_16x16x32_bf16 v[122:125], v[146:149], v[218:221], v[122:125]
	v_mfma_f32_16x16x32_bf16 v[90:93], v[154:157], v[218:221], v[90:93]
	v_mfma_f32_16x16x32_bf16 v[134:137], v[150:153], v[186:189], v[134:137]
	v_mfma_f32_16x16x32_bf16 v[102:105], v[158:161], v[186:189], v[102:105]
	v_mfma_f32_16x16x32_bf16 v[130:133], v[150:153], v[194:197], v[130:133]
	v_mfma_f32_16x16x32_bf16 v[98:101], v[158:161], v[194:197], v[98:101]
	v_mfma_f32_16x16x32_bf16 v[126:129], v[150:153], v[208:211], v[126:129]
	v_mfma_f32_16x16x32_bf16 v[94:97], v[158:161], v[208:211], v[94:97]
	v_mfma_f32_16x16x32_bf16 v[122:125], v[150:153], v[226:229], v[122:125]
	v_mfma_f32_16x16x32_bf16 v[90:93], v[158:161], v[226:229], v[90:93]
	v_mfma_f32_16x16x32_bf16 v[70:73], v[162:165], v[178:181], v[70:73]
	v_mfma_f32_16x16x32_bf16 v[30:33], v[170:173], v[178:181], v[30:33]
	v_mfma_f32_16x16x32_bf16 v[66:69], v[162:165], v[190:193], v[66:69]
	v_mfma_f32_16x16x32_bf16 v[26:29], v[170:173], v[190:193], v[26:29]
	v_mfma_f32_16x16x32_bf16 v[62:65], v[162:165], v[198:201], v[62:65]
	v_mfma_f32_16x16x32_bf16 v[22:25], v[170:173], v[198:201], v[22:25]
	v_mfma_f32_16x16x32_bf16 v[58:61], v[162:165], v[218:221], v[58:61]
	v_mfma_f32_16x16x32_bf16 v[18:21], v[170:173], v[218:221], v[18:21]
	v_mfma_f32_16x16x32_bf16 v[70:73], v[166:169], v[186:189], v[70:73]
	v_mfma_f32_16x16x32_bf16 v[30:33], v[174:177], v[186:189], v[30:33]
	v_mfma_f32_16x16x32_bf16 v[66:69], v[166:169], v[194:197], v[66:69]
	v_mfma_f32_16x16x32_bf16 v[26:29], v[174:177], v[194:197], v[26:29]
	v_mfma_f32_16x16x32_bf16 v[62:65], v[166:169], v[208:211], v[62:65]
	v_mfma_f32_16x16x32_bf16 v[22:25], v[174:177], v[208:211], v[22:25]
	v_mfma_f32_16x16x32_bf16 v[58:61], v[166:169], v[226:229], v[58:61]
	v_mfma_f32_16x16x32_bf16 v[18:21], v[174:177], v[226:229], v[18:21]
	s_barrier
	s_add_i32 s4, s22, s13
	v_lshl_add_u64 v[38:39], s[8:9], 0, v[34:35]
	s_mov_b32 m0, s4
	ds_read_b128 v[178:181], v145 offset:16384
	ds_read_b128 v[186:189], v145 offset:17408
	ds_read_b128 v[190:193], v145 offset:18432
	ds_read_b128 v[194:197], v145 offset:19456
	ds_read_b128 v[198:201], v145 offset:20480
	ds_read_b128 v[208:211], v145 offset:21504
	ds_read_b128 v[218:221], v145 offset:22528
	ds_read_b128 v[226:229], v145 offset:23552
	global_load_lds_dwordx4 v[38:39], off
	s_add_i32 m0, s4, 0x2000
	s_add_u32 s4, s8, 0xb0000
	v_lshl_add_u64 v[40:41], s[8:9], 0, v[36:37]
	s_addc_u32 s5, s9, 0
	s_add_i32 s22, s23, s13
	global_load_lds_dwordx4 v[40:41], off
	v_lshl_add_u64 v[202:203], s[4:5], 0, v[34:35]
	s_mov_b32 m0, s22
	v_lshl_add_u64 v[212:213], s[10:11], 0, v[36:37]
	global_load_lds_dwordx4 v[202:203], off
	v_lshl_add_u64 v[202:203], s[4:5], 0, v[36:37]
	s_add_i32 m0, s22, 0x2000
	s_nop 0
	global_load_lds_dwordx4 v[202:203], off
	v_lshl_add_u64 v[202:203], s[10:11], 0, v[34:35]
	s_mov_b32 m0, s14
	s_nop 0
	global_load_lds_dwordx4 v[202:203], off
	s_mov_b32 m0, s15
	s_nop 0
	global_load_lds_dwordx4 v[212:213], off
	s_waitcnt vmcnt(8)
	s_waitcnt lgkmcnt(0)
	s_barrier
; #define PG8_STAGE(bufoff, gbase, voff) do { _Pragma("unroll") for (int _i = 0; _i < 2; ++_i) \
;         __builtin_amdgcn_global_load_lds((const unsigned*)((const char*)(gbase) + (voff)[_i]), (PG8_LAS unsigned*)(lds + (bufoff) + ldsw + _i * 8192), 16, 0, 0); } while (0)
; #define PG8_LDA(dst, b, h) do { _Pragma("unroll") for (int m = 0; m < 4; ++m) _Pragma("unroll") for (int k = 0; k < 2; ++k) dst[m][k] = *(const PG8_LAS bf16x8*)(lds + PG8_SA(b, h) + aoff + m * 2048 + k * 1024); } while (0)
; #define PG8_LDB(dst, b, h) do { _Pragma("unroll") for (int n = 0; n < 2; ++n) _Pragma("unroll") for (int k = 0; k < 2; ++k) dst[n][k] = *(const PG8_LAS bf16x8*)(lds + PG8_SB(b, h) + boff + n * 2048 + k * 1024); } while (0)
; #define PG8_MMA(ai, bj, At, Bt) do { __builtin_amdgcn_s_setprio(1); _Pragma("unroll") for (int m = 0; m < 4; ++m) _Pragma("unroll") for (int n = 0; n < 2; ++n) _Pragma("unroll") for (int k = 0; k < 2; ++k) \
;         acc[ai][bj][m][n] = __builtin_amdgcn_mfma_f32_16x16x32_bf16(Bt[n][k], At[m][k], acc[ai][bj][m][n], 0, 0, 0); __builtin_amdgcn_s_setprio(0); } while (0)
; #define PG8_WAIT_V(n) asm volatile("s_waitcnt vmcnt(" #n ")" ::: "memory")
; #define PG8_WAIT_L(n) asm volatile("s_waitcnt lgkmcnt(" #n ")" ::: "memory")
; #define PG8_BAR __builtin_amdgcn_s_barrier()
; #define PG8_SCHED __builtin_amdgcn_sched_barrier(0)
; template <class Epi, class Sched, bool ALIGN_EPI = false, bool SP2 = false>
; __device__ __forceinline__ void gemm_phase(PG8_LAS unsigned char* lds, const Gemm g, const Sched& S, const Epi& E) {
;     ...
;             PG8_WAIT_V(8); PG8_WAIT_L(0); PG8_BAR; PG8_MMA(1, 0, At, B0); PG8_MMA(1, 1, At, B1); PG8_BAR; PG8_SCHED;
;             PG8_LDB(B0, 1, 0); PG8_LDB(B1, 1, 1); PG8_SCHED; PG8_LDA(At, 1, 0); PG8_STAGE(PG8_SA(0, 1), a2 + hstep, voffA);
;             PG8_WAIT_V(8); PG8_WAIT_L(0); PG8_BAR; PG8_MMA(0, 0, At, B0); PG8_MMA(0, 1, At, B1); PG8_BAR; PG8_SCHED;
	s_waitcnt lgkmcnt(0)
	v_mfma_f32_16x16x32_bf16 v[118:121], v[146:149], v[178:181], v[118:121]
	v_mfma_f32_16x16x32_bf16 v[86:89], v[154:157], v[178:181], v[86:89]
	v_mfma_f32_16x16x32_bf16 v[114:117], v[146:149], v[190:193], v[114:117]
	v_mfma_f32_16x16x32_bf16 v[82:85], v[154:157], v[190:193], v[82:85]
	v_mfma_f32_16x16x32_bf16 v[110:113], v[146:149], v[198:201], v[110:113]
	v_mfma_f32_16x16x32_bf16 v[78:81], v[154:157], v[198:201], v[78:81]
	v_mfma_f32_16x16x32_bf16 v[106:109], v[146:149], v[218:221], v[106:109]
	v_mfma_f32_16x16x32_bf16 v[74:77], v[154:157], v[218:221], v[74:77]
	v_mfma_f32_16x16x32_bf16 v[118:121], v[150:153], v[186:189], v[118:121]
	v_mfma_f32_16x16x32_bf16 v[86:89], v[158:161], v[186:189], v[86:89]
	v_mfma_f32_16x16x32_bf16 v[114:117], v[150:153], v[194:197], v[114:117]
	v_mfma_f32_16x16x32_bf16 v[82:85], v[158:161], v[194:197], v[82:85]
	v_mfma_f32_16x16x32_bf16 v[110:113], v[150:153], v[208:211], v[110:113]
	v_mfma_f32_16x16x32_bf16 v[78:81], v[158:161], v[208:211], v[78:81]
	v_mfma_f32_16x16x32_bf16 v[106:109], v[150:153], v[226:229], v[106:109]
	v_mfma_f32_16x16x32_bf16 v[74:77], v[158:161], v[226:229], v[74:77]
	v_mfma_f32_16x16x32_bf16 v[54:57], v[162:165], v[178:181], v[54:57]
	v_mfma_f32_16x16x32_bf16 v[14:17], v[170:173], v[178:181], v[14:17]
	v_mfma_f32_16x16x32_bf16 v[50:53], v[162:165], v[190:193], v[50:53]
	v_mfma_f32_16x16x32_bf16 v[10:13], v[170:173], v[190:193], v[10:13]
	v_mfma_f32_16x16x32_bf16 v[46:49], v[162:165], v[198:201], v[46:49]
	v_mfma_f32_16x16x32_bf16 v[6:9], v[170:173], v[198:201], v[6:9]
	v_mfma_f32_16x16x32_bf16 v[42:45], v[162:165], v[218:221], v[42:45]
	v_mfma_f32_16x16x32_bf16 v[2:5], v[170:173], v[218:221], v[2:5]
	v_mfma_f32_16x16x32_bf16 v[54:57], v[166:169], v[186:189], v[54:57]
	v_mfma_f32_16x16x32_bf16 v[14:17], v[174:177], v[186:189], v[14:17]
	v_mfma_f32_16x16x32_bf16 v[50:53], v[166:169], v[194:197], v[50:53]
	v_mfma_f32_16x16x32_bf16 v[10:13], v[174:177], v[194:197], v[10:13]
	v_mfma_f32_16x16x32_bf16 v[46:49], v[166:169], v[208:211], v[46:49]
	v_mfma_f32_16x16x32_bf16 v[6:9], v[174:177], v[208:211], v[6:9]
	v_mfma_f32_16x16x32_bf16 v[42:45], v[166:169], v[226:229], v[42:45]
	v_mfma_f32_16x16x32_bf16 v[2:5], v[174:177], v[226:229], v[2:5]
	s_barrier
	s_add_i32 s22, 0, 0x18000
	s_add_i32 s23, 0, 0x1c000
	v_add_u32_e32 v158, s22, v144
	v_add_u32_e32 v174, s23, v144
	ds_read_b128 v[146:149], v158
	ds_read_b128 v[150:153], v158 offset:1024
	ds_read_b128 v[154:157], v158 offset:2048
	ds_read_b128 v[158:161], v158 offset:3072
	ds_read_b128 v[162:165], v174
	ds_read_b128 v[166:169], v174 offset:1024
	ds_read_b128 v[170:173], v174 offset:2048
	ds_read_b128 v[174:177], v174 offset:3072
	s_add_u32 s4, s10, 0xb0000
	s_addc_u32 s5, s11, 0
	s_mov_b32 m0, s16
	v_lshl_add_u64 v[230:231], s[4:5], 0, v[34:35]
	ds_read_b128 v[178:181], v145 offset:32768
	ds_read_b128 v[186:189], v145 offset:33792
	ds_read_b128 v[190:193], v145 offset:34816
	ds_read_b128 v[194:197], v145 offset:35840
	ds_read_b128 v[198:201], v145 offset:36864
	ds_read_b128 v[208:211], v145 offset:37888
	ds_read_b128 v[218:221], v145 offset:38912
	ds_read_b128 v[226:229], v145 offset:39936
	global_load_lds_dwordx4 v[230:231], off
	v_lshl_add_u64 v[230:231], s[4:5], 0, v[36:37]
	s_mov_b32 m0, s17
	s_nop 0
	global_load_lds_dwordx4 v[230:231], off
	s_waitcnt vmcnt(8)
	s_waitcnt lgkmcnt(0)
	s_barrier
	s_waitcnt lgkmcnt(0)
	v_mfma_f32_16x16x32_bf16 v[134:137], v[146:149], v[178:181], v[134:137]
	v_mfma_f32_16x16x32_bf16 v[102:105], v[154:157], v[178:181], v[102:105]
	v_mfma_f32_16x16x32_bf16 v[130:133], v[146:149], v[190:193], v[130:133]
	v_mfma_f32_16x16x32_bf16 v[98:101], v[154:157], v[190:193], v[98:101]
	v_mfma_f32_16x16x32_bf16 v[126:129], v[146:149], v[198:201], v[126:129]
	v_mfma_f32_16x16x32_bf16 v[94:97], v[154:157], v[198:201], v[94:97]
	v_mfma_f32_16x16x32_bf16 v[122:125], v[146:149], v[218:221], v[122:125]
	v_mfma_f32_16x16x32_bf16 v[90:93], v[154:157], v[218:221], v[90:93]
	v_mfma_f32_16x16x32_bf16 v[134:137], v[150:153], v[186:189], v[134:137]
	v_mfma_f32_16x16x32_bf16 v[102:105], v[158:161], v[186:189], v[102:105]
	v_mfma_f32_16x16x32_bf16 v[130:133], v[150:153], v[194:197], v[130:133]
	v_mfma_f32_16x16x32_bf16 v[98:101], v[158:161], v[194:197], v[98:101]
	v_mfma_f32_16x16x32_bf16 v[126:129], v[150:153], v[208:211], v[126:129]
	v_mfma_f32_16x16x32_bf16 v[94:97], v[158:161], v[208:211], v[94:97]
	v_mfma_f32_16x16x32_bf16 v[122:125], v[150:153], v[226:229], v[122:125]
	v_mfma_f32_16x16x32_bf16 v[90:93], v[158:161], v[226:229], v[90:93]
	v_mfma_f32_16x16x32_bf16 v[70:73], v[162:165], v[178:181], v[70:73]
	v_mfma_f32_16x16x32_bf16 v[30:33], v[170:173], v[178:181], v[30:33]
	v_mfma_f32_16x16x32_bf16 v[66:69], v[162:165], v[190:193], v[66:69]
	v_mfma_f32_16x16x32_bf16 v[26:29], v[170:173], v[190:193], v[26:29]
	v_mfma_f32_16x16x32_bf16 v[62:65], v[162:165], v[198:201], v[62:65]
	v_mfma_f32_16x16x32_bf16 v[22:25], v[170:173], v[198:201], v[22:25]
	v_mfma_f32_16x16x32_bf16 v[58:61], v[162:165], v[218:221], v[58:61]
	v_mfma_f32_16x16x32_bf16 v[18:21], v[170:173], v[218:221], v[18:21]
	v_mfma_f32_16x16x32_bf16 v[70:73], v[166:169], v[186:189], v[70:73]
	v_mfma_f32_16x16x32_bf16 v[30:33], v[174:177], v[186:189], v[30:33]
	v_mfma_f32_16x16x32_bf16 v[66:69], v[166:169], v[194:197], v[66:69]
	v_mfma_f32_16x16x32_bf16 v[26:29], v[174:177], v[194:197], v[26:29]
	v_mfma_f32_16x16x32_bf16 v[62:65], v[166:169], v[208:211], v[62:65]
	v_mfma_f32_16x16x32_bf16 v[22:25], v[174:177], v[208:211], v[22:25]
	v_mfma_f32_16x16x32_bf16 v[58:61], v[166:169], v[226:229], v[58:61]
	v_mfma_f32_16x16x32_bf16 v[18:21], v[174:177], v[226:229], v[18:21]
	s_barrier
; #define PG8_STAGE(bufoff, gbase, voff) do { _Pragma("unroll") for (int _i = 0; _i < 2; ++_i) \
;         __builtin_amdgcn_global_load_lds((const unsigned*)((const char*)(gbase) + (voff)[_i]), (PG8_LAS unsigned*)(lds + (bufoff) + ldsw + _i * 8192), 16, 0, 0); } while (0)
; #define PG8_LDA(dst, b, h) do { _Pragma("unroll") for (int m = 0; m < 4; ++m) _Pragma("unroll") for (int k = 0; k < 2; ++k) dst[m][k] = *(const PG8_LAS bf16x8*)(lds + PG8_SA(b, h) + aoff + m * 2048 + k * 1024); } while (0)
; #define PG8_MMA(ai, bj, At, Bt) do { __builtin_amdgcn_s_setprio(1); _Pragma("unroll") for (int m = 0; m < 4; ++m) _Pragma("unroll") for (int n = 0; n < 2; ++n) _Pragma("unroll") for (int k = 0; k < 2; ++k) \
;         acc[ai][bj][m][n] = __builtin_amdgcn_mfma_f32_16x16x32_bf16(Bt[n][k], At[m][k], acc[ai][bj][m][n], 0, 0, 0); __builtin_amdgcn_s_setprio(0); } while (0)
; #define PG8_WAIT_V(n) asm volatile("s_waitcnt vmcnt(" #n ")" ::: "memory")
; #define PG8_WAIT_L(n) asm volatile("s_waitcnt lgkmcnt(" #n ")" ::: "memory")
; #define PG8_BAR __builtin_amdgcn_s_barrier()
; #define PG8_SCHED __builtin_amdgcn_sched_barrier(0)
; template <class Epi, class Sched, bool ALIGN_EPI = false, bool SP2 = false>
; __device__ __forceinline__ void gemm_phase(PG8_LAS unsigned char* lds, const Gemm g, const Sched& S, const Epi& E) {
;     ...
;             PG8_LDA(At, 1, 1); PG8_STAGE(PG8_SB(1, 0), b3, voffB); PG8_STAGE(PG8_SB(1, 1), b3 + hstep, voffB); PG8_STAGE(PG8_SA(1, 0), a3, voffA);
;             PG8_WAIT_V(8); PG8_WAIT_L(0); PG8_BAR; PG8_MMA(1, 0, At, B0); PG8_MMA(1, 1, At, B1); PG8_BAR; PG8_SCHED;
	s_add_i32 s4, s22, s13
	v_lshl_add_u64 v[38:39], v[38:39], 0, s[70:71]
	s_mov_b32 m0, s4
	ds_read_b128 v[178:181], v145 offset:49152
	ds_read_b128 v[186:189], v145 offset:50176
	ds_read_b128 v[190:193], v145 offset:51200
	ds_read_b128 v[194:197], v145 offset:52224
	ds_read_b128 v[198:201], v145 offset:53248
	ds_read_b128 v[208:211], v145 offset:54272
	ds_read_b128 v[218:221], v145 offset:55296
	ds_read_b128 v[226:229], v145 offset:56320
	global_load_lds_dwordx4 v[38:39], off
	s_add_i32 m0, s4, 0x2000
	s_add_u32 s4, s8, 0xb0080
	v_lshl_add_u64 v[38:39], v[40:41], 0, s[70:71]
	s_addc_u32 s5, s9, 0
	s_add_i32 s8, s23, s13
	global_load_lds_dwordx4 v[38:39], off
	v_lshl_add_u64 v[38:39], s[4:5], 0, v[34:35]
	s_mov_b32 m0, s8
	s_nop 0
	global_load_lds_dwordx4 v[38:39], off
	v_lshl_add_u64 v[38:39], s[4:5], 0, v[36:37]
	s_add_i32 m0, s8, 0x2000
	s_nop 0
	global_load_lds_dwordx4 v[38:39], off
	v_lshl_add_u64 v[38:39], v[202:203], 0, s[70:71]
	s_mov_b32 m0, s19
	s_nop 0
	global_load_lds_dwordx4 v[38:39], off
	v_lshl_add_u64 v[38:39], v[212:213], 0, s[70:71]
	s_mov_b32 m0, s20
	s_nop 0
	global_load_lds_dwordx4 v[38:39], off
	s_waitcnt vmcnt(8)
	s_waitcnt lgkmcnt(0)
	s_barrier
	s_waitcnt lgkmcnt(0)
	v_mfma_f32_16x16x32_bf16 v[118:121], v[146:149], v[178:181], v[118:121]
	v_mfma_f32_16x16x32_bf16 v[86:89], v[154:157], v[178:181], v[86:89]
	v_mfma_f32_16x16x32_bf16 v[114:117], v[146:149], v[190:193], v[114:117]
	v_mfma_f32_16x16x32_bf16 v[82:85], v[154:157], v[190:193], v[82:85]
	v_mfma_f32_16x16x32_bf16 v[110:113], v[146:149], v[198:201], v[110:113]
	v_mfma_f32_16x16x32_bf16 v[78:81], v[154:157], v[198:201], v[78:81]
	v_mfma_f32_16x16x32_bf16 v[106:109], v[146:149], v[218:221], v[106:109]
	v_mfma_f32_16x16x32_bf16 v[74:77], v[154:157], v[218:221], v[74:77]
	v_mfma_f32_16x16x32_bf16 v[118:121], v[150:153], v[186:189], v[118:121]
	v_mfma_f32_16x16x32_bf16 v[86:89], v[158:161], v[186:189], v[86:89]
	v_mfma_f32_16x16x32_bf16 v[114:117], v[150:153], v[194:197], v[114:117]
	v_mfma_f32_16x16x32_bf16 v[82:85], v[158:161], v[194:197], v[82:85]
	v_mfma_f32_16x16x32_bf16 v[110:113], v[150:153], v[208:211], v[110:113]
	v_mfma_f32_16x16x32_bf16 v[78:81], v[158:161], v[208:211], v[78:81]
	v_mfma_f32_16x16x32_bf16 v[106:109], v[150:153], v[226:229], v[106:109]
	v_mfma_f32_16x16x32_bf16 v[74:77], v[158:161], v[226:229], v[74:77]
	v_mfma_f32_16x16x32_bf16 v[54:57], v[162:165], v[178:181], v[54:57]
	v_mfma_f32_16x16x32_bf16 v[14:17], v[170:173], v[178:181], v[14:17]
	v_mfma_f32_16x16x32_bf16 v[50:53], v[162:165], v[190:193], v[50:53]
	v_mfma_f32_16x16x32_bf16 v[10:13], v[170:173], v[190:193], v[10:13]
	v_mfma_f32_16x16x32_bf16 v[46:49], v[162:165], v[198:201], v[46:49]
	v_mfma_f32_16x16x32_bf16 v[6:9], v[170:173], v[198:201], v[6:9]
	v_mfma_f32_16x16x32_bf16 v[42:45], v[162:165], v[218:221], v[42:45]
	v_mfma_f32_16x16x32_bf16 v[2:5], v[170:173], v[218:221], v[2:5]
	v_mfma_f32_16x16x32_bf16 v[54:57], v[166:169], v[186:189], v[54:57]
	v_mfma_f32_16x16x32_bf16 v[14:17], v[174:177], v[186:189], v[14:17]
	v_mfma_f32_16x16x32_bf16 v[50:53], v[166:169], v[194:197], v[50:53]
	v_mfma_f32_16x16x32_bf16 v[10:13], v[174:177], v[194:197], v[10:13]
	v_mfma_f32_16x16x32_bf16 v[46:49], v[166:169], v[208:211], v[46:49]
	v_mfma_f32_16x16x32_bf16 v[6:9], v[174:177], v[208:211], v[6:9]
	v_mfma_f32_16x16x32_bf16 v[42:45], v[166:169], v[226:229], v[42:45]
	v_mfma_f32_16x16x32_bf16 v[2:5], v[174:177], v[226:229], v[2:5]
	s_barrier
	s_cmp_ge_u32 s21, s49
	s_mov_b64 s[4:5], s[6:7]
	s_mov_b32 s8, s21
	s_cbranch_scc0 .LBB0_1010
	s_cmpk_lt_u32 s12, 0x100
	s_cbranch_scc0 .LBB0_1013
	s_barrier

; __device__ __forceinline__ void xcd_barrier(const XcdBarrier& b) {
;     asm volatile("s_waitcnt vmcnt(0)" ::: "memory");
;     __syncthreads();
;     if (threadIdx.x == 0) {
;         unsigned* bar = b.bar;
;         __builtin_amdgcn_s_waitcnt(0);
.LBB0_1014:
	ds_read_b64 v[2:3], v204
	s_setprio 0
	s_getreg_b32 s4, hwreg(HW_REG_XCC_ID, 0, 4)
	s_waitcnt vmcnt(0)
	s_waitcnt lgkmcnt(0)
	s_barrier
	v_readfirstlane_b32 s3, v3
	v_readfirstlane_b32 s2, v2
	s_and_saveexec_b64 s[0:1], s[76:77]
	s_cbranch_execnz .LBB0_1015
	s_getpc_b64 s[98:99]
